# v75 + GEMM read-section tail: s_setprio 1, then one merged s_waitcnt vmcnt(8) lgkmcnt(0), then the barrier
# speedup vs baseline: 1.0019x; 1.0019x over previous
; #define PG8_STAGE(bufoff, gbase, voff) do { _Pragma("unroll") for (int _i = 0; _i < 2; ++_i) \
;         __builtin_amdgcn_global_load_lds((const unsigned*)((const char*)(gbase) + (voff)[_i]), (LAS unsigned*)(lds + (bufoff) + ldsw + _i * 8192), 16, 0, 0); } while (0)
; #define PG8_LDA(dst, b, h) do { _Pragma("unroll") for (int m = 0; m < 4; ++m) _Pragma("unroll") for (int k = 0; k < 2; ++k) dst[m][k] = *(const LAS bf16x8*)(lds + PG8_SA(b, h) + aoff + m * 2048 + k * 1024); } while (0)
; #define PG8_LDB(dst, b, h) do { _Pragma("unroll") for (int n = 0; n < 2; ++n) _Pragma("unroll") for (int k = 0; k < 2; ++k) dst[n][k] = *(const LAS bf16x8*)(lds + PG8_SB(b, h) + boff + n * 2048 + k * 1024); } while (0)
; #define PG8_BAR __builtin_amdgcn_s_barrier()
; template <class Epi, bool ALIGN_EPI = PG8_ALIGN, bool SP2 = PG8_SP2>
; __device__ __forceinline__ void gemm_phase(LAS uchar* lds, const Gemm g, const StaticOrder& S, const Epi& E) {
;     ...
;         for (int t = tb; t < tb + tblk; t += 2) {
;             const bool last = (t == nt - 2);
;             const char* a1 = cA + (size_t)(t + 1) * kstep;
;             const char* a2 = last ? nA : cA + (size_t)(t + 2) * kstep; const char* b2 = last ? nB : cB + (size_t)(t + 2) * kstep;
;             const char* a3 = a2 + kstep; const char* b3 = b2 + kstep;
;             if constexpr (SP2) {
;             PG8_LDB(B0, 0, 0); PG8_LDB(B1, 0, 1); PG8_SCHED; PG8_LDA(At, 0, 0); PG8_STAGE(PG8_SA(1, 1), a1 + hstepA, voffA);
;             PG8_WAIT_V(8); PG8_WAIT_L(0); PG8_BAR; PG8_MMA(0, 0, At, B0); PG8_MMA(0, 1, At, B1); PG8_BAR; PG8_SCHED;
;             PG8_LDA(At, 0, 1); PG8_STAGE(PG8_SB(0, 0), b2, voffB); PG8_STAGE(PG8_SB(0, 1), b2 + hstepB, voffB); PG8_STAGE(PG8_SA(0, 0), a2, voffA);
;             PG8_WAIT_V(8); PG8_WAIT_L(0); PG8_BAR; PG8_MMA(1, 0, At, B0); PG8_MMA(1, 1, At, B1); PG8_BAR; PG8_SCHED;
;             PG8_LDB(B0, 1, 0); PG8_LDB(B1, 1, 1); PG8_SCHED; PG8_LDA(At, 1, 0); PG8_STAGE(PG8_SA(0, 1), a2 + hstepA, voffA);
;             PG8_WAIT_V(8); PG8_WAIT_L(0); PG8_BAR; PG8_MMA(0, 0, At, B0); PG8_MMA(0, 1, At, B1); PG8_BAR; PG8_SCHED;
;             PG8_LDA(At, 1, 1); PG8_STAGE(PG8_SB(1, 0), b3, voffB); PG8_STAGE(PG8_SB(1, 1), b3 + hstepB, voffB); PG8_STAGE(PG8_SA(1, 0), a3, voffA);
;             PG8_WAIT_V(8); PG8_WAIT_L(0); PG8_BAR; PG8_MMA(1, 0, At, B0); PG8_MMA(1, 1, At, B1); PG8_BAR; PG8_SCHED;
.Lrw_done_345_1_pl:
	s_waitcnt lgkmcnt(0)
	s_setprio 1
	s_barrier
	v_mfma_f32_16x16x32_bf16 v[62:65], v[164:167], v[204:207], 0
	v_mfma_f32_16x16x32_bf16 v[58:61], v[176:179], v[204:207], 0
	v_mfma_f32_16x16x32_bf16 v[54:57], v[164:167], v[212:215], 0
	v_mfma_f32_16x16x32_bf16 v[46:49], v[176:179], v[212:215], 0
	v_mfma_f32_16x16x32_bf16 v[38:41], v[164:167], v[220:223], 0
	v_mfma_f32_16x16x32_bf16 v[30:33], v[176:179], v[220:223], 0
	v_mfma_f32_16x16x32_bf16 v[22:25], v[164:167], v[228:231], 0
	v_mfma_f32_16x16x32_bf16 v[14:17], v[176:179], v[228:231], 0
	v_mfma_f32_16x16x32_bf16 v[62:65], v[172:175], v[208:211], v[62:65]
	v_mfma_f32_16x16x32_bf16 v[58:61], v[184:187], v[208:211], v[58:61]
	v_mfma_f32_16x16x32_bf16 v[54:57], v[172:175], v[216:219], v[54:57]
	v_mfma_f32_16x16x32_bf16 v[46:49], v[184:187], v[216:219], v[46:49]
	v_mfma_f32_16x16x32_bf16 v[38:41], v[172:175], v[224:227], v[38:41]
	v_mfma_f32_16x16x32_bf16 v[30:33], v[184:187], v[224:227], v[30:33]
	v_mfma_f32_16x16x32_bf16 v[22:25], v[172:175], v[232:235], v[22:25]
	v_mfma_f32_16x16x32_bf16 v[14:17], v[184:187], v[232:235], v[14:17]
	v_mfma_f32_16x16x32_bf16 v[50:53], v[188:191], v[204:207], 0
	v_mfma_f32_16x16x32_bf16 v[42:45], v[196:199], v[204:207], 0
	v_mfma_f32_16x16x32_bf16 v[34:37], v[188:191], v[212:215], 0
	v_mfma_f32_16x16x32_bf16 v[26:29], v[196:199], v[212:215], 0
	v_mfma_f32_16x16x32_bf16 v[18:21], v[188:191], v[220:223], 0
	v_mfma_f32_16x16x32_bf16 v[10:13], v[196:199], v[220:223], 0
	v_mfma_f32_16x16x32_bf16 v[6:9], v[188:191], v[228:231], 0
	v_mfma_f32_16x16x32_bf16 v[2:5], v[196:199], v[228:231], 0
	v_mfma_f32_16x16x32_bf16 v[50:53], v[192:195], v[208:211], v[50:53]
	v_mfma_f32_16x16x32_bf16 v[42:45], v[200:203], v[208:211], v[42:45]
	v_mfma_f32_16x16x32_bf16 v[34:37], v[192:195], v[216:219], v[34:37]
	v_mfma_f32_16x16x32_bf16 v[26:29], v[200:203], v[216:219], v[26:29]
	v_mfma_f32_16x16x32_bf16 v[18:21], v[192:195], v[224:227], v[18:21]
	v_mfma_f32_16x16x32_bf16 v[10:13], v[200:203], v[224:227], v[10:13]
	v_mfma_f32_16x16x32_bf16 v[6:9], v[192:195], v[232:235], v[6:9]
	v_mfma_f32_16x16x32_bf16 v[2:5], v[200:203], v[232:235], v[2:5]
	s_barrier
	s_setprio 0
	s_add_i32 s41, 0, 0x18000
	s_add_i32 s42, 0, 0x1c000
	v_add_u32_e32 v184, s41, v139
	v_add_u32_e32 v200, s42, v139
	ds_read_b128 v[164:167], v184
	ds_read_b128 v[172:175], v184 offset:1024
	ds_read_b128 v[176:179], v184 offset:2048
	ds_read_b128 v[184:187], v184 offset:3072
	ds_read_b128 v[188:191], v200
	ds_read_b128 v[192:195], v200 offset:1024
	ds_read_b128 v[196:199], v200 offset:2048
	ds_read_b128 v[200:203], v200 offset:3072
	s_add_u32 s16, s20, 0x44000
	s_addc_u32 s17, s21, 0
	s_mov_b32 m0, s27
	v_lshl_add_u64 v[240:241], s[16:17], 0, v[156:157]
	ds_read_b128 v[204:207], v171 offset:32768
	ds_read_b128 v[208:211], v171 offset:33792
	ds_read_b128 v[212:215], v171 offset:34816
	ds_read_b128 v[216:219], v171 offset:35840
	ds_read_b128 v[220:223], v171 offset:36864
	ds_read_b128 v[224:227], v171 offset:37888
	ds_read_b128 v[228:231], v171 offset:38912
	ds_read_b128 v[232:235], v171 offset:39936
	global_load_lds_dwordx4 v[240:241], off
	s_mov_b32 m0, s28
	v_lshl_add_u64 v[240:241], s[16:17], 0, v[132:133]
	global_load_lds_dwordx4 v[240:241], off
	s_setprio 1
	s_waitcnt vmcnt(8) lgkmcnt(0)
	s_barrier
	v_mfma_f32_16x16x32_bf16 v[126:129], v[164:167], v[204:207], v[126:129]
	v_mfma_f32_16x16x32_bf16 v[122:125], v[176:179], v[204:207], v[122:125]
	v_mfma_f32_16x16x32_bf16 v[118:121], v[164:167], v[212:215], v[118:121]
	v_mfma_f32_16x16x32_bf16 v[110:113], v[176:179], v[212:215], v[110:113]
	v_mfma_f32_16x16x32_bf16 v[102:105], v[164:167], v[220:223], v[102:105]
	v_mfma_f32_16x16x32_bf16 v[94:97], v[176:179], v[220:223], v[94:97]
	v_mfma_f32_16x16x32_bf16 v[86:89], v[164:167], v[228:231], v[86:89]
	v_mfma_f32_16x16x32_bf16 v[78:81], v[176:179], v[228:231], v[78:81]
	v_mfma_f32_16x16x32_bf16 v[126:129], v[172:175], v[208:211], v[126:129]
	v_mfma_f32_16x16x32_bf16 v[122:125], v[184:187], v[208:211], v[122:125]
	v_mfma_f32_16x16x32_bf16 v[118:121], v[172:175], v[216:219], v[118:121]
	v_mfma_f32_16x16x32_bf16 v[110:113], v[184:187], v[216:219], v[110:113]
	v_mfma_f32_16x16x32_bf16 v[102:105], v[172:175], v[224:227], v[102:105]
	v_mfma_f32_16x16x32_bf16 v[94:97], v[184:187], v[224:227], v[94:97]
	v_mfma_f32_16x16x32_bf16 v[86:89], v[172:175], v[232:235], v[86:89]
	v_mfma_f32_16x16x32_bf16 v[78:81], v[184:187], v[232:235], v[78:81]
	v_mfma_f32_16x16x32_bf16 v[114:117], v[188:191], v[204:207], v[114:117]
	v_mfma_f32_16x16x32_bf16 v[106:109], v[196:199], v[204:207], v[106:109]
	v_mfma_f32_16x16x32_bf16 v[98:101], v[188:191], v[212:215], v[98:101]
	v_mfma_f32_16x16x32_bf16 v[90:93], v[196:199], v[212:215], v[90:93]
	v_mfma_f32_16x16x32_bf16 v[82:85], v[188:191], v[220:223], v[82:85]
	v_mfma_f32_16x16x32_bf16 v[74:77], v[196:199], v[220:223], v[74:77]
	v_mfma_f32_16x16x32_bf16 v[70:73], v[188:191], v[228:231], v[70:73]
	v_mfma_f32_16x16x32_bf16 v[66:69], v[196:199], v[228:231], v[66:69]
	v_mfma_f32_16x16x32_bf16 v[114:117], v[192:195], v[208:211], v[114:117]
	v_mfma_f32_16x16x32_bf16 v[106:109], v[200:203], v[208:211], v[106:109]
	v_mfma_f32_16x16x32_bf16 v[98:101], v[192:195], v[216:219], v[98:101]
	v_mfma_f32_16x16x32_bf16 v[90:93], v[200:203], v[216:219], v[90:93]
	v_mfma_f32_16x16x32_bf16 v[82:85], v[192:195], v[224:227], v[82:85]
	v_mfma_f32_16x16x32_bf16 v[74:77], v[200:203], v[224:227], v[74:77]
	v_mfma_f32_16x16x32_bf16 v[70:73], v[192:195], v[232:235], v[70:73]
	v_mfma_f32_16x16x32_bf16 v[66:69], v[200:203], v[232:235], v[66:69]
	s_barrier
; #define PG8_STAGE(bufoff, gbase, voff) do { _Pragma("unroll") for (int _i = 0; _i < 2; ++_i) \
;         __builtin_amdgcn_global_load_lds((const unsigned*)((const char*)(gbase) + (voff)[_i]), (LAS unsigned*)(lds + (bufoff) + ldsw + _i * 8192), 16, 0, 0); } while (0)
; #define PG8_LDA(dst, b, h) do { _Pragma("unroll") for (int m = 0; m < 4; ++m) _Pragma("unroll") for (int k = 0; k < 2; ++k) dst[m][k] = *(const LAS bf16x8*)(lds + PG8_SA(b, h) + aoff + m * 2048 + k * 1024); } while (0)
; #define PG8_LDB(dst, b, h) do { _Pragma("unroll") for (int n = 0; n < 2; ++n) _Pragma("unroll") for (int k = 0; k < 2; ++k) dst[n][k] = *(const LAS bf16x8*)(lds + PG8_SB(b, h) + boff + n * 2048 + k * 1024); } while (0)
; #define PG8_BAR __builtin_amdgcn_s_barrier()
; template <class Epi, bool ALIGN_EPI = PG8_ALIGN, bool SP2 = PG8_SP2>
; __device__ __forceinline__ void gemm_phase(LAS uchar* lds, const Gemm g, const StaticOrder& S, const Epi& E) {
;     ...
;         for (int t = tb; t < tb + tblk; t += 2) {
;             const bool last = (t == nt - 2);
;             const char* a1 = cA + (size_t)(t + 1) * kstep;
;             const char* a2 = last ? nA : cA + (size_t)(t + 2) * kstep; const char* b2 = last ? nB : cB + (size_t)(t + 2) * kstep;
;             const char* a3 = a2 + kstep; const char* b3 = b2 + kstep;
;             if constexpr (SP2) {
;             PG8_LDB(B0, 0, 0); PG8_LDB(B1, 0, 1); PG8_SCHED; PG8_LDA(At, 0, 0); PG8_STAGE(PG8_SA(1, 1), a1 + hstepA, voffA);
;             PG8_WAIT_V(8); PG8_WAIT_L(0); PG8_BAR; PG8_MMA(0, 0, At, B0); PG8_MMA(0, 1, At, B1); PG8_BAR; PG8_SCHED;
;             PG8_LDA(At, 0, 1); PG8_STAGE(PG8_SB(0, 0), b2, voffB); PG8_STAGE(PG8_SB(0, 1), b2 + hstepB, voffB); PG8_STAGE(PG8_SA(0, 0), a2, voffA);
;             PG8_WAIT_V(8); PG8_WAIT_L(0); PG8_BAR; PG8_MMA(1, 0, At, B0); PG8_MMA(1, 1, At, B1); PG8_BAR; PG8_SCHED;
;             PG8_LDB(B0, 1, 0); PG8_LDB(B1, 1, 1); PG8_SCHED; PG8_LDA(At, 1, 0); PG8_STAGE(PG8_SA(0, 1), a2 + hstepA, voffA);
;             PG8_WAIT_V(8); PG8_WAIT_L(0); PG8_BAR; PG8_MMA(0, 0, At, B0); PG8_MMA(0, 1, At, B1); PG8_BAR; PG8_SCHED;
;             PG8_LDA(At, 1, 1); PG8_STAGE(PG8_SB(1, 0), b3, voffB); PG8_STAGE(PG8_SB(1, 1), b3 + hstepB, voffB); PG8_STAGE(PG8_SA(1, 0), a3, voffA);
;             PG8_WAIT_V(8); PG8_WAIT_L(0); PG8_BAR; PG8_MMA(1, 0, At, B0); PG8_MMA(1, 1, At, B1); PG8_BAR; PG8_SCHED;
	s_setprio 0
	s_add_i32 s16, s41, s23
	v_lshl_add_u64 v[168:169], v[168:169], 0, s[84:85]
	s_mov_b32 m0, s16
	ds_read_b128 v[204:207], v171 offset:49152
	ds_read_b128 v[208:211], v171 offset:50176
	ds_read_b128 v[212:215], v171 offset:51200
	ds_read_b128 v[216:219], v171 offset:52224
	ds_read_b128 v[220:223], v171 offset:53248
	ds_read_b128 v[224:227], v171 offset:54272
	ds_read_b128 v[228:231], v171 offset:55296
	ds_read_b128 v[232:235], v171 offset:56320
	global_load_lds_dwordx4 v[168:169], off
	s_add_i32 m0, s16, 0x2000
	s_add_u32 s4, s4, 0x44080
	v_lshl_add_u64 v[168:169], v[180:181], 0, s[84:85]
	s_addc_u32 s5, s5, 0
	s_add_i32 s16, s42, s23
	global_load_lds_dwordx4 v[168:169], off
	s_mov_b32 m0, s16
	v_lshl_add_u64 v[168:169], s[4:5], 0, v[134:135]
	global_load_lds_dwordx4 v[168:169], off
	s_add_i32 m0, s16, 0x2000
	v_lshl_add_u64 v[168:169], s[4:5], 0, v[130:131]
	global_load_lds_dwordx4 v[168:169], off
	s_mov_b32 m0, s29
	v_lshl_add_u64 v[168:169], v[236:237], 0, s[84:85]
	global_load_lds_dwordx4 v[168:169], off
	s_mov_b32 m0, s30
	v_lshl_add_u64 v[168:169], v[238:239], 0, s[84:85]
	global_load_lds_dwordx4 v[168:169], off
	s_setprio 1
	s_waitcnt vmcnt(8) lgkmcnt(0)
	s_barrier
	v_mfma_f32_16x16x32_bf16 v[62:65], v[164:167], v[204:207], v[62:65]
	v_mfma_f32_16x16x32_bf16 v[58:61], v[176:179], v[204:207], v[58:61]
	v_mfma_f32_16x16x32_bf16 v[54:57], v[164:167], v[212:215], v[54:57]
	v_mfma_f32_16x16x32_bf16 v[46:49], v[176:179], v[212:215], v[46:49]
	v_mfma_f32_16x16x32_bf16 v[38:41], v[164:167], v[220:223], v[38:41]
	v_mfma_f32_16x16x32_bf16 v[30:33], v[176:179], v[220:223], v[30:33]
	v_mfma_f32_16x16x32_bf16 v[22:25], v[164:167], v[228:231], v[22:25]
	v_mfma_f32_16x16x32_bf16 v[14:17], v[176:179], v[228:231], v[14:17]
	v_mfma_f32_16x16x32_bf16 v[62:65], v[172:175], v[208:211], v[62:65]
	v_mfma_f32_16x16x32_bf16 v[58:61], v[184:187], v[208:211], v[58:61]
	v_mfma_f32_16x16x32_bf16 v[54:57], v[172:175], v[216:219], v[54:57]
	v_mfma_f32_16x16x32_bf16 v[46:49], v[184:187], v[216:219], v[46:49]
	v_mfma_f32_16x16x32_bf16 v[38:41], v[172:175], v[224:227], v[38:41]
	v_mfma_f32_16x16x32_bf16 v[30:33], v[184:187], v[224:227], v[30:33]
	v_mfma_f32_16x16x32_bf16 v[22:25], v[172:175], v[232:235], v[22:25]
	v_mfma_f32_16x16x32_bf16 v[14:17], v[184:187], v[232:235], v[14:17]
	v_mfma_f32_16x16x32_bf16 v[50:53], v[188:191], v[204:207], v[50:53]
	v_mfma_f32_16x16x32_bf16 v[42:45], v[196:199], v[204:207], v[42:45]
	v_mfma_f32_16x16x32_bf16 v[34:37], v[188:191], v[212:215], v[34:37]
	v_mfma_f32_16x16x32_bf16 v[26:29], v[196:199], v[212:215], v[26:29]
	v_mfma_f32_16x16x32_bf16 v[18:21], v[188:191], v[220:223], v[18:21]
	v_mfma_f32_16x16x32_bf16 v[10:13], v[196:199], v[220:223], v[10:13]
	v_mfma_f32_16x16x32_bf16 v[6:9], v[188:191], v[228:231], v[6:9]
	v_mfma_f32_16x16x32_bf16 v[2:5], v[196:199], v[228:231], v[2:5]
	v_mfma_f32_16x16x32_bf16 v[50:53], v[192:195], v[208:211], v[50:53]
	v_mfma_f32_16x16x32_bf16 v[42:45], v[200:203], v[208:211], v[42:45]
	v_mfma_f32_16x16x32_bf16 v[34:37], v[192:195], v[216:219], v[34:37]
	v_mfma_f32_16x16x32_bf16 v[26:29], v[200:203], v[216:219], v[26:29]
	v_mfma_f32_16x16x32_bf16 v[18:21], v[192:195], v[224:227], v[18:21]
	v_mfma_f32_16x16x32_bf16 v[10:13], v[200:203], v[224:227], v[10:13]
	v_mfma_f32_16x16x32_bf16 v[6:9], v[192:195], v[232:235], v[6:9]
	v_mfma_f32_16x16x32_bf16 v[2:5], v[200:203], v[232:235], v[2:5]
	s_barrier
	s_setprio 0
	s_add_i32 s40, s40, 2
	s_add_u32 s38, s38, 0x100
	s_addc_u32 s39, s39, 0
	s_cmp_gt_u32 s40, 13
	s_mov_b64 s[16:17], s[18:19]
.LBB0_345:
	s_add_u32 s18, s16, 0x100
	s_addc_u32 s19, s17, 0
	s_add_i32 s41, 0, 0x10000
	s_cmp_eq_u32 s40, 12
	s_cselect_b32 s21, s7, s19
	s_cselect_b32 s20, s6, s18
	v_add_u32_e32 v168, s41, v139
	s_cselect_b32 s5, s15, s39
	s_cselect_b32 s4, s14, s38
	s_add_i32 s42, 0, 0x14000
	ds_read_b128 v[164:167], v168
	ds_read_b128 v[172:175], v168 offset:1024
	ds_read_b128 v[176:179], v168 offset:2048
	ds_read_b128 v[184:187], v168 offset:3072
	v_add_u32_e32 v168, s42, v139
	ds_read_b128 v[188:191], v168
	ds_read_b128 v[192:195], v168 offset:1024
	ds_read_b128 v[196:199], v168 offset:2048
	ds_read_b128 v[200:203], v168 offset:3072
	v_lshl_add_u64 v[168:169], s[16:17], 0, v[160:161]
	s_add_i32 m0, s25, 0xc000
	ds_read_b128 v[204:207], v171
	ds_read_b128 v[208:211], v171 offset:1024
	ds_read_b128 v[212:215], v171 offset:2048
	ds_read_b128 v[216:219], v171 offset:3072
	ds_read_b128 v[220:223], v171 offset:4096
	ds_read_b128 v[224:227], v171 offset:5120
	ds_read_b128 v[228:231], v171 offset:6144
	ds_read_b128 v[232:235], v171 offset:7168
	global_load_lds_dwordx4 v[168:169], off
	s_add_i32 m0, s25, 0xe000
	v_lshl_add_u64 v[168:169], s[16:17], 0, v[162:163]
	global_load_lds_dwordx4 v[168:169], off
	s_setprio 1
	s_waitcnt vmcnt(8) lgkmcnt(0)
	s_barrier
; #define PG8_STAGE(bufoff, gbase, voff) do { _Pragma("unroll") for (int _i = 0; _i < 2; ++_i) \
;         __builtin_amdgcn_global_load_lds((const unsigned*)((const char*)(gbase) + (voff)[_i]), (LAS unsigned*)(lds + (bufoff) + ldsw + _i * 8192), 16, 0, 0); } while (0)
; #define PG8_LDA(dst, b, h) do { _Pragma("unroll") for (int m = 0; m < 4; ++m) _Pragma("unroll") for (int k = 0; k < 2; ++k) dst[m][k] = *(const LAS bf16x8*)(lds + PG8_SA(b, h) + aoff + m * 2048 + k * 1024); } while (0)
; #define PG8_LDB(dst, b, h) do { _Pragma("unroll") for (int n = 0; n < 2; ++n) _Pragma("unroll") for (int k = 0; k < 2; ++k) dst[n][k] = *(const LAS bf16x8*)(lds + PG8_SB(b, h) + boff + n * 2048 + k * 1024); } while (0)
; #define PG8_MMA(ai, bj, At, Bt) do { __builtin_amdgcn_s_setprio(1); _Pragma("unroll") for (int m = 0; m < 4; ++m) _Pragma("unroll") for (int n = 0; n < 2; ++n) _Pragma("unroll") for (int k = 0; k < 2; ++k) \
;         acc[ai][bj][m][n] = __builtin_amdgcn_mfma_f32_16x16x32_bf16(Bt[n][k], At[m][k], acc[ai][bj][m][n], 0, 0, 0); __builtin_amdgcn_s_setprio(0); } while (0)
; #define PG8_WAIT_V(n) asm volatile("s_waitcnt vmcnt(" #n ")" ::: "memory")
; #define PG8_WAIT_L(n) asm volatile("s_waitcnt lgkmcnt(" #n ")" ::: "memory")
; #define PG8_BAR __builtin_amdgcn_s_barrier()
; #define PG8_SCHED __builtin_amdgcn_sched_barrier(0)
; template <class Epi, bool ALIGN_EPI = PG8_ALIGN, bool SP2 = PG8_SP2>
; __device__ __forceinline__ void gemm_phase(LAS uchar* lds, const Gemm g, const StaticOrder& S, const Epi& E) {
;     ...
;             PG8_LDB(B0, 0, 0); PG8_LDB(B1, 0, 1); PG8_SCHED; PG8_LDA(At, 0, 0); PG8_STAGE(PG8_SA(1, 1), a1 + hstepA, voffA);
;             PG8_WAIT_V(8); PG8_WAIT_L(0); PG8_BAR; PG8_MMA(0, 0, At, B0); PG8_MMA(0, 1, At, B1); PG8_BAR; PG8_SCHED;
;             PG8_LDA(At, 0, 1); PG8_STAGE(PG8_SB(0, 0), b2, voffB); PG8_STAGE(PG8_SB(0, 1), b2 + hstepB, voffB); PG8_STAGE(PG8_SA(0, 0), a2, voffA);
;             PG8_WAIT_V(8); PG8_WAIT_L(0); PG8_BAR; PG8_MMA(1, 0, At, B0); PG8_MMA(1, 1, At, B1); PG8_BAR; PG8_SCHED;
	v_mfma_f32_16x16x32_bf16 v[126:129], v[164:167], v[204:207], v[126:129]
	v_mfma_f32_16x16x32_bf16 v[122:125], v[176:179], v[204:207], v[122:125]
	v_mfma_f32_16x16x32_bf16 v[118:121], v[164:167], v[212:215], v[118:121]
	v_mfma_f32_16x16x32_bf16 v[110:113], v[176:179], v[212:215], v[110:113]
	v_mfma_f32_16x16x32_bf16 v[102:105], v[164:167], v[220:223], v[102:105]
	v_mfma_f32_16x16x32_bf16 v[94:97], v[176:179], v[220:223], v[94:97]
	v_mfma_f32_16x16x32_bf16 v[86:89], v[164:167], v[228:231], v[86:89]
	v_mfma_f32_16x16x32_bf16 v[78:81], v[176:179], v[228:231], v[78:81]
	v_mfma_f32_16x16x32_bf16 v[126:129], v[172:175], v[208:211], v[126:129]
	v_mfma_f32_16x16x32_bf16 v[122:125], v[184:187], v[208:211], v[122:125]
	v_mfma_f32_16x16x32_bf16 v[118:121], v[172:175], v[216:219], v[118:121]
	v_mfma_f32_16x16x32_bf16 v[110:113], v[184:187], v[216:219], v[110:113]
	v_mfma_f32_16x16x32_bf16 v[102:105], v[172:175], v[224:227], v[102:105]
	v_mfma_f32_16x16x32_bf16 v[94:97], v[184:187], v[224:227], v[94:97]
	v_mfma_f32_16x16x32_bf16 v[86:89], v[172:175], v[232:235], v[86:89]
	v_mfma_f32_16x16x32_bf16 v[78:81], v[184:187], v[232:235], v[78:81]
	v_mfma_f32_16x16x32_bf16 v[114:117], v[188:191], v[204:207], v[114:117]
	v_mfma_f32_16x16x32_bf16 v[106:109], v[196:199], v[204:207], v[106:109]
	v_mfma_f32_16x16x32_bf16 v[98:101], v[188:191], v[212:215], v[98:101]
	v_mfma_f32_16x16x32_bf16 v[90:93], v[196:199], v[212:215], v[90:93]
	v_mfma_f32_16x16x32_bf16 v[82:85], v[188:191], v[220:223], v[82:85]
	v_mfma_f32_16x16x32_bf16 v[74:77], v[196:199], v[220:223], v[74:77]
	v_mfma_f32_16x16x32_bf16 v[70:73], v[188:191], v[228:231], v[70:73]
	v_mfma_f32_16x16x32_bf16 v[66:69], v[196:199], v[228:231], v[66:69]
	v_mfma_f32_16x16x32_bf16 v[114:117], v[192:195], v[208:211], v[114:117]
	v_mfma_f32_16x16x32_bf16 v[106:109], v[200:203], v[208:211], v[106:109]
	v_mfma_f32_16x16x32_bf16 v[98:101], v[192:195], v[216:219], v[98:101]
	v_mfma_f32_16x16x32_bf16 v[90:93], v[200:203], v[216:219], v[90:93]
	v_mfma_f32_16x16x32_bf16 v[82:85], v[192:195], v[224:227], v[82:85]
	v_mfma_f32_16x16x32_bf16 v[74:77], v[200:203], v[224:227], v[74:77]
	v_mfma_f32_16x16x32_bf16 v[70:73], v[192:195], v[232:235], v[70:73]
	v_mfma_f32_16x16x32_bf16 v[66:69], v[200:203], v[232:235], v[66:69]
	s_barrier
	s_setprio 0
	s_add_i32 s16, s41, s23
	v_lshl_add_u64 v[168:169], s[4:5], 0, v[134:135]
	s_mov_b32 m0, s16
	ds_read_b128 v[204:207], v171 offset:16384
	ds_read_b128 v[208:211], v171 offset:17408
	ds_read_b128 v[212:215], v171 offset:18432
	ds_read_b128 v[216:219], v171 offset:19456
	ds_read_b128 v[220:223], v171 offset:20480
	ds_read_b128 v[224:227], v171 offset:21504
	ds_read_b128 v[228:231], v171 offset:22528
	ds_read_b128 v[232:235], v171 offset:23552
	global_load_lds_dwordx4 v[168:169], off
	s_add_i32 m0, s16, 0x2000
	s_add_u32 s16, s4, 0x44000
	v_lshl_add_u64 v[180:181], s[4:5], 0, v[130:131]
	s_addc_u32 s17, s5, 0
	s_add_i32 s41, s42, s23
	global_load_lds_dwordx4 v[180:181], off
	v_lshl_add_u64 v[236:237], s[16:17], 0, v[134:135]
	s_mov_b32 m0, s41
	global_load_lds_dwordx4 v[236:237], off
	s_add_i32 m0, s41, 0x2000
	v_lshl_add_u64 v[236:237], s[16:17], 0, v[130:131]
	global_load_lds_dwordx4 v[236:237], off
	s_mov_b32 m0, s25
	v_lshl_add_u64 v[236:237], s[20:21], 0, v[156:157]
	global_load_lds_dwordx4 v[236:237], off
	s_mov_b32 m0, s26
	v_lshl_add_u64 v[238:239], s[20:21], 0, v[132:133]
	global_load_lds_dwordx4 v[238:239], off
	s_setprio 1
	s_waitcnt vmcnt(8) lgkmcnt(0)
	s_barrier
	v_mfma_f32_16x16x32_bf16 v[62:65], v[164:167], v[204:207], v[62:65]
	v_mfma_f32_16x16x32_bf16 v[58:61], v[176:179], v[204:207], v[58:61]
	v_mfma_f32_16x16x32_bf16 v[54:57], v[164:167], v[212:215], v[54:57]
	v_mfma_f32_16x16x32_bf16 v[46:49], v[176:179], v[212:215], v[46:49]
	v_mfma_f32_16x16x32_bf16 v[38:41], v[164:167], v[220:223], v[38:41]
	v_mfma_f32_16x16x32_bf16 v[30:33], v[176:179], v[220:223], v[30:33]
	v_mfma_f32_16x16x32_bf16 v[22:25], v[164:167], v[228:231], v[22:25]
	v_mfma_f32_16x16x32_bf16 v[14:17], v[176:179], v[228:231], v[14:17]
	v_mfma_f32_16x16x32_bf16 v[62:65], v[172:175], v[208:211], v[62:65]
	v_mfma_f32_16x16x32_bf16 v[58:61], v[184:187], v[208:211], v[58:61]
	v_mfma_f32_16x16x32_bf16 v[54:57], v[172:175], v[216:219], v[54:57]
	v_mfma_f32_16x16x32_bf16 v[46:49], v[184:187], v[216:219], v[46:49]
	v_mfma_f32_16x16x32_bf16 v[38:41], v[172:175], v[224:227], v[38:41]
	v_mfma_f32_16x16x32_bf16 v[30:33], v[184:187], v[224:227], v[30:33]
	v_mfma_f32_16x16x32_bf16 v[22:25], v[172:175], v[232:235], v[22:25]
	v_mfma_f32_16x16x32_bf16 v[14:17], v[184:187], v[232:235], v[14:17]
	v_mfma_f32_16x16x32_bf16 v[50:53], v[188:191], v[204:207], v[50:53]
	v_mfma_f32_16x16x32_bf16 v[42:45], v[196:199], v[204:207], v[42:45]
	v_mfma_f32_16x16x32_bf16 v[34:37], v[188:191], v[212:215], v[34:37]
	v_mfma_f32_16x16x32_bf16 v[26:29], v[196:199], v[212:215], v[26:29]
	v_mfma_f32_16x16x32_bf16 v[18:21], v[188:191], v[220:223], v[18:21]
	v_mfma_f32_16x16x32_bf16 v[10:13], v[196:199], v[220:223], v[10:13]
	v_mfma_f32_16x16x32_bf16 v[6:9], v[188:191], v[228:231], v[6:9]
	v_mfma_f32_16x16x32_bf16 v[2:5], v[196:199], v[228:231], v[2:5]
	v_mfma_f32_16x16x32_bf16 v[50:53], v[192:195], v[208:211], v[50:53]
	v_mfma_f32_16x16x32_bf16 v[42:45], v[200:203], v[208:211], v[42:45]
	v_mfma_f32_16x16x32_bf16 v[34:37], v[192:195], v[216:219], v[34:37]
	v_mfma_f32_16x16x32_bf16 v[26:29], v[200:203], v[216:219], v[26:29]
	v_mfma_f32_16x16x32_bf16 v[18:21], v[192:195], v[224:227], v[18:21]
	v_mfma_f32_16x16x32_bf16 v[10:13], v[200:203], v[224:227], v[10:13]
	v_mfma_f32_16x16x32_bf16 v[6:9], v[192:195], v[232:235], v[6:9]
	v_mfma_f32_16x16x32_bf16 v[2:5], v[200:203], v[232:235], v[2:5]
	s_barrier
; #define PG8_STAGE(bufoff, gbase, voff) do { _Pragma("unroll") for (int _i = 0; _i < 2; ++_i) \
;         __builtin_amdgcn_global_load_lds((const unsigned*)((const char*)(gbase) + (voff)[_i]), (LAS unsigned*)(lds + (bufoff) + ldsw + _i * 8192), 16, 0, 0); } while (0)
; #define PG8_LDA(dst, b, h) do { _Pragma("unroll") for (int m = 0; m < 4; ++m) _Pragma("unroll") for (int k = 0; k < 2; ++k) dst[m][k] = *(const LAS bf16x8*)(lds + PG8_SA(b, h) + aoff + m * 2048 + k * 1024); } while (0)
; #define PG8_LDB(dst, b, h) do { _Pragma("unroll") for (int n = 0; n < 2; ++n) _Pragma("unroll") for (int k = 0; k < 2; ++k) dst[n][k] = *(const LAS bf16x8*)(lds + PG8_SB(b, h) + boff + n * 2048 + k * 1024); } while (0)
; #define PG8_MMA(ai, bj, At, Bt) do { __builtin_amdgcn_s_setprio(1); _Pragma("unroll") for (int m = 0; m < 4; ++m) _Pragma("unroll") for (int n = 0; n < 2; ++n) _Pragma("unroll") for (int k = 0; k < 2; ++k) \
;         acc[ai][bj][m][n] = __builtin_amdgcn_mfma_f32_16x16x32_bf16(Bt[n][k], At[m][k], acc[ai][bj][m][n], 0, 0, 0); __builtin_amdgcn_s_setprio(0); } while (0)
; #define PG8_WAIT_V(n) asm volatile("s_waitcnt vmcnt(" #n ")" ::: "memory")
; #define PG8_WAIT_L(n) asm volatile("s_waitcnt lgkmcnt(" #n ")" ::: "memory")
; #define PG8_BAR __builtin_amdgcn_s_barrier()
; #define PG8_SCHED __builtin_amdgcn_sched_barrier(0)
; template <class Epi, bool ALIGN_EPI = PG8_ALIGN, bool SP2 = PG8_SP2>
; __device__ __forceinline__ void gemm_phase(LAS uchar* lds, const Gemm g, const StaticOrder& S, const Epi& E) {
;     ...
;             PG8_LDB(B0, 1, 0); PG8_LDB(B1, 1, 1); PG8_SCHED; PG8_LDA(At, 1, 0); PG8_STAGE(PG8_SA(0, 1), a2 + hstepA, voffA);
;             PG8_WAIT_V(8); PG8_WAIT_L(0); PG8_BAR; PG8_MMA(0, 0, At, B0); PG8_MMA(0, 1, At, B1); PG8_BAR; PG8_SCHED;
	s_setprio 0
	s_add_i32 s41, 0, 0x18000
	s_add_i32 s42, 0, 0x1c000
	v_add_u32_e32 v184, s41, v139
	v_add_u32_e32 v200, s42, v139
	ds_read_b128 v[164:167], v184
	ds_read_b128 v[172:175], v184 offset:1024
	ds_read_b128 v[176:179], v184 offset:2048
	ds_read_b128 v[184:187], v184 offset:3072
	ds_read_b128 v[188:191], v200
	ds_read_b128 v[192:195], v200 offset:1024
	ds_read_b128 v[196:199], v200 offset:2048
	ds_read_b128 v[200:203], v200 offset:3072
	s_add_u32 s16, s20, 0x44000
	s_addc_u32 s17, s21, 0
	s_mov_b32 m0, s27
	v_lshl_add_u64 v[240:241], s[16:17], 0, v[156:157]
	ds_read_b128 v[204:207], v171 offset:32768
	ds_read_b128 v[208:211], v171 offset:33792
	ds_read_b128 v[212:215], v171 offset:34816
	ds_read_b128 v[216:219], v171 offset:35840
	ds_read_b128 v[220:223], v171 offset:36864
	ds_read_b128 v[224:227], v171 offset:37888
	ds_read_b128 v[228:231], v171 offset:38912
	ds_read_b128 v[232:235], v171 offset:39936
	global_load_lds_dwordx4 v[240:241], off
	s_mov_b32 m0, s28
	v_lshl_add_u64 v[240:241], s[16:17], 0, v[132:133]
	global_load_lds_dwordx4 v[240:241], off
	s_setprio 1
	s_waitcnt vmcnt(8) lgkmcnt(0)
	s_barrier
	v_mfma_f32_16x16x32_bf16 v[126:129], v[164:167], v[204:207], v[126:129]
	v_mfma_f32_16x16x32_bf16 v[122:125], v[176:179], v[204:207], v[122:125]
	v_mfma_f32_16x16x32_bf16 v[118:121], v[164:167], v[212:215], v[118:121]
	v_mfma_f32_16x16x32_bf16 v[110:113], v[176:179], v[212:215], v[110:113]
	v_mfma_f32_16x16x32_bf16 v[102:105], v[164:167], v[220:223], v[102:105]
	v_mfma_f32_16x16x32_bf16 v[94:97], v[176:179], v[220:223], v[94:97]
	v_mfma_f32_16x16x32_bf16 v[86:89], v[164:167], v[228:231], v[86:89]
	v_mfma_f32_16x16x32_bf16 v[78:81], v[176:179], v[228:231], v[78:81]
	v_mfma_f32_16x16x32_bf16 v[126:129], v[172:175], v[208:211], v[126:129]
	v_mfma_f32_16x16x32_bf16 v[122:125], v[184:187], v[208:211], v[122:125]
	v_mfma_f32_16x16x32_bf16 v[118:121], v[172:175], v[216:219], v[118:121]
	v_mfma_f32_16x16x32_bf16 v[110:113], v[184:187], v[216:219], v[110:113]
	v_mfma_f32_16x16x32_bf16 v[102:105], v[172:175], v[224:227], v[102:105]
	v_mfma_f32_16x16x32_bf16 v[94:97], v[184:187], v[224:227], v[94:97]
	v_mfma_f32_16x16x32_bf16 v[86:89], v[172:175], v[232:235], v[86:89]
	v_mfma_f32_16x16x32_bf16 v[78:81], v[184:187], v[232:235], v[78:81]
	v_mfma_f32_16x16x32_bf16 v[114:117], v[188:191], v[204:207], v[114:117]
	v_mfma_f32_16x16x32_bf16 v[106:109], v[196:199], v[204:207], v[106:109]
	v_mfma_f32_16x16x32_bf16 v[98:101], v[188:191], v[212:215], v[98:101]
	v_mfma_f32_16x16x32_bf16 v[90:93], v[196:199], v[212:215], v[90:93]
	v_mfma_f32_16x16x32_bf16 v[82:85], v[188:191], v[220:223], v[82:85]
	v_mfma_f32_16x16x32_bf16 v[74:77], v[196:199], v[220:223], v[74:77]
	v_mfma_f32_16x16x32_bf16 v[70:73], v[188:191], v[228:231], v[70:73]
	v_mfma_f32_16x16x32_bf16 v[66:69], v[196:199], v[228:231], v[66:69]
	v_mfma_f32_16x16x32_bf16 v[114:117], v[192:195], v[208:211], v[114:117]
	v_mfma_f32_16x16x32_bf16 v[106:109], v[200:203], v[208:211], v[106:109]
	v_mfma_f32_16x16x32_bf16 v[98:101], v[192:195], v[216:219], v[98:101]
	v_mfma_f32_16x16x32_bf16 v[90:93], v[200:203], v[216:219], v[90:93]
	v_mfma_f32_16x16x32_bf16 v[82:85], v[192:195], v[224:227], v[82:85]
	v_mfma_f32_16x16x32_bf16 v[74:77], v[200:203], v[224:227], v[74:77]
	v_mfma_f32_16x16x32_bf16 v[70:73], v[192:195], v[232:235], v[70:73]
	v_mfma_f32_16x16x32_bf16 v[66:69], v[200:203], v[232:235], v[66:69]
	s_barrier
; #define PG8_STAGE(bufoff, gbase, voff) do { _Pragma("unroll") for (int _i = 0; _i < 2; ++_i) \
;         __builtin_amdgcn_global_load_lds((const unsigned*)((const char*)(gbase) + (voff)[_i]), (LAS unsigned*)(lds + (bufoff) + ldsw + _i * 8192), 16, 0, 0); } while (0)
; #define PG8_LDA(dst, b, h) do { _Pragma("unroll") for (int m = 0; m < 4; ++m) _Pragma("unroll") for (int k = 0; k < 2; ++k) dst[m][k] = *(const LAS bf16x8*)(lds + PG8_SA(b, h) + aoff + m * 2048 + k * 1024); } while (0)
; #define PG8_MMA(ai, bj, At, Bt) do { __builtin_amdgcn_s_setprio(1); _Pragma("unroll") for (int m = 0; m < 4; ++m) _Pragma("unroll") for (int n = 0; n < 2; ++n) _Pragma("unroll") for (int k = 0; k < 2; ++k) \
;         acc[ai][bj][m][n] = __builtin_amdgcn_mfma_f32_16x16x32_bf16(Bt[n][k], At[m][k], acc[ai][bj][m][n], 0, 0, 0); __builtin_amdgcn_s_setprio(0); } while (0)
; #define PG8_WAIT_V(n) asm volatile("s_waitcnt vmcnt(" #n ")" ::: "memory")
; #define PG8_WAIT_L(n) asm volatile("s_waitcnt lgkmcnt(" #n ")" ::: "memory")
; #define PG8_BAR __builtin_amdgcn_s_barrier()
; #define PG8_SCHED __builtin_amdgcn_sched_barrier(0)
; template <class Epi, bool ALIGN_EPI = PG8_ALIGN, bool SP2 = PG8_SP2>
; __device__ __forceinline__ void gemm_phase(LAS uchar* lds, const Gemm g, const StaticOrder& S, const Epi& E) {
;     ...
;         for (int t = tb; t < tb + tblk; t += 2) {
;             const bool last = (t == nt - 2);
;             const char* a1 = cA + (size_t)(t + 1) * kstep;
;             const char* a2 = last ? nA : cA + (size_t)(t + 2) * kstep; const char* b2 = last ? nB : cB + (size_t)(t + 2) * kstep;
;             const char* a3 = a2 + kstep; const char* b3 = b2 + kstep;
;     ...
;             PG8_LDA(At, 1, 1); PG8_STAGE(PG8_SB(1, 0), b3, voffB); PG8_STAGE(PG8_SB(1, 1), b3 + hstepB, voffB); PG8_STAGE(PG8_SA(1, 0), a3, voffA);
;             PG8_WAIT_V(8); PG8_WAIT_L(0); PG8_BAR; PG8_MMA(1, 0, At, B0); PG8_MMA(1, 1, At, B1); PG8_BAR; PG8_SCHED;
;     __device__ __forceinline__ void operator()(const f32x4 (&acc)[2][2][4][2], const pg8::Unit& u, int wr, int wc, int fr, int fq, int) const {
;         const int row0 = u.pm * 256 + wr * 64 + fr;
;         if (u.pn < 24) {
	s_setprio 0
	s_add_i32 s16, s41, s23
	v_lshl_add_u64 v[168:169], v[168:169], 0, s[84:85]
	s_mov_b32 m0, s16
	ds_read_b128 v[204:207], v171 offset:49152
	ds_read_b128 v[208:211], v171 offset:50176
	ds_read_b128 v[212:215], v171 offset:51200
	ds_read_b128 v[216:219], v171 offset:52224
	ds_read_b128 v[220:223], v171 offset:53248
	ds_read_b128 v[224:227], v171 offset:54272
	ds_read_b128 v[228:231], v171 offset:55296
	ds_read_b128 v[232:235], v171 offset:56320
	global_load_lds_dwordx4 v[168:169], off
	s_add_i32 m0, s16, 0x2000
	s_add_u32 s4, s4, 0x44080
	v_lshl_add_u64 v[168:169], v[180:181], 0, s[84:85]
	s_addc_u32 s5, s5, 0
	s_add_i32 s16, s42, s23
	global_load_lds_dwordx4 v[168:169], off
	s_mov_b32 m0, s16
	v_lshl_add_u64 v[168:169], s[4:5], 0, v[134:135]
	global_load_lds_dwordx4 v[168:169], off
	s_add_i32 m0, s16, 0x2000
	v_lshl_add_u64 v[168:169], s[4:5], 0, v[130:131]
	global_load_lds_dwordx4 v[168:169], off
	s_mov_b32 m0, s29
	v_lshl_add_u64 v[168:169], v[236:237], 0, s[84:85]
	global_load_lds_dwordx4 v[168:169], off
	s_mov_b32 m0, s30
	v_lshl_add_u64 v[168:169], v[238:239], 0, s[84:85]
	global_load_lds_dwordx4 v[168:169], off
	s_setprio 1
	s_waitcnt vmcnt(8) lgkmcnt(0)
	s_barrier
	v_mfma_f32_16x16x32_bf16 v[62:65], v[164:167], v[204:207], v[62:65]
	v_mfma_f32_16x16x32_bf16 v[58:61], v[176:179], v[204:207], v[58:61]
	v_mfma_f32_16x16x32_bf16 v[54:57], v[164:167], v[212:215], v[54:57]
	v_mfma_f32_16x16x32_bf16 v[46:49], v[176:179], v[212:215], v[46:49]
	v_mfma_f32_16x16x32_bf16 v[38:41], v[164:167], v[220:223], v[38:41]
	v_mfma_f32_16x16x32_bf16 v[30:33], v[176:179], v[220:223], v[30:33]
	v_mfma_f32_16x16x32_bf16 v[22:25], v[164:167], v[228:231], v[22:25]
	v_mfma_f32_16x16x32_bf16 v[14:17], v[176:179], v[228:231], v[14:17]
	v_mfma_f32_16x16x32_bf16 v[62:65], v[172:175], v[208:211], v[62:65]
	v_mfma_f32_16x16x32_bf16 v[58:61], v[184:187], v[208:211], v[58:61]
	v_mfma_f32_16x16x32_bf16 v[54:57], v[172:175], v[216:219], v[54:57]
	v_mfma_f32_16x16x32_bf16 v[46:49], v[184:187], v[216:219], v[46:49]
	v_mfma_f32_16x16x32_bf16 v[38:41], v[172:175], v[224:227], v[38:41]
	v_mfma_f32_16x16x32_bf16 v[30:33], v[184:187], v[224:227], v[30:33]
	v_mfma_f32_16x16x32_bf16 v[22:25], v[172:175], v[232:235], v[22:25]
	v_mfma_f32_16x16x32_bf16 v[14:17], v[184:187], v[232:235], v[14:17]
	v_mfma_f32_16x16x32_bf16 v[50:53], v[188:191], v[204:207], v[50:53]
	v_mfma_f32_16x16x32_bf16 v[42:45], v[196:199], v[204:207], v[42:45]
	v_mfma_f32_16x16x32_bf16 v[34:37], v[188:191], v[212:215], v[34:37]
	v_mfma_f32_16x16x32_bf16 v[26:29], v[196:199], v[212:215], v[26:29]
	v_mfma_f32_16x16x32_bf16 v[18:21], v[188:191], v[220:223], v[18:21]
	v_mfma_f32_16x16x32_bf16 v[10:13], v[196:199], v[220:223], v[10:13]
	v_mfma_f32_16x16x32_bf16 v[6:9], v[188:191], v[228:231], v[6:9]
	v_mfma_f32_16x16x32_bf16 v[2:5], v[196:199], v[228:231], v[2:5]
	v_mfma_f32_16x16x32_bf16 v[50:53], v[192:195], v[208:211], v[50:53]
	v_mfma_f32_16x16x32_bf16 v[42:45], v[200:203], v[208:211], v[42:45]
	v_mfma_f32_16x16x32_bf16 v[34:37], v[192:195], v[216:219], v[34:37]
	v_mfma_f32_16x16x32_bf16 v[26:29], v[200:203], v[216:219], v[26:29]
	v_mfma_f32_16x16x32_bf16 v[18:21], v[192:195], v[224:227], v[18:21]
	v_mfma_f32_16x16x32_bf16 v[10:13], v[200:203], v[224:227], v[10:13]
	v_mfma_f32_16x16x32_bf16 v[6:9], v[192:195], v[232:235], v[6:9]
	v_mfma_f32_16x16x32_bf16 v[2:5], v[200:203], v[232:235], v[2:5]
	s_barrier
	s_setprio 0
	s_add_i32 s40, s40, 2
	s_add_u32 s38, s38, 0x100
	s_addc_u32 s39, s39, 0
	s_cmp_gt_u32 s40, 13
	s_mov_b64 s[16:17], s[18:19]
	s_cbranch_scc0 .LBB0_345
	s_mov_b32 s97, 0
	s_and_b64 vcc, exec, s[10:11]
	s_cbranch_vccnz .LBB0_350
	v_lshl_add_u32 v164, s37, 8, v1
	s_cmp_gt_i32 s36, 23
	s_mov_b64 s[4:5], -1
	s_cbranch_scc1 .LBB0_351

; #define PG8_STAGE(bufoff, gbase, voff) do { _Pragma("unroll") for (int _i = 0; _i < 2; ++_i) \
;         __builtin_amdgcn_global_load_lds((const unsigned*)((const char*)(gbase) + (voff)[_i]), (LAS unsigned*)(lds + (bufoff) + ldsw + _i * 8192), 16, 0, 0); } while (0)
; #define PG8_LDA(dst, b, h) do { _Pragma("unroll") for (int m = 0; m < 4; ++m) _Pragma("unroll") for (int k = 0; k < 2; ++k) dst[m][k] = *(const LAS bf16x8*)(lds + PG8_SA(b, h) + aoff + m * 2048 + k * 1024); } while (0)
; #define PG8_LDB(dst, b, h) do { _Pragma("unroll") for (int n = 0; n < 2; ++n) _Pragma("unroll") for (int k = 0; k < 2; ++k) dst[n][k] = *(const LAS bf16x8*)(lds + PG8_SB(b, h) + boff + n * 2048 + k * 1024); } while (0)
; #define PG8_WAIT_V(n) asm volatile("s_waitcnt vmcnt(" #n ")" ::: "memory")
; #define PG8_WAIT_L(n) asm volatile("s_waitcnt lgkmcnt(" #n ")" ::: "memory")
; #define PG8_BAR __builtin_amdgcn_s_barrier()
; #define PG8_SCHED __builtin_amdgcn_sched_barrier(0)
; template <class Epi, bool ALIGN_EPI = PG8_ALIGN, bool SP2 = PG8_SP2>
; __device__ __forceinline__ void gemm_phase(LAS uchar* lds, const Gemm g, const StaticOrder& S, const Epi& E) {
;     ...
;         for (int t = tb; t < tb + tblk; t += 2) {
;             const bool last = (t == nt - 2);
;             const char* a1 = cA + (size_t)(t + 1) * kstep;
;             const char* a2 = last ? nA : cA + (size_t)(t + 2) * kstep; const char* b2 = last ? nB : cB + (size_t)(t + 2) * kstep;
;             const char* a3 = a2 + kstep; const char* b3 = b2 + kstep;
;             if constexpr (SP2) {
;             PG8_LDB(B0, 0, 0); PG8_LDB(B1, 0, 1); PG8_SCHED; PG8_LDA(At, 0, 0); PG8_STAGE(PG8_SA(1, 1), a1 + hstepA, voffA);
;             PG8_WAIT_V(8); PG8_WAIT_L(0); PG8_BAR; PG8_MMA(0, 0, At, B0); PG8_MMA(0, 1, At, B1); PG8_BAR; PG8_SCHED;
;             PG8_LDA(At, 0, 1); PG8_STAGE(PG8_SB(0, 0), b2, voffB); PG8_STAGE(PG8_SB(0, 1), b2 + hstepB, voffB); PG8_STAGE(PG8_SA(0, 0), a2, voffA);
;             PG8_WAIT_V(8); PG8_WAIT_L(0); PG8_BAR; PG8_MMA(1, 0, At, B0); PG8_MMA(1, 1, At, B1); PG8_BAR; PG8_SCHED;
;             PG8_LDB(B0, 1, 0); PG8_LDB(B1, 1, 1); PG8_SCHED; PG8_LDA(At, 1, 0); PG8_STAGE(PG8_SA(0, 1), a2 + hstepA, voffA);
;             PG8_WAIT_V(8); PG8_WAIT_L(0); PG8_BAR; PG8_MMA(0, 0, At, B0); PG8_MMA(0, 1, At, B1); PG8_BAR; PG8_SCHED;
.LBB0_580:
	s_add_i32 s42, s42, 2
	s_add_u32 s4, s14, s18
	s_addc_u32 s5, s15, s19
	s_add_u32 s4, s4, 0x100
	s_addc_u32 s5, s5, 0
	s_add_u32 s43, s38, s18
	s_addc_u32 s44, s39, s19
	s_add_i32 s45, 0, 0x10000
	s_cmpk_eq_i32 s18, 0xf00
	s_cselect_b32 s21, s1, s5
	s_cselect_b32 s20, s0, s4
	v_add_u32_e32 v1, s45, v168
	s_cselect_b32 s5, s13, s44
	s_cselect_b32 s4, s12, s43
	s_add_i32 s43, 0, 0x14000
	ds_read_b128 v[174:177], v1
	ds_read_b128 v[178:181], v1 offset:1024
	ds_read_b128 v[184:187], v1 offset:2048
	ds_read_b128 v[188:191], v1 offset:3072
	v_add_u32_e32 v1, s43, v168
	ds_read_b128 v[192:195], v1
	ds_read_b128 v[196:199], v1 offset:1024
	ds_read_b128 v[200:203], v1 offset:2048
	ds_read_b128 v[204:207], v1 offset:3072
	v_lshl_add_u64 v[2:3], v[164:165], 0, s[18:19]
	s_add_i32 m0, s25, 0xc000
	ds_read_b128 v[208:211], v170
	ds_read_b128 v[212:215], v170 offset:1024
	ds_read_b128 v[216:219], v170 offset:2048
	ds_read_b128 v[220:223], v170 offset:3072
	ds_read_b128 v[224:227], v170 offset:4096
	ds_read_b128 v[228:231], v170 offset:5120
	ds_read_b128 v[232:235], v170 offset:6144
	ds_read_b128 v[236:239], v170 offset:7168
	global_load_lds_dwordx4 v[2:3], off
	s_add_i32 m0, s25, 0xe000
	v_lshl_add_u64 v[2:3], v[166:167], 0, s[18:19]
	global_load_lds_dwordx4 v[2:3], off
	s_setprio 1
	s_waitcnt vmcnt(8) lgkmcnt(0)
	s_barrier
	v_mfma_f32_16x16x32_bf16 v[128:131], v[174:177], v[208:211], v[128:131]
	v_mfma_f32_16x16x32_bf16 v[124:127], v[184:187], v[208:211], v[124:127]
	v_mfma_f32_16x16x32_bf16 v[112:115], v[174:177], v[216:219], v[112:115]
	v_mfma_f32_16x16x32_bf16 v[108:111], v[184:187], v[216:219], v[108:111]
	v_mfma_f32_16x16x32_bf16 v[96:99], v[174:177], v[224:227], v[96:99]
	v_mfma_f32_16x16x32_bf16 v[92:95], v[184:187], v[224:227], v[92:95]
	v_mfma_f32_16x16x32_bf16 v[80:83], v[174:177], v[232:235], v[80:83]
	v_mfma_f32_16x16x32_bf16 v[76:79], v[184:187], v[232:235], v[76:79]
	v_mfma_f32_16x16x32_bf16 v[128:131], v[178:181], v[212:215], v[128:131]
	v_mfma_f32_16x16x32_bf16 v[124:127], v[188:191], v[212:215], v[124:127]
	v_mfma_f32_16x16x32_bf16 v[112:115], v[178:181], v[220:223], v[112:115]
	v_mfma_f32_16x16x32_bf16 v[108:111], v[188:191], v[220:223], v[108:111]
	v_mfma_f32_16x16x32_bf16 v[96:99], v[178:181], v[228:231], v[96:99]
	v_mfma_f32_16x16x32_bf16 v[92:95], v[188:191], v[228:231], v[92:95]
	v_mfma_f32_16x16x32_bf16 v[80:83], v[178:181], v[236:239], v[80:83]
	v_mfma_f32_16x16x32_bf16 v[76:79], v[188:191], v[236:239], v[76:79]
	v_mfma_f32_16x16x32_bf16 v[120:123], v[192:195], v[208:211], v[120:123]
	v_mfma_f32_16x16x32_bf16 v[116:119], v[200:203], v[208:211], v[116:119]
	v_mfma_f32_16x16x32_bf16 v[104:107], v[192:195], v[216:219], v[104:107]
	v_mfma_f32_16x16x32_bf16 v[100:103], v[200:203], v[216:219], v[100:103]
	v_mfma_f32_16x16x32_bf16 v[88:91], v[192:195], v[224:227], v[88:91]
	v_mfma_f32_16x16x32_bf16 v[84:87], v[200:203], v[224:227], v[84:87]
	v_mfma_f32_16x16x32_bf16 v[72:75], v[192:195], v[232:235], v[72:75]
	v_mfma_f32_16x16x32_bf16 v[68:71], v[200:203], v[232:235], v[68:71]
	v_mfma_f32_16x16x32_bf16 v[120:123], v[196:199], v[212:215], v[120:123]
	v_mfma_f32_16x16x32_bf16 v[116:119], v[204:207], v[212:215], v[116:119]
	v_mfma_f32_16x16x32_bf16 v[104:107], v[196:199], v[220:223], v[104:107]
	v_mfma_f32_16x16x32_bf16 v[100:103], v[204:207], v[220:223], v[100:103]
	v_mfma_f32_16x16x32_bf16 v[88:91], v[196:199], v[228:231], v[88:91]
	v_mfma_f32_16x16x32_bf16 v[84:87], v[204:207], v[228:231], v[84:87]
	v_mfma_f32_16x16x32_bf16 v[72:75], v[196:199], v[236:239], v[72:75]
	v_mfma_f32_16x16x32_bf16 v[68:71], v[204:207], v[236:239], v[68:71]
	s_barrier
	s_setprio 0
	s_add_i32 s44, s45, s24
	v_lshl_add_u64 v[240:241], s[4:5], 0, v[134:135]
	s_mov_b32 m0, s44
	ds_read_b128 v[208:211], v170 offset:16384
	ds_read_b128 v[212:215], v170 offset:17408
	ds_read_b128 v[216:219], v170 offset:18432
	ds_read_b128 v[220:223], v170 offset:19456
	ds_read_b128 v[224:227], v170 offset:20480
	ds_read_b128 v[228:231], v170 offset:21504
	ds_read_b128 v[232:235], v170 offset:22528
	ds_read_b128 v[236:239], v170 offset:23552
	global_load_lds_dwordx4 v[240:241], off
	s_add_i32 m0, s44, 0x2000
	s_add_u32 s44, s4, 0x84000
	v_lshl_add_u64 v[242:243], s[4:5], 0, v[158:159]
	s_addc_u32 s45, s5, 0
	s_add_i32 s43, s43, s24
	global_load_lds_dwordx4 v[242:243], off
	v_lshl_add_u64 v[2:3], s[44:45], 0, v[134:135]
	s_mov_b32 m0, s43
	global_load_lds_dwordx4 v[2:3], off
	v_lshl_add_u64 v[2:3], s[44:45], 0, v[158:159]
	s_add_i32 m0, s43, 0x2000
	global_load_lds_dwordx4 v[2:3], off
	s_mov_b32 m0, s25
	v_lshl_add_u64 v[244:245], s[20:21], 0, v[132:133]
	global_load_lds_dwordx4 v[244:245], off
	s_mov_b32 m0, s26
	v_lshl_add_u64 v[246:247], s[20:21], 0, v[156:157]
	global_load_lds_dwordx4 v[246:247], off
	s_setprio 1
	s_waitcnt vmcnt(8) lgkmcnt(0)
	s_barrier
; #define PG8_STAGE(bufoff, gbase, voff) do { _Pragma("unroll") for (int _i = 0; _i < 2; ++_i) \
;         __builtin_amdgcn_global_load_lds((const unsigned*)((const char*)(gbase) + (voff)[_i]), (LAS unsigned*)(lds + (bufoff) + ldsw + _i * 8192), 16, 0, 0); } while (0)
; #define PG8_LDA(dst, b, h) do { _Pragma("unroll") for (int m = 0; m < 4; ++m) _Pragma("unroll") for (int k = 0; k < 2; ++k) dst[m][k] = *(const LAS bf16x8*)(lds + PG8_SA(b, h) + aoff + m * 2048 + k * 1024); } while (0)
; #define PG8_LDB(dst, b, h) do { _Pragma("unroll") for (int n = 0; n < 2; ++n) _Pragma("unroll") for (int k = 0; k < 2; ++k) dst[n][k] = *(const LAS bf16x8*)(lds + PG8_SB(b, h) + boff + n * 2048 + k * 1024); } while (0)
; #define PG8_MMA(ai, bj, At, Bt) do { __builtin_amdgcn_s_setprio(1); _Pragma("unroll") for (int m = 0; m < 4; ++m) _Pragma("unroll") for (int n = 0; n < 2; ++n) _Pragma("unroll") for (int k = 0; k < 2; ++k) \
;         acc[ai][bj][m][n] = __builtin_amdgcn_mfma_f32_16x16x32_bf16(Bt[n][k], At[m][k], acc[ai][bj][m][n], 0, 0, 0); __builtin_amdgcn_s_setprio(0); } while (0)
; #define PG8_WAIT_V(n) asm volatile("s_waitcnt vmcnt(" #n ")" ::: "memory")
; #define PG8_WAIT_L(n) asm volatile("s_waitcnt lgkmcnt(" #n ")" ::: "memory")
; #define PG8_BAR __builtin_amdgcn_s_barrier()
; #define PG8_SCHED __builtin_amdgcn_sched_barrier(0)
; template <class Epi, bool ALIGN_EPI = PG8_ALIGN, bool SP2 = PG8_SP2>
; __device__ __forceinline__ void gemm_phase(LAS uchar* lds, const Gemm g, const StaticOrder& S, const Epi& E) {
;     ...
;             PG8_WAIT_V(8); PG8_WAIT_L(0); PG8_BAR; PG8_MMA(0, 0, At, B0); PG8_MMA(0, 1, At, B1); PG8_BAR; PG8_SCHED;
;             PG8_LDA(At, 0, 1); PG8_STAGE(PG8_SB(0, 0), b2, voffB); PG8_STAGE(PG8_SB(0, 1), b2 + hstepB, voffB); PG8_STAGE(PG8_SA(0, 0), a2, voffA);
;             PG8_WAIT_V(8); PG8_WAIT_L(0); PG8_BAR; PG8_MMA(1, 0, At, B0); PG8_MMA(1, 1, At, B1); PG8_BAR; PG8_SCHED;
;             PG8_LDB(B0, 1, 0); PG8_LDB(B1, 1, 1); PG8_SCHED; PG8_LDA(At, 1, 0); PG8_STAGE(PG8_SA(0, 1), a2 + hstepA, voffA);
;             PG8_WAIT_V(8); PG8_WAIT_L(0); PG8_BAR; PG8_MMA(0, 0, At, B0); PG8_MMA(0, 1, At, B1); PG8_BAR; PG8_SCHED;
	v_mfma_f32_16x16x32_bf16 v[64:67], v[174:177], v[208:211], v[64:67]
	v_mfma_f32_16x16x32_bf16 v[60:63], v[184:187], v[208:211], v[60:63]
	v_mfma_f32_16x16x32_bf16 v[48:51], v[174:177], v[216:219], v[48:51]
	v_mfma_f32_16x16x32_bf16 v[44:47], v[184:187], v[216:219], v[44:47]
	v_mfma_f32_16x16x32_bf16 v[32:35], v[174:177], v[224:227], v[32:35]
	v_mfma_f32_16x16x32_bf16 v[28:31], v[184:187], v[224:227], v[28:31]
	v_mfma_f32_16x16x32_bf16 v[16:19], v[174:177], v[232:235], v[16:19]
	v_mfma_f32_16x16x32_bf16 v[12:15], v[184:187], v[232:235], v[12:15]
	v_mfma_f32_16x16x32_bf16 v[64:67], v[178:181], v[212:215], v[64:67]
	v_mfma_f32_16x16x32_bf16 v[60:63], v[188:191], v[212:215], v[60:63]
	v_mfma_f32_16x16x32_bf16 v[48:51], v[178:181], v[220:223], v[48:51]
	v_mfma_f32_16x16x32_bf16 v[44:47], v[188:191], v[220:223], v[44:47]
	v_mfma_f32_16x16x32_bf16 v[32:35], v[178:181], v[228:231], v[32:35]
	v_mfma_f32_16x16x32_bf16 v[28:31], v[188:191], v[228:231], v[28:31]
	v_mfma_f32_16x16x32_bf16 v[16:19], v[178:181], v[236:239], v[16:19]
	v_mfma_f32_16x16x32_bf16 v[12:15], v[188:191], v[236:239], v[12:15]
	v_mfma_f32_16x16x32_bf16 v[56:59], v[192:195], v[208:211], v[56:59]
	v_mfma_f32_16x16x32_bf16 v[52:55], v[200:203], v[208:211], v[52:55]
	v_mfma_f32_16x16x32_bf16 v[40:43], v[192:195], v[216:219], v[40:43]
	v_mfma_f32_16x16x32_bf16 v[36:39], v[200:203], v[216:219], v[36:39]
	v_mfma_f32_16x16x32_bf16 v[24:27], v[192:195], v[224:227], v[24:27]
	v_mfma_f32_16x16x32_bf16 v[20:23], v[200:203], v[224:227], v[20:23]
	v_mfma_f32_16x16x32_bf16 v[8:11], v[192:195], v[232:235], v[8:11]
	v_mfma_f32_16x16x32_bf16 v[2:5], v[200:203], v[232:235], v[4:7]
	v_mfma_f32_16x16x32_bf16 v[56:59], v[196:199], v[212:215], v[56:59]
	v_mfma_f32_16x16x32_bf16 v[52:55], v[204:207], v[212:215], v[52:55]
	v_mfma_f32_16x16x32_bf16 v[40:43], v[196:199], v[220:223], v[40:43]
	v_mfma_f32_16x16x32_bf16 v[36:39], v[204:207], v[220:223], v[36:39]
	v_mfma_f32_16x16x32_bf16 v[24:27], v[196:199], v[228:231], v[24:27]
	v_mfma_f32_16x16x32_bf16 v[20:23], v[204:207], v[228:231], v[20:23]
	v_mfma_f32_16x16x32_bf16 v[8:11], v[196:199], v[236:239], v[8:11]
	v_mfma_f32_16x16x32_bf16 v[2:5], v[204:207], v[236:239], v[2:5]
	s_barrier
	s_setprio 0
	s_add_i32 s43, 0, 0x18000
	v_add_u32_e32 v1, s43, v168
	s_add_i32 s44, 0, 0x1c000
	ds_read_b128 v[174:177], v1
	ds_read_b128 v[178:181], v1 offset:1024
	ds_read_b128 v[184:187], v1 offset:2048
	ds_read_b128 v[188:191], v1 offset:3072
	v_add_u32_e32 v1, s44, v168
	ds_read_b128 v[192:195], v1
	ds_read_b128 v[196:199], v1 offset:1024
	ds_read_b128 v[200:203], v1 offset:2048
	ds_read_b128 v[204:207], v1 offset:3072
	s_add_u32 s20, s20, 0x184000
	s_addc_u32 s21, s21, 0
	s_mov_b32 m0, s27
	v_lshl_add_u64 v[6:7], s[20:21], 0, v[132:133]
	ds_read_b128 v[208:211], v170 offset:32768
	ds_read_b128 v[212:215], v170 offset:33792
	ds_read_b128 v[216:219], v170 offset:34816
	ds_read_b128 v[220:223], v170 offset:35840
	ds_read_b128 v[224:227], v170 offset:36864
	ds_read_b128 v[228:231], v170 offset:37888
	ds_read_b128 v[232:235], v170 offset:38912
	ds_read_b128 v[236:239], v170 offset:39936
	global_load_lds_dwordx4 v[6:7], off
	s_mov_b32 m0, s28
	v_lshl_add_u64 v[6:7], s[20:21], 0, v[156:157]
	global_load_lds_dwordx4 v[6:7], off
	s_setprio 1
	s_waitcnt vmcnt(8) lgkmcnt(0)
	s_barrier
	v_mfma_f32_16x16x32_bf16 v[128:131], v[174:177], v[208:211], v[128:131]
	v_mfma_f32_16x16x32_bf16 v[124:127], v[184:187], v[208:211], v[124:127]
	v_mfma_f32_16x16x32_bf16 v[112:115], v[174:177], v[216:219], v[112:115]
	v_mfma_f32_16x16x32_bf16 v[108:111], v[184:187], v[216:219], v[108:111]
	v_mfma_f32_16x16x32_bf16 v[96:99], v[174:177], v[224:227], v[96:99]
	v_mfma_f32_16x16x32_bf16 v[92:95], v[184:187], v[224:227], v[92:95]
	v_mfma_f32_16x16x32_bf16 v[80:83], v[174:177], v[232:235], v[80:83]
	v_mfma_f32_16x16x32_bf16 v[76:79], v[184:187], v[232:235], v[76:79]
	v_mfma_f32_16x16x32_bf16 v[128:131], v[178:181], v[212:215], v[128:131]
	v_mfma_f32_16x16x32_bf16 v[124:127], v[188:191], v[212:215], v[124:127]
	v_mfma_f32_16x16x32_bf16 v[112:115], v[178:181], v[220:223], v[112:115]
	v_mfma_f32_16x16x32_bf16 v[108:111], v[188:191], v[220:223], v[108:111]
	v_mfma_f32_16x16x32_bf16 v[96:99], v[178:181], v[228:231], v[96:99]
	v_mfma_f32_16x16x32_bf16 v[92:95], v[188:191], v[228:231], v[92:95]
	v_mfma_f32_16x16x32_bf16 v[80:83], v[178:181], v[236:239], v[80:83]
	v_mfma_f32_16x16x32_bf16 v[76:79], v[188:191], v[236:239], v[76:79]
	v_mfma_f32_16x16x32_bf16 v[120:123], v[192:195], v[208:211], v[120:123]
	v_mfma_f32_16x16x32_bf16 v[116:119], v[200:203], v[208:211], v[116:119]
	v_mfma_f32_16x16x32_bf16 v[104:107], v[192:195], v[216:219], v[104:107]
	v_mfma_f32_16x16x32_bf16 v[100:103], v[200:203], v[216:219], v[100:103]
	v_mfma_f32_16x16x32_bf16 v[88:91], v[192:195], v[224:227], v[88:91]
	v_mfma_f32_16x16x32_bf16 v[84:87], v[200:203], v[224:227], v[84:87]
	v_mfma_f32_16x16x32_bf16 v[72:75], v[192:195], v[232:235], v[72:75]
	v_mfma_f32_16x16x32_bf16 v[68:71], v[200:203], v[232:235], v[68:71]
	v_mfma_f32_16x16x32_bf16 v[120:123], v[196:199], v[212:215], v[120:123]
	v_mfma_f32_16x16x32_bf16 v[116:119], v[204:207], v[212:215], v[116:119]
	v_mfma_f32_16x16x32_bf16 v[104:107], v[196:199], v[220:223], v[104:107]
	v_mfma_f32_16x16x32_bf16 v[100:103], v[204:207], v[220:223], v[100:103]
	v_mfma_f32_16x16x32_bf16 v[88:91], v[196:199], v[228:231], v[88:91]
	v_mfma_f32_16x16x32_bf16 v[84:87], v[204:207], v[228:231], v[84:87]
	v_mfma_f32_16x16x32_bf16 v[72:75], v[196:199], v[236:239], v[72:75]
	v_mfma_f32_16x16x32_bf16 v[68:71], v[204:207], v[236:239], v[68:71]
	s_barrier
; #define LAS __attribute__((address_space(3)))
; #define PG8_STAGE(bufoff, gbase, voff) do { _Pragma("unroll") for (int _i = 0; _i < 2; ++_i) \
;         __builtin_amdgcn_global_load_lds((const unsigned*)((const char*)(gbase) + (voff)[_i]), (LAS unsigned*)(lds + (bufoff) + ldsw + _i * 8192), 16, 0, 0); } while (0)
; #define PG8_LDA(dst, b, h) do { _Pragma("unroll") for (int m = 0; m < 4; ++m) _Pragma("unroll") for (int k = 0; k < 2; ++k) dst[m][k] = *(const LAS bf16x8*)(lds + PG8_SA(b, h) + aoff + m * 2048 + k * 1024); } while (0)
; #define PG8_MMA(ai, bj, At, Bt) do { __builtin_amdgcn_s_setprio(1); _Pragma("unroll") for (int m = 0; m < 4; ++m) _Pragma("unroll") for (int n = 0; n < 2; ++n) _Pragma("unroll") for (int k = 0; k < 2; ++k) \
;         acc[ai][bj][m][n] = __builtin_amdgcn_mfma_f32_16x16x32_bf16(Bt[n][k], At[m][k], acc[ai][bj][m][n], 0, 0, 0); __builtin_amdgcn_s_setprio(0); } while (0)
; #define PG8_BAR __builtin_amdgcn_s_barrier()
; template <class Epi, bool ALIGN_EPI = PG8_ALIGN, bool SP2 = PG8_SP2>
; __device__ __forceinline__ void gemm_phase(LAS uchar* lds, const Gemm g, const StaticOrder& S, const Epi& E) {
;     ...
; #pragma unroll 1
;         for (int tb = 0; tb < nt; tb += tblk) {
;         if constexpr (Epi::GROUPS) { if (tb > 0) {
;             const LAS float* rt = (const LAS float*)(lds + LDS_RT) + ((ui & 1) * 256 + wr * 64 + fr) * 8 + ((tb >> 2) - 1);
; #pragma unroll
;             for (int a = 0; a < 2; ++a)
; #pragma unroll
;                 for (int m = 0; m < 4; ++m) { const float f = rt[(a * 128 + m * 16) * 8];
; #pragma unroll
;                     for (int b = 0; b < 2; ++b)
; #pragma unroll
;                         for (int n = 0; n < 2; ++n) acc[a][b][m][n] *= f; } } }
; #pragma unroll 1
;         for (int t = tb; t < tb + tblk; t += 2) {
;             const bool last = (t == nt - 2);
;             const char* a1 = cA + (size_t)(t + 1) * kstep;
;             const char* a2 = last ? nA : cA + (size_t)(t + 2) * kstep; const char* b2 = last ? nB : cB + (size_t)(t + 2) * kstep;
;             const char* a3 = a2 + kstep; const char* b3 = b2 + kstep;
;     ...
;             PG8_LDA(At, 1, 1); PG8_STAGE(PG8_SB(1, 0), b3, voffB); PG8_STAGE(PG8_SB(1, 1), b3 + hstepB, voffB); PG8_STAGE(PG8_SA(1, 0), a3, voffA);
;             PG8_WAIT_V(8); PG8_WAIT_L(0); PG8_BAR; PG8_MMA(1, 0, At, B0); PG8_MMA(1, 1, At, B1); PG8_BAR; PG8_SCHED;
	s_setprio 0
	s_add_i32 s20, s43, s24
	v_lshl_add_u64 v[6:7], v[240:241], 0, s[84:85]
	s_mov_b32 m0, s20
	ds_read_b128 v[208:211], v170 offset:49152
	ds_read_b128 v[212:215], v170 offset:50176
	ds_read_b128 v[216:219], v170 offset:51200
	ds_read_b128 v[220:223], v170 offset:52224
	ds_read_b128 v[224:227], v170 offset:53248
	ds_read_b128 v[228:231], v170 offset:54272
	ds_read_b128 v[232:235], v170 offset:55296
	ds_read_b128 v[236:239], v170 offset:56320
	global_load_lds_dwordx4 v[6:7], off
	s_add_i32 m0, s20, 0x2000
	s_add_u32 s4, s4, 0x84080
	v_lshl_add_u64 v[6:7], v[242:243], 0, s[84:85]
	s_addc_u32 s5, s5, 0
	s_add_i32 s20, s44, s24
	global_load_lds_dwordx4 v[6:7], off
	s_mov_b32 m0, s20
	v_lshl_add_u64 v[6:7], s[4:5], 0, v[134:135]
	global_load_lds_dwordx4 v[6:7], off
	s_add_i32 m0, s20, 0x2000
	v_lshl_add_u64 v[6:7], s[4:5], 0, v[158:159]
	global_load_lds_dwordx4 v[6:7], off
	s_mov_b32 m0, s29
	v_lshl_add_u64 v[6:7], v[244:245], 0, s[84:85]
	global_load_lds_dwordx4 v[6:7], off
	s_mov_b32 m0, s30
	v_lshl_add_u64 v[6:7], v[246:247], 0, s[84:85]
	global_load_lds_dwordx4 v[6:7], off
	s_setprio 1
	s_waitcnt vmcnt(8) lgkmcnt(0)
	s_barrier
	v_mfma_f32_16x16x32_bf16 v[64:67], v[174:177], v[208:211], v[64:67]
	v_mfma_f32_16x16x32_bf16 v[60:63], v[184:187], v[208:211], v[60:63]
	v_mfma_f32_16x16x32_bf16 v[48:51], v[174:177], v[216:219], v[48:51]
	v_mfma_f32_16x16x32_bf16 v[44:47], v[184:187], v[216:219], v[44:47]
	v_mfma_f32_16x16x32_bf16 v[32:35], v[174:177], v[224:227], v[32:35]
	v_mfma_f32_16x16x32_bf16 v[28:31], v[184:187], v[224:227], v[28:31]
	v_mfma_f32_16x16x32_bf16 v[16:19], v[174:177], v[232:235], v[16:19]
	v_mfma_f32_16x16x32_bf16 v[12:15], v[184:187], v[232:235], v[12:15]
	v_mfma_f32_16x16x32_bf16 v[64:67], v[178:181], v[212:215], v[64:67]
	v_mfma_f32_16x16x32_bf16 v[60:63], v[188:191], v[212:215], v[60:63]
	v_mfma_f32_16x16x32_bf16 v[48:51], v[178:181], v[220:223], v[48:51]
	v_mfma_f32_16x16x32_bf16 v[44:47], v[188:191], v[220:223], v[44:47]
	v_mfma_f32_16x16x32_bf16 v[32:35], v[178:181], v[228:231], v[32:35]
	v_mfma_f32_16x16x32_bf16 v[28:31], v[188:191], v[228:231], v[28:31]
	v_mfma_f32_16x16x32_bf16 v[16:19], v[178:181], v[236:239], v[16:19]
	v_mfma_f32_16x16x32_bf16 v[12:15], v[188:191], v[236:239], v[12:15]
	v_mfma_f32_16x16x32_bf16 v[56:59], v[192:195], v[208:211], v[56:59]
	v_mfma_f32_16x16x32_bf16 v[52:55], v[200:203], v[208:211], v[52:55]
	v_mfma_f32_16x16x32_bf16 v[40:43], v[192:195], v[216:219], v[40:43]
	v_mfma_f32_16x16x32_bf16 v[36:39], v[200:203], v[216:219], v[36:39]
	v_mfma_f32_16x16x32_bf16 v[24:27], v[192:195], v[224:227], v[24:27]
	v_mfma_f32_16x16x32_bf16 v[20:23], v[200:203], v[224:227], v[20:23]
	v_mfma_f32_16x16x32_bf16 v[6:9], v[192:195], v[232:235], v[8:11]
	v_mfma_f32_16x16x32_bf16 v[2:5], v[200:203], v[232:235], v[2:5]
	v_mfma_f32_16x16x32_bf16 v[56:59], v[196:199], v[212:215], v[56:59]
	v_mfma_f32_16x16x32_bf16 v[52:55], v[204:207], v[212:215], v[52:55]
	v_mfma_f32_16x16x32_bf16 v[40:43], v[196:199], v[220:223], v[40:43]
	v_mfma_f32_16x16x32_bf16 v[36:39], v[204:207], v[220:223], v[36:39]
	v_mfma_f32_16x16x32_bf16 v[24:27], v[196:199], v[228:231], v[24:27]
	v_mfma_f32_16x16x32_bf16 v[20:23], v[204:207], v[228:231], v[20:23]
	v_mfma_f32_16x16x32_bf16 v[8:11], v[196:199], v[236:239], v[6:9]
	v_mfma_f32_16x16x32_bf16 v[4:7], v[204:207], v[236:239], v[2:5]
	s_barrier
	s_setprio 0
	s_add_u32 s18, s18, 0x100
	s_addc_u32 s19, s19, 0
	s_cmp_ge_u32 s42, s41
	s_cbranch_scc0 .LBB0_580
	s_add_u32 s16, s16, 0x200
	s_addc_u32 s17, s17, 0
	s_cmp_lt_u32 s40, 28
	s_cbranch_scc0 .LBB0_583
	s_mov_b32 s40, s41
	s_cmp_eq_u32 s40, 0
	s_cbranch_scc0 .LBB0_578
	s_branch .LBB0_579

; #define PG8_STAGE(bufoff, gbase, voff) do { _Pragma("unroll") for (int _i = 0; _i < 2; ++_i) \
;         __builtin_amdgcn_global_load_lds((const unsigned*)((const char*)(gbase) + (voff)[_i]), (LAS unsigned*)(lds + (bufoff) + ldsw + _i * 8192), 16, 0, 0); } while (0)
; #define PG8_LDA(dst, b, h) do { _Pragma("unroll") for (int m = 0; m < 4; ++m) _Pragma("unroll") for (int k = 0; k < 2; ++k) dst[m][k] = *(const LAS bf16x8*)(lds + PG8_SA(b, h) + aoff + m * 2048 + k * 1024); } while (0)
; #define PG8_LDB(dst, b, h) do { _Pragma("unroll") for (int n = 0; n < 2; ++n) _Pragma("unroll") for (int k = 0; k < 2; ++k) dst[n][k] = *(const LAS bf16x8*)(lds + PG8_SB(b, h) + boff + n * 2048 + k * 1024); } while (0)
; #define PG8_MMA(ai, bj, At, Bt) do { __builtin_amdgcn_s_setprio(1); _Pragma("unroll") for (int m = 0; m < 4; ++m) _Pragma("unroll") for (int n = 0; n < 2; ++n) _Pragma("unroll") for (int k = 0; k < 2; ++k) \
;         acc[ai][bj][m][n] = __builtin_amdgcn_mfma_f32_16x16x32_bf16(Bt[n][k], At[m][k], acc[ai][bj][m][n], 0, 0, 0); __builtin_amdgcn_s_setprio(0); } while (0)
; #define PG8_WAIT_V(n) asm volatile("s_waitcnt vmcnt(" #n ")" ::: "memory")
; #define PG8_WAIT_L(n) asm volatile("s_waitcnt lgkmcnt(" #n ")" ::: "memory")
; #define PG8_BAR __builtin_amdgcn_s_barrier()
; template <class Epi, bool ALIGN_EPI = PG8_ALIGN, bool SP2 = PG8_SP2>
; __device__ __forceinline__ void gemm_phase(LAS uchar* lds, const Gemm g, const StaticOrder& S, const Epi& E) {
;     ...
;         for (int t = tb; t < tb + tblk; t += 2) {
;             const bool last = (t == nt - 2);
;             const char* a1 = cA + (size_t)(t + 1) * kstep;
;             const char* a2 = last ? nA : cA + (size_t)(t + 2) * kstep; const char* b2 = last ? nB : cB + (size_t)(t + 2) * kstep;
;             const char* a3 = a2 + kstep; const char* b3 = b2 + kstep;
;             if constexpr (SP2) {
;             PG8_LDB(B0, 0, 0); PG8_LDB(B1, 0, 1); PG8_SCHED; PG8_LDA(At, 0, 0); PG8_STAGE(PG8_SA(1, 1), a1 + hstepA, voffA);
;             PG8_WAIT_V(8); PG8_WAIT_L(0); PG8_BAR; PG8_MMA(0, 0, At, B0); PG8_MMA(0, 1, At, B1); PG8_BAR; PG8_SCHED;
;             PG8_LDA(At, 0, 1); PG8_STAGE(PG8_SB(0, 0), b2, voffB); PG8_STAGE(PG8_SB(0, 1), b2 + hstepB, voffB); PG8_STAGE(PG8_SA(0, 0), a2, voffA);
;             PG8_WAIT_V(8); PG8_WAIT_L(0); PG8_BAR; PG8_MMA(1, 0, At, B0); PG8_MMA(1, 1, At, B1); PG8_BAR; PG8_SCHED;
.LBB0_668:
	s_add_u32 s36, s14, 0x100
	s_addc_u32 s37, s15, 0
	s_mov_b32 s38, -2
	s_add_u32 s14, s12, 0x100
	s_addc_u32 s15, s13, 0
	s_add_i32 s39, 0, 0x10000
	s_cmp_eq_u32 s38, 12
	s_cselect_b32 s19, s5, s15
	s_cselect_b32 s18, s4, s14
	s_cselect_b32 s17, s11, s37
	s_cselect_b32 s16, s10, s36
	s_add_i32 s40, 0, 0x14000
	v_add_u32_e32 v174, s39, v139
	v_add_u32_e32 v192, s40, v139
	ds_read_b128 v[160:163], v174
	ds_read_b128 v[164:167], v174 offset:1024
	ds_read_b128 v[168:171], v174 offset:2048
	ds_read_b128 v[174:177], v174 offset:3072
	ds_read_b128 v[178:181], v192
	ds_read_b128 v[184:187], v192 offset:1024
	ds_read_b128 v[188:191], v192 offset:2048
	ds_read_b128 v[192:195], v192 offset:3072
	v_lshl_add_u64 v[228:229], s[12:13], 0, v[156:157]
	s_add_i32 m0, s23, 0xc000
	ds_read_b128 v[196:199], v173
	ds_read_b128 v[200:203], v173 offset:1024
	ds_read_b128 v[204:207], v173 offset:2048
	ds_read_b128 v[208:211], v173 offset:3072
	ds_read_b128 v[212:215], v173 offset:4096
	ds_read_b128 v[216:219], v173 offset:5120
	ds_read_b128 v[220:223], v173 offset:6144
	ds_read_b128 v[224:227], v173 offset:7168
	global_load_lds_dwordx4 v[228:229], off
	s_add_i32 m0, s23, 0xe000
	v_lshl_add_u64 v[228:229], s[12:13], 0, v[158:159]
	global_load_lds_dwordx4 v[228:229], off
	s_setprio 1
	s_waitcnt vmcnt(8) lgkmcnt(0)
	s_barrier
	v_mfma_f32_16x16x32_bf16 v[126:129], v[160:163], v[196:199], 0
	v_mfma_f32_16x16x32_bf16 v[122:125], v[168:171], v[196:199], 0
	v_mfma_f32_16x16x32_bf16 v[118:121], v[160:163], v[204:207], 0
	v_mfma_f32_16x16x32_bf16 v[110:113], v[168:171], v[204:207], 0
	v_mfma_f32_16x16x32_bf16 v[102:105], v[160:163], v[212:215], 0
	v_mfma_f32_16x16x32_bf16 v[94:97], v[168:171], v[212:215], 0
	v_mfma_f32_16x16x32_bf16 v[86:89], v[160:163], v[220:223], 0
	v_mfma_f32_16x16x32_bf16 v[78:81], v[168:171], v[220:223], 0
	v_mfma_f32_16x16x32_bf16 v[126:129], v[164:167], v[200:203], v[126:129]
	v_mfma_f32_16x16x32_bf16 v[122:125], v[174:177], v[200:203], v[122:125]
	v_mfma_f32_16x16x32_bf16 v[118:121], v[164:167], v[208:211], v[118:121]
	v_mfma_f32_16x16x32_bf16 v[110:113], v[174:177], v[208:211], v[110:113]
	v_mfma_f32_16x16x32_bf16 v[102:105], v[164:167], v[216:219], v[102:105]
	v_mfma_f32_16x16x32_bf16 v[94:97], v[174:177], v[216:219], v[94:97]
	v_mfma_f32_16x16x32_bf16 v[86:89], v[164:167], v[224:227], v[86:89]
	v_mfma_f32_16x16x32_bf16 v[78:81], v[174:177], v[224:227], v[78:81]
	v_mfma_f32_16x16x32_bf16 v[114:117], v[178:181], v[196:199], 0
	v_mfma_f32_16x16x32_bf16 v[106:109], v[188:191], v[196:199], 0
	v_mfma_f32_16x16x32_bf16 v[98:101], v[178:181], v[204:207], 0
	v_mfma_f32_16x16x32_bf16 v[90:93], v[188:191], v[204:207], 0
	v_mfma_f32_16x16x32_bf16 v[82:85], v[178:181], v[212:215], 0
	v_mfma_f32_16x16x32_bf16 v[74:77], v[188:191], v[212:215], 0
	v_mfma_f32_16x16x32_bf16 v[70:73], v[178:181], v[220:223], 0
	v_mfma_f32_16x16x32_bf16 v[66:69], v[188:191], v[220:223], 0
	v_mfma_f32_16x16x32_bf16 v[114:117], v[184:187], v[200:203], v[114:117]
	v_mfma_f32_16x16x32_bf16 v[106:109], v[192:195], v[200:203], v[106:109]
	v_mfma_f32_16x16x32_bf16 v[98:101], v[184:187], v[208:211], v[98:101]
	v_mfma_f32_16x16x32_bf16 v[90:93], v[192:195], v[208:211], v[90:93]
	v_mfma_f32_16x16x32_bf16 v[82:85], v[184:187], v[216:219], v[82:85]
	v_mfma_f32_16x16x32_bf16 v[74:77], v[192:195], v[216:219], v[74:77]
	v_mfma_f32_16x16x32_bf16 v[70:73], v[184:187], v[224:227], v[70:73]
	v_mfma_f32_16x16x32_bf16 v[66:69], v[192:195], v[224:227], v[66:69]
	s_barrier
	s_setprio 0
	s_add_i32 s12, s39, s21
	v_lshl_add_u64 v[228:229], s[16:17], 0, v[134:135]
	s_mov_b32 m0, s12
	ds_read_b128 v[196:199], v173 offset:16384
	ds_read_b128 v[200:203], v173 offset:17408
	ds_read_b128 v[204:207], v173 offset:18432
	ds_read_b128 v[208:211], v173 offset:19456
	ds_read_b128 v[212:215], v173 offset:20480
	ds_read_b128 v[216:219], v173 offset:21504
	ds_read_b128 v[220:223], v173 offset:22528
	ds_read_b128 v[224:227], v173 offset:23552
	global_load_lds_dwordx4 v[228:229], off
	s_add_i32 m0, s12, 0x2000
	s_add_u32 s12, s16, 0x44000
	v_lshl_add_u64 v[230:231], s[16:17], 0, v[130:131]
	s_addc_u32 s13, s17, 0
	s_add_i32 s39, s40, s21
	global_load_lds_dwordx4 v[230:231], off
	v_lshl_add_u64 v[232:233], s[12:13], 0, v[134:135]
	s_mov_b32 m0, s39
	global_load_lds_dwordx4 v[232:233], off
	s_add_i32 m0, s39, 0x2000
	v_lshl_add_u64 v[232:233], s[12:13], 0, v[130:131]
	global_load_lds_dwordx4 v[232:233], off
	s_mov_b32 m0, s23
	v_lshl_add_u64 v[232:233], s[18:19], 0, v[152:153]
	global_load_lds_dwordx4 v[232:233], off
	s_mov_b32 m0, s24
	v_lshl_add_u64 v[234:235], s[18:19], 0, v[132:133]
	global_load_lds_dwordx4 v[234:235], off
	s_setprio 1
	s_waitcnt vmcnt(8) lgkmcnt(0)
	s_barrier
; #define PG8_STAGE(bufoff, gbase, voff) do { _Pragma("unroll") for (int _i = 0; _i < 2; ++_i) \
;         __builtin_amdgcn_global_load_lds((const unsigned*)((const char*)(gbase) + (voff)[_i]), (LAS unsigned*)(lds + (bufoff) + ldsw + _i * 8192), 16, 0, 0); } while (0)
; #define PG8_LDA(dst, b, h) do { _Pragma("unroll") for (int m = 0; m < 4; ++m) _Pragma("unroll") for (int k = 0; k < 2; ++k) dst[m][k] = *(const LAS bf16x8*)(lds + PG8_SA(b, h) + aoff + m * 2048 + k * 1024); } while (0)
; #define PG8_LDB(dst, b, h) do { _Pragma("unroll") for (int n = 0; n < 2; ++n) _Pragma("unroll") for (int k = 0; k < 2; ++k) dst[n][k] = *(const LAS bf16x8*)(lds + PG8_SB(b, h) + boff + n * 2048 + k * 1024); } while (0)
; #define PG8_MMA(ai, bj, At, Bt) do { __builtin_amdgcn_s_setprio(1); _Pragma("unroll") for (int m = 0; m < 4; ++m) _Pragma("unroll") for (int n = 0; n < 2; ++n) _Pragma("unroll") for (int k = 0; k < 2; ++k) \
;         acc[ai][bj][m][n] = __builtin_amdgcn_mfma_f32_16x16x32_bf16(Bt[n][k], At[m][k], acc[ai][bj][m][n], 0, 0, 0); __builtin_amdgcn_s_setprio(0); } while (0)
; #define PG8_WAIT_V(n) asm volatile("s_waitcnt vmcnt(" #n ")" ::: "memory")
; #define PG8_WAIT_L(n) asm volatile("s_waitcnt lgkmcnt(" #n ")" ::: "memory")
; #define PG8_BAR __builtin_amdgcn_s_barrier()
; #define PG8_SCHED __builtin_amdgcn_sched_barrier(0)
; template <class Epi, bool ALIGN_EPI = PG8_ALIGN, bool SP2 = PG8_SP2>
; __device__ __forceinline__ void gemm_phase(LAS uchar* lds, const Gemm g, const StaticOrder& S, const Epi& E) {
;     ...
;             PG8_WAIT_V(8); PG8_WAIT_L(0); PG8_BAR; PG8_MMA(1, 0, At, B0); PG8_MMA(1, 1, At, B1); PG8_BAR; PG8_SCHED;
;             PG8_LDB(B0, 1, 0); PG8_LDB(B1, 1, 1); PG8_SCHED; PG8_LDA(At, 1, 0); PG8_STAGE(PG8_SA(0, 1), a2 + hstepA, voffA);
;             PG8_WAIT_V(8); PG8_WAIT_L(0); PG8_BAR; PG8_MMA(0, 0, At, B0); PG8_MMA(0, 1, At, B1); PG8_BAR; PG8_SCHED;
	v_mfma_f32_16x16x32_bf16 v[62:65], v[160:163], v[196:199], 0
	v_mfma_f32_16x16x32_bf16 v[58:61], v[168:171], v[196:199], 0
	v_mfma_f32_16x16x32_bf16 v[54:57], v[160:163], v[204:207], 0
	v_mfma_f32_16x16x32_bf16 v[46:49], v[168:171], v[204:207], 0
	v_mfma_f32_16x16x32_bf16 v[38:41], v[160:163], v[212:215], 0
	v_mfma_f32_16x16x32_bf16 v[30:33], v[168:171], v[212:215], 0
	v_mfma_f32_16x16x32_bf16 v[22:25], v[160:163], v[220:223], 0
	v_mfma_f32_16x16x32_bf16 v[14:17], v[168:171], v[220:223], 0
	v_mfma_f32_16x16x32_bf16 v[62:65], v[164:167], v[200:203], v[62:65]
	v_mfma_f32_16x16x32_bf16 v[58:61], v[174:177], v[200:203], v[58:61]
	v_mfma_f32_16x16x32_bf16 v[54:57], v[164:167], v[208:211], v[54:57]
	v_mfma_f32_16x16x32_bf16 v[46:49], v[174:177], v[208:211], v[46:49]
	v_mfma_f32_16x16x32_bf16 v[38:41], v[164:167], v[216:219], v[38:41]
	v_mfma_f32_16x16x32_bf16 v[30:33], v[174:177], v[216:219], v[30:33]
	v_mfma_f32_16x16x32_bf16 v[22:25], v[164:167], v[224:227], v[22:25]
	v_mfma_f32_16x16x32_bf16 v[14:17], v[174:177], v[224:227], v[14:17]
	v_mfma_f32_16x16x32_bf16 v[50:53], v[178:181], v[196:199], 0
	v_mfma_f32_16x16x32_bf16 v[42:45], v[188:191], v[196:199], 0
	v_mfma_f32_16x16x32_bf16 v[34:37], v[178:181], v[204:207], 0
	v_mfma_f32_16x16x32_bf16 v[26:29], v[188:191], v[204:207], 0
	v_mfma_f32_16x16x32_bf16 v[18:21], v[178:181], v[212:215], 0
	v_mfma_f32_16x16x32_bf16 v[10:13], v[188:191], v[212:215], 0
	v_mfma_f32_16x16x32_bf16 v[6:9], v[178:181], v[220:223], 0
	v_mfma_f32_16x16x32_bf16 v[2:5], v[188:191], v[220:223], 0
	v_mfma_f32_16x16x32_bf16 v[50:53], v[184:187], v[200:203], v[50:53]
	v_mfma_f32_16x16x32_bf16 v[42:45], v[192:195], v[200:203], v[42:45]
	v_mfma_f32_16x16x32_bf16 v[34:37], v[184:187], v[208:211], v[34:37]
	v_mfma_f32_16x16x32_bf16 v[26:29], v[192:195], v[208:211], v[26:29]
	v_mfma_f32_16x16x32_bf16 v[18:21], v[184:187], v[216:219], v[18:21]
	v_mfma_f32_16x16x32_bf16 v[10:13], v[192:195], v[216:219], v[10:13]
	v_mfma_f32_16x16x32_bf16 v[6:9], v[184:187], v[224:227], v[6:9]
	v_mfma_f32_16x16x32_bf16 v[2:5], v[192:195], v[224:227], v[2:5]
	s_barrier
	s_setprio 0
	s_add_i32 s39, 0, 0x18000
	s_add_i32 s40, 0, 0x1c000
	v_add_u32_e32 v174, s39, v139
	v_add_u32_e32 v192, s40, v139
	ds_read_b128 v[160:163], v174
	ds_read_b128 v[164:167], v174 offset:1024
	ds_read_b128 v[168:171], v174 offset:2048
	ds_read_b128 v[174:177], v174 offset:3072
	ds_read_b128 v[178:181], v192
	ds_read_b128 v[184:187], v192 offset:1024
	ds_read_b128 v[188:191], v192 offset:2048
	ds_read_b128 v[192:195], v192 offset:3072
	s_add_u32 s12, s18, 0x44000
	s_addc_u32 s13, s19, 0
	s_mov_b32 m0, s25
	v_lshl_add_u64 v[236:237], s[12:13], 0, v[152:153]
	ds_read_b128 v[196:199], v173 offset:32768
	ds_read_b128 v[200:203], v173 offset:33792
	ds_read_b128 v[204:207], v173 offset:34816
	ds_read_b128 v[208:211], v173 offset:35840
	ds_read_b128 v[212:215], v173 offset:36864
	ds_read_b128 v[216:219], v173 offset:37888
	ds_read_b128 v[220:223], v173 offset:38912
	ds_read_b128 v[224:227], v173 offset:39936
	global_load_lds_dwordx4 v[236:237], off
	s_mov_b32 m0, s26
	v_lshl_add_u64 v[236:237], s[12:13], 0, v[132:133]
	global_load_lds_dwordx4 v[236:237], off
	s_setprio 1
	s_waitcnt vmcnt(8) lgkmcnt(0)
	s_barrier
	v_mfma_f32_16x16x32_bf16 v[126:129], v[160:163], v[196:199], v[126:129]
	v_mfma_f32_16x16x32_bf16 v[122:125], v[168:171], v[196:199], v[122:125]
	v_mfma_f32_16x16x32_bf16 v[118:121], v[160:163], v[204:207], v[118:121]
	v_mfma_f32_16x16x32_bf16 v[110:113], v[168:171], v[204:207], v[110:113]
	v_mfma_f32_16x16x32_bf16 v[102:105], v[160:163], v[212:215], v[102:105]
	v_mfma_f32_16x16x32_bf16 v[94:97], v[168:171], v[212:215], v[94:97]
	v_mfma_f32_16x16x32_bf16 v[86:89], v[160:163], v[220:223], v[86:89]
	v_mfma_f32_16x16x32_bf16 v[78:81], v[168:171], v[220:223], v[78:81]
	v_mfma_f32_16x16x32_bf16 v[126:129], v[164:167], v[200:203], v[126:129]
	v_mfma_f32_16x16x32_bf16 v[122:125], v[174:177], v[200:203], v[122:125]
	v_mfma_f32_16x16x32_bf16 v[118:121], v[164:167], v[208:211], v[118:121]
	v_mfma_f32_16x16x32_bf16 v[110:113], v[174:177], v[208:211], v[110:113]
	v_mfma_f32_16x16x32_bf16 v[102:105], v[164:167], v[216:219], v[102:105]
	v_mfma_f32_16x16x32_bf16 v[94:97], v[174:177], v[216:219], v[94:97]
	v_mfma_f32_16x16x32_bf16 v[86:89], v[164:167], v[224:227], v[86:89]
	v_mfma_f32_16x16x32_bf16 v[78:81], v[174:177], v[224:227], v[78:81]
	v_mfma_f32_16x16x32_bf16 v[114:117], v[178:181], v[196:199], v[114:117]
	v_mfma_f32_16x16x32_bf16 v[106:109], v[188:191], v[196:199], v[106:109]
	v_mfma_f32_16x16x32_bf16 v[98:101], v[178:181], v[204:207], v[98:101]
	v_mfma_f32_16x16x32_bf16 v[90:93], v[188:191], v[204:207], v[90:93]
	v_mfma_f32_16x16x32_bf16 v[82:85], v[178:181], v[212:215], v[82:85]
	v_mfma_f32_16x16x32_bf16 v[74:77], v[188:191], v[212:215], v[74:77]
	v_mfma_f32_16x16x32_bf16 v[70:73], v[178:181], v[220:223], v[70:73]
	v_mfma_f32_16x16x32_bf16 v[66:69], v[188:191], v[220:223], v[66:69]
	v_mfma_f32_16x16x32_bf16 v[114:117], v[184:187], v[200:203], v[114:117]
	v_mfma_f32_16x16x32_bf16 v[106:109], v[192:195], v[200:203], v[106:109]
	v_mfma_f32_16x16x32_bf16 v[98:101], v[184:187], v[208:211], v[98:101]
	v_mfma_f32_16x16x32_bf16 v[90:93], v[192:195], v[208:211], v[90:93]
	v_mfma_f32_16x16x32_bf16 v[82:85], v[184:187], v[216:219], v[82:85]
	v_mfma_f32_16x16x32_bf16 v[74:77], v[192:195], v[216:219], v[74:77]
	v_mfma_f32_16x16x32_bf16 v[70:73], v[184:187], v[224:227], v[70:73]
	v_mfma_f32_16x16x32_bf16 v[66:69], v[192:195], v[224:227], v[66:69]
	s_barrier
; #define PG8_STAGE(bufoff, gbase, voff) do { _Pragma("unroll") for (int _i = 0; _i < 2; ++_i) \
;         __builtin_amdgcn_global_load_lds((const unsigned*)((const char*)(gbase) + (voff)[_i]), (LAS unsigned*)(lds + (bufoff) + ldsw + _i * 8192), 16, 0, 0); } while (0)
; #define PG8_LDA(dst, b, h) do { _Pragma("unroll") for (int m = 0; m < 4; ++m) _Pragma("unroll") for (int k = 0; k < 2; ++k) dst[m][k] = *(const LAS bf16x8*)(lds + PG8_SA(b, h) + aoff + m * 2048 + k * 1024); } while (0)
; #define PG8_LDB(dst, b, h) do { _Pragma("unroll") for (int n = 0; n < 2; ++n) _Pragma("unroll") for (int k = 0; k < 2; ++k) dst[n][k] = *(const LAS bf16x8*)(lds + PG8_SB(b, h) + boff + n * 2048 + k * 1024); } while (0)
; #define PG8_MMA(ai, bj, At, Bt) do { __builtin_amdgcn_s_setprio(1); _Pragma("unroll") for (int m = 0; m < 4; ++m) _Pragma("unroll") for (int n = 0; n < 2; ++n) _Pragma("unroll") for (int k = 0; k < 2; ++k) \
;         acc[ai][bj][m][n] = __builtin_amdgcn_mfma_f32_16x16x32_bf16(Bt[n][k], At[m][k], acc[ai][bj][m][n], 0, 0, 0); __builtin_amdgcn_s_setprio(0); } while (0)
; #define PG8_WAIT_V(n) asm volatile("s_waitcnt vmcnt(" #n ")" ::: "memory")
; #define PG8_WAIT_L(n) asm volatile("s_waitcnt lgkmcnt(" #n ")" ::: "memory")
; #define PG8_BAR __builtin_amdgcn_s_barrier()
; #define PG8_SCHED __builtin_amdgcn_sched_barrier(0)
; template <class Epi, bool ALIGN_EPI = PG8_ALIGN, bool SP2 = PG8_SP2>
; __device__ __forceinline__ void gemm_phase(LAS uchar* lds, const Gemm g, const StaticOrder& S, const Epi& E) {
;     ...
;         for (int t = tb; t < tb + tblk; t += 2) {
;             const bool last = (t == nt - 2);
;             const char* a1 = cA + (size_t)(t + 1) * kstep;
;             const char* a2 = last ? nA : cA + (size_t)(t + 2) * kstep; const char* b2 = last ? nB : cB + (size_t)(t + 2) * kstep;
;             const char* a3 = a2 + kstep; const char* b3 = b2 + kstep;
;             if constexpr (SP2) {
;             PG8_LDB(B0, 0, 0); PG8_LDB(B1, 0, 1); PG8_SCHED; PG8_LDA(At, 0, 0); PG8_STAGE(PG8_SA(1, 1), a1 + hstepA, voffA);
;     ...
;             PG8_LDA(At, 1, 1); PG8_STAGE(PG8_SB(1, 0), b3, voffB); PG8_STAGE(PG8_SB(1, 1), b3 + hstepB, voffB); PG8_STAGE(PG8_SA(1, 0), a3, voffA);
;             PG8_WAIT_V(8); PG8_WAIT_L(0); PG8_BAR; PG8_MMA(1, 0, At, B0); PG8_MMA(1, 1, At, B1); PG8_BAR; PG8_SCHED;
	s_setprio 0
	s_add_i32 s12, s39, s21
	v_lshl_add_u64 v[228:229], v[228:229], 0, s[84:85]
	s_mov_b32 m0, s12
	ds_read_b128 v[196:199], v173 offset:49152
	ds_read_b128 v[200:203], v173 offset:50176
	ds_read_b128 v[204:207], v173 offset:51200
	ds_read_b128 v[208:211], v173 offset:52224
	ds_read_b128 v[212:215], v173 offset:53248
	ds_read_b128 v[216:219], v173 offset:54272
	ds_read_b128 v[220:223], v173 offset:55296
	ds_read_b128 v[224:227], v173 offset:56320
	global_load_lds_dwordx4 v[228:229], off
	s_add_i32 m0, s12, 0x2000
	s_add_u32 s12, s16, 0x44080
	v_lshl_add_u64 v[228:229], v[230:231], 0, s[84:85]
	s_addc_u32 s13, s17, 0
	s_add_i32 s16, s40, s21
	global_load_lds_dwordx4 v[228:229], off
	s_mov_b32 m0, s16
	v_lshl_add_u64 v[228:229], s[12:13], 0, v[134:135]
	global_load_lds_dwordx4 v[228:229], off
	s_add_i32 m0, s16, 0x2000
	v_lshl_add_u64 v[228:229], s[12:13], 0, v[130:131]
	global_load_lds_dwordx4 v[228:229], off
	s_mov_b32 m0, s27
	v_lshl_add_u64 v[228:229], v[232:233], 0, s[84:85]
	global_load_lds_dwordx4 v[228:229], off
	s_mov_b32 m0, s28
	v_lshl_add_u64 v[228:229], v[234:235], 0, s[84:85]
	global_load_lds_dwordx4 v[228:229], off
	s_setprio 1
	s_waitcnt vmcnt(8) lgkmcnt(0)
	s_barrier
	v_mfma_f32_16x16x32_bf16 v[62:65], v[160:163], v[196:199], v[62:65]
	v_mfma_f32_16x16x32_bf16 v[58:61], v[168:171], v[196:199], v[58:61]
	v_mfma_f32_16x16x32_bf16 v[54:57], v[160:163], v[204:207], v[54:57]
	v_mfma_f32_16x16x32_bf16 v[46:49], v[168:171], v[204:207], v[46:49]
	v_mfma_f32_16x16x32_bf16 v[38:41], v[160:163], v[212:215], v[38:41]
	v_mfma_f32_16x16x32_bf16 v[30:33], v[168:171], v[212:215], v[30:33]
	v_mfma_f32_16x16x32_bf16 v[22:25], v[160:163], v[220:223], v[22:25]
	v_mfma_f32_16x16x32_bf16 v[14:17], v[168:171], v[220:223], v[14:17]
	v_mfma_f32_16x16x32_bf16 v[62:65], v[164:167], v[200:203], v[62:65]
	v_mfma_f32_16x16x32_bf16 v[58:61], v[174:177], v[200:203], v[58:61]
	v_mfma_f32_16x16x32_bf16 v[54:57], v[164:167], v[208:211], v[54:57]
	v_mfma_f32_16x16x32_bf16 v[46:49], v[174:177], v[208:211], v[46:49]
	v_mfma_f32_16x16x32_bf16 v[38:41], v[164:167], v[216:219], v[38:41]
	v_mfma_f32_16x16x32_bf16 v[30:33], v[174:177], v[216:219], v[30:33]
	v_mfma_f32_16x16x32_bf16 v[22:25], v[164:167], v[224:227], v[22:25]
	v_mfma_f32_16x16x32_bf16 v[14:17], v[174:177], v[224:227], v[14:17]
	v_mfma_f32_16x16x32_bf16 v[50:53], v[178:181], v[196:199], v[50:53]
	v_mfma_f32_16x16x32_bf16 v[42:45], v[188:191], v[196:199], v[42:45]
	v_mfma_f32_16x16x32_bf16 v[34:37], v[178:181], v[204:207], v[34:37]
	v_mfma_f32_16x16x32_bf16 v[26:29], v[188:191], v[204:207], v[26:29]
	v_mfma_f32_16x16x32_bf16 v[18:21], v[178:181], v[212:215], v[18:21]
	v_mfma_f32_16x16x32_bf16 v[10:13], v[188:191], v[212:215], v[10:13]
	v_mfma_f32_16x16x32_bf16 v[6:9], v[178:181], v[220:223], v[6:9]
	v_mfma_f32_16x16x32_bf16 v[2:5], v[188:191], v[220:223], v[2:5]
	v_mfma_f32_16x16x32_bf16 v[50:53], v[184:187], v[200:203], v[50:53]
	v_mfma_f32_16x16x32_bf16 v[42:45], v[192:195], v[200:203], v[42:45]
	v_mfma_f32_16x16x32_bf16 v[34:37], v[184:187], v[208:211], v[34:37]
	v_mfma_f32_16x16x32_bf16 v[26:29], v[192:195], v[208:211], v[26:29]
	v_mfma_f32_16x16x32_bf16 v[18:21], v[184:187], v[216:219], v[18:21]
	v_mfma_f32_16x16x32_bf16 v[10:13], v[192:195], v[216:219], v[10:13]
	v_mfma_f32_16x16x32_bf16 v[6:9], v[184:187], v[224:227], v[6:9]
	v_mfma_f32_16x16x32_bf16 v[2:5], v[192:195], v[224:227], v[2:5]
	s_barrier
	s_setprio 0
	s_add_i32 s38, s38, 2
	s_add_u32 s36, s36, 0x100
	s_addc_u32 s37, s37, 0
	s_cmp_gt_u32 s38, 13
	s_mov_b64 s[12:13], s[14:15]
.LBB0_669:
	s_add_u32 s14, s12, 0x100
	s_addc_u32 s15, s13, 0
	s_add_i32 s39, 0, 0x10000
	s_cmp_eq_u32 s38, 12
	s_cselect_b32 s19, s5, s15
	s_cselect_b32 s18, s4, s14
	s_cselect_b32 s17, s11, s37
	s_cselect_b32 s16, s10, s36
	s_add_i32 s40, 0, 0x14000
	v_add_u32_e32 v174, s39, v139
	v_add_u32_e32 v192, s40, v139
	ds_read_b128 v[160:163], v174
	ds_read_b128 v[164:167], v174 offset:1024
	ds_read_b128 v[168:171], v174 offset:2048
	ds_read_b128 v[174:177], v174 offset:3072
	ds_read_b128 v[178:181], v192
	ds_read_b128 v[184:187], v192 offset:1024
	ds_read_b128 v[188:191], v192 offset:2048
	ds_read_b128 v[192:195], v192 offset:3072
	v_lshl_add_u64 v[228:229], s[12:13], 0, v[156:157]
	s_add_i32 m0, s23, 0xc000
	ds_read_b128 v[196:199], v173
	ds_read_b128 v[200:203], v173 offset:1024
	ds_read_b128 v[204:207], v173 offset:2048
	ds_read_b128 v[208:211], v173 offset:3072
	ds_read_b128 v[212:215], v173 offset:4096
	ds_read_b128 v[216:219], v173 offset:5120
	ds_read_b128 v[220:223], v173 offset:6144
	ds_read_b128 v[224:227], v173 offset:7168
	global_load_lds_dwordx4 v[228:229], off
	s_add_i32 m0, s23, 0xe000
	v_lshl_add_u64 v[228:229], s[12:13], 0, v[158:159]
	global_load_lds_dwordx4 v[228:229], off
	s_setprio 1
	s_waitcnt vmcnt(8) lgkmcnt(0)
	s_barrier
; #define PG8_STAGE(bufoff, gbase, voff) do { _Pragma("unroll") for (int _i = 0; _i < 2; ++_i) \
;         __builtin_amdgcn_global_load_lds((const unsigned*)((const char*)(gbase) + (voff)[_i]), (LAS unsigned*)(lds + (bufoff) + ldsw + _i * 8192), 16, 0, 0); } while (0)
; #define PG8_LDA(dst, b, h) do { _Pragma("unroll") for (int m = 0; m < 4; ++m) _Pragma("unroll") for (int k = 0; k < 2; ++k) dst[m][k] = *(const LAS bf16x8*)(lds + PG8_SA(b, h) + aoff + m * 2048 + k * 1024); } while (0)
; #define PG8_LDB(dst, b, h) do { _Pragma("unroll") for (int n = 0; n < 2; ++n) _Pragma("unroll") for (int k = 0; k < 2; ++k) dst[n][k] = *(const LAS bf16x8*)(lds + PG8_SB(b, h) + boff + n * 2048 + k * 1024); } while (0)
; #define PG8_MMA(ai, bj, At, Bt) do { __builtin_amdgcn_s_setprio(1); _Pragma("unroll") for (int m = 0; m < 4; ++m) _Pragma("unroll") for (int n = 0; n < 2; ++n) _Pragma("unroll") for (int k = 0; k < 2; ++k) \
;         acc[ai][bj][m][n] = __builtin_amdgcn_mfma_f32_16x16x32_bf16(Bt[n][k], At[m][k], acc[ai][bj][m][n], 0, 0, 0); __builtin_amdgcn_s_setprio(0); } while (0)
; #define PG8_WAIT_V(n) asm volatile("s_waitcnt vmcnt(" #n ")" ::: "memory")
; #define PG8_WAIT_L(n) asm volatile("s_waitcnt lgkmcnt(" #n ")" ::: "memory")
; #define PG8_BAR __builtin_amdgcn_s_barrier()
; #define PG8_SCHED __builtin_amdgcn_sched_barrier(0)
; template <class Epi, bool ALIGN_EPI = PG8_ALIGN, bool SP2 = PG8_SP2>
; __device__ __forceinline__ void gemm_phase(LAS uchar* lds, const Gemm g, const StaticOrder& S, const Epi& E) {
;     ...
;             PG8_LDB(B0, 0, 0); PG8_LDB(B1, 0, 1); PG8_SCHED; PG8_LDA(At, 0, 0); PG8_STAGE(PG8_SA(1, 1), a1 + hstepA, voffA);
;             PG8_WAIT_V(8); PG8_WAIT_L(0); PG8_BAR; PG8_MMA(0, 0, At, B0); PG8_MMA(0, 1, At, B1); PG8_BAR; PG8_SCHED;
;             PG8_LDA(At, 0, 1); PG8_STAGE(PG8_SB(0, 0), b2, voffB); PG8_STAGE(PG8_SB(0, 1), b2 + hstepB, voffB); PG8_STAGE(PG8_SA(0, 0), a2, voffA);
;             PG8_WAIT_V(8); PG8_WAIT_L(0); PG8_BAR; PG8_MMA(1, 0, At, B0); PG8_MMA(1, 1, At, B1); PG8_BAR; PG8_SCHED;
	v_mfma_f32_16x16x32_bf16 v[126:129], v[160:163], v[196:199], v[126:129]
	v_mfma_f32_16x16x32_bf16 v[122:125], v[168:171], v[196:199], v[122:125]
	v_mfma_f32_16x16x32_bf16 v[118:121], v[160:163], v[204:207], v[118:121]
	v_mfma_f32_16x16x32_bf16 v[110:113], v[168:171], v[204:207], v[110:113]
	v_mfma_f32_16x16x32_bf16 v[102:105], v[160:163], v[212:215], v[102:105]
	v_mfma_f32_16x16x32_bf16 v[94:97], v[168:171], v[212:215], v[94:97]
	v_mfma_f32_16x16x32_bf16 v[86:89], v[160:163], v[220:223], v[86:89]
	v_mfma_f32_16x16x32_bf16 v[78:81], v[168:171], v[220:223], v[78:81]
	v_mfma_f32_16x16x32_bf16 v[126:129], v[164:167], v[200:203], v[126:129]
	v_mfma_f32_16x16x32_bf16 v[122:125], v[174:177], v[200:203], v[122:125]
	v_mfma_f32_16x16x32_bf16 v[118:121], v[164:167], v[208:211], v[118:121]
	v_mfma_f32_16x16x32_bf16 v[110:113], v[174:177], v[208:211], v[110:113]
	v_mfma_f32_16x16x32_bf16 v[102:105], v[164:167], v[216:219], v[102:105]
	v_mfma_f32_16x16x32_bf16 v[94:97], v[174:177], v[216:219], v[94:97]
	v_mfma_f32_16x16x32_bf16 v[86:89], v[164:167], v[224:227], v[86:89]
	v_mfma_f32_16x16x32_bf16 v[78:81], v[174:177], v[224:227], v[78:81]
	v_mfma_f32_16x16x32_bf16 v[114:117], v[178:181], v[196:199], v[114:117]
	v_mfma_f32_16x16x32_bf16 v[106:109], v[188:191], v[196:199], v[106:109]
	v_mfma_f32_16x16x32_bf16 v[98:101], v[178:181], v[204:207], v[98:101]
	v_mfma_f32_16x16x32_bf16 v[90:93], v[188:191], v[204:207], v[90:93]
	v_mfma_f32_16x16x32_bf16 v[82:85], v[178:181], v[212:215], v[82:85]
	v_mfma_f32_16x16x32_bf16 v[74:77], v[188:191], v[212:215], v[74:77]
	v_mfma_f32_16x16x32_bf16 v[70:73], v[178:181], v[220:223], v[70:73]
	v_mfma_f32_16x16x32_bf16 v[66:69], v[188:191], v[220:223], v[66:69]
	v_mfma_f32_16x16x32_bf16 v[114:117], v[184:187], v[200:203], v[114:117]
	v_mfma_f32_16x16x32_bf16 v[106:109], v[192:195], v[200:203], v[106:109]
	v_mfma_f32_16x16x32_bf16 v[98:101], v[184:187], v[208:211], v[98:101]
	v_mfma_f32_16x16x32_bf16 v[90:93], v[192:195], v[208:211], v[90:93]
	v_mfma_f32_16x16x32_bf16 v[82:85], v[184:187], v[216:219], v[82:85]
	v_mfma_f32_16x16x32_bf16 v[74:77], v[192:195], v[216:219], v[74:77]
	v_mfma_f32_16x16x32_bf16 v[70:73], v[184:187], v[224:227], v[70:73]
	v_mfma_f32_16x16x32_bf16 v[66:69], v[192:195], v[224:227], v[66:69]
	s_barrier
	s_setprio 0
	s_add_i32 s12, s39, s21
	v_lshl_add_u64 v[228:229], s[16:17], 0, v[134:135]
	s_mov_b32 m0, s12
	ds_read_b128 v[196:199], v173 offset:16384
	ds_read_b128 v[200:203], v173 offset:17408
	ds_read_b128 v[204:207], v173 offset:18432
	ds_read_b128 v[208:211], v173 offset:19456
	ds_read_b128 v[212:215], v173 offset:20480
	ds_read_b128 v[216:219], v173 offset:21504
	ds_read_b128 v[220:223], v173 offset:22528
	ds_read_b128 v[224:227], v173 offset:23552
	global_load_lds_dwordx4 v[228:229], off
	s_add_i32 m0, s12, 0x2000
	s_add_u32 s12, s16, 0x44000
	v_lshl_add_u64 v[230:231], s[16:17], 0, v[130:131]
	s_addc_u32 s13, s17, 0
	s_add_i32 s39, s40, s21
	global_load_lds_dwordx4 v[230:231], off
	v_lshl_add_u64 v[232:233], s[12:13], 0, v[134:135]
	s_mov_b32 m0, s39
	global_load_lds_dwordx4 v[232:233], off
	s_add_i32 m0, s39, 0x2000
	v_lshl_add_u64 v[232:233], s[12:13], 0, v[130:131]
	global_load_lds_dwordx4 v[232:233], off
	s_mov_b32 m0, s23
	v_lshl_add_u64 v[232:233], s[18:19], 0, v[152:153]
	global_load_lds_dwordx4 v[232:233], off
	s_mov_b32 m0, s24
	v_lshl_add_u64 v[234:235], s[18:19], 0, v[132:133]
	global_load_lds_dwordx4 v[234:235], off
	s_setprio 1
	s_waitcnt vmcnt(8) lgkmcnt(0)
	s_barrier
	v_mfma_f32_16x16x32_bf16 v[62:65], v[160:163], v[196:199], v[62:65]
	v_mfma_f32_16x16x32_bf16 v[58:61], v[168:171], v[196:199], v[58:61]
	v_mfma_f32_16x16x32_bf16 v[54:57], v[160:163], v[204:207], v[54:57]
	v_mfma_f32_16x16x32_bf16 v[46:49], v[168:171], v[204:207], v[46:49]
	v_mfma_f32_16x16x32_bf16 v[38:41], v[160:163], v[212:215], v[38:41]
	v_mfma_f32_16x16x32_bf16 v[30:33], v[168:171], v[212:215], v[30:33]
	v_mfma_f32_16x16x32_bf16 v[22:25], v[160:163], v[220:223], v[22:25]
	v_mfma_f32_16x16x32_bf16 v[14:17], v[168:171], v[220:223], v[14:17]
	v_mfma_f32_16x16x32_bf16 v[62:65], v[164:167], v[200:203], v[62:65]
	v_mfma_f32_16x16x32_bf16 v[58:61], v[174:177], v[200:203], v[58:61]
	v_mfma_f32_16x16x32_bf16 v[54:57], v[164:167], v[208:211], v[54:57]
	v_mfma_f32_16x16x32_bf16 v[46:49], v[174:177], v[208:211], v[46:49]
	v_mfma_f32_16x16x32_bf16 v[38:41], v[164:167], v[216:219], v[38:41]
	v_mfma_f32_16x16x32_bf16 v[30:33], v[174:177], v[216:219], v[30:33]
	v_mfma_f32_16x16x32_bf16 v[22:25], v[164:167], v[224:227], v[22:25]
	v_mfma_f32_16x16x32_bf16 v[14:17], v[174:177], v[224:227], v[14:17]
	v_mfma_f32_16x16x32_bf16 v[50:53], v[178:181], v[196:199], v[50:53]
	v_mfma_f32_16x16x32_bf16 v[42:45], v[188:191], v[196:199], v[42:45]
	v_mfma_f32_16x16x32_bf16 v[34:37], v[178:181], v[204:207], v[34:37]
	v_mfma_f32_16x16x32_bf16 v[26:29], v[188:191], v[204:207], v[26:29]
	v_mfma_f32_16x16x32_bf16 v[18:21], v[178:181], v[212:215], v[18:21]
	v_mfma_f32_16x16x32_bf16 v[10:13], v[188:191], v[212:215], v[10:13]
	v_mfma_f32_16x16x32_bf16 v[6:9], v[178:181], v[220:223], v[6:9]
	v_mfma_f32_16x16x32_bf16 v[2:5], v[188:191], v[220:223], v[2:5]
	v_mfma_f32_16x16x32_bf16 v[50:53], v[184:187], v[200:203], v[50:53]
	v_mfma_f32_16x16x32_bf16 v[42:45], v[192:195], v[200:203], v[42:45]
	v_mfma_f32_16x16x32_bf16 v[34:37], v[184:187], v[208:211], v[34:37]
	v_mfma_f32_16x16x32_bf16 v[26:29], v[192:195], v[208:211], v[26:29]
	v_mfma_f32_16x16x32_bf16 v[18:21], v[184:187], v[216:219], v[18:21]
	v_mfma_f32_16x16x32_bf16 v[10:13], v[192:195], v[216:219], v[10:13]
	v_mfma_f32_16x16x32_bf16 v[6:9], v[184:187], v[224:227], v[6:9]
	v_mfma_f32_16x16x32_bf16 v[2:5], v[192:195], v[224:227], v[2:5]
	s_barrier
; #define PG8_STAGE(bufoff, gbase, voff) do { _Pragma("unroll") for (int _i = 0; _i < 2; ++_i) \
;         __builtin_amdgcn_global_load_lds((const unsigned*)((const char*)(gbase) + (voff)[_i]), (LAS unsigned*)(lds + (bufoff) + ldsw + _i * 8192), 16, 0, 0); } while (0)
; #define PG8_LDA(dst, b, h) do { _Pragma("unroll") for (int m = 0; m < 4; ++m) _Pragma("unroll") for (int k = 0; k < 2; ++k) dst[m][k] = *(const LAS bf16x8*)(lds + PG8_SA(b, h) + aoff + m * 2048 + k * 1024); } while (0)
; #define PG8_LDB(dst, b, h) do { _Pragma("unroll") for (int n = 0; n < 2; ++n) _Pragma("unroll") for (int k = 0; k < 2; ++k) dst[n][k] = *(const LAS bf16x8*)(lds + PG8_SB(b, h) + boff + n * 2048 + k * 1024); } while (0)
; #define PG8_MMA(ai, bj, At, Bt) do { __builtin_amdgcn_s_setprio(1); _Pragma("unroll") for (int m = 0; m < 4; ++m) _Pragma("unroll") for (int n = 0; n < 2; ++n) _Pragma("unroll") for (int k = 0; k < 2; ++k) \
;         acc[ai][bj][m][n] = __builtin_amdgcn_mfma_f32_16x16x32_bf16(Bt[n][k], At[m][k], acc[ai][bj][m][n], 0, 0, 0); __builtin_amdgcn_s_setprio(0); } while (0)
; #define PG8_WAIT_V(n) asm volatile("s_waitcnt vmcnt(" #n ")" ::: "memory")
; #define PG8_WAIT_L(n) asm volatile("s_waitcnt lgkmcnt(" #n ")" ::: "memory")
; #define PG8_BAR __builtin_amdgcn_s_barrier()
; #define PG8_SCHED __builtin_amdgcn_sched_barrier(0)
; template <class Epi, bool ALIGN_EPI = PG8_ALIGN, bool SP2 = PG8_SP2>
; __device__ __forceinline__ void gemm_phase(LAS uchar* lds, const Gemm g, const StaticOrder& S, const Epi& E) {
;     ...
;             PG8_LDB(B0, 1, 0); PG8_LDB(B1, 1, 1); PG8_SCHED; PG8_LDA(At, 1, 0); PG8_STAGE(PG8_SA(0, 1), a2 + hstepA, voffA);
;             PG8_WAIT_V(8); PG8_WAIT_L(0); PG8_BAR; PG8_MMA(0, 0, At, B0); PG8_MMA(0, 1, At, B1); PG8_BAR; PG8_SCHED;
	s_setprio 0
	s_add_i32 s39, 0, 0x18000
	s_add_i32 s40, 0, 0x1c000
	v_add_u32_e32 v174, s39, v139
	v_add_u32_e32 v192, s40, v139
	ds_read_b128 v[160:163], v174
	ds_read_b128 v[164:167], v174 offset:1024
	ds_read_b128 v[168:171], v174 offset:2048
	ds_read_b128 v[174:177], v174 offset:3072
	ds_read_b128 v[178:181], v192
	ds_read_b128 v[184:187], v192 offset:1024
	ds_read_b128 v[188:191], v192 offset:2048
	ds_read_b128 v[192:195], v192 offset:3072
	s_add_u32 s12, s18, 0x44000
	s_addc_u32 s13, s19, 0
	s_mov_b32 m0, s25
	v_lshl_add_u64 v[236:237], s[12:13], 0, v[152:153]
	ds_read_b128 v[196:199], v173 offset:32768
	ds_read_b128 v[200:203], v173 offset:33792
	ds_read_b128 v[204:207], v173 offset:34816
	ds_read_b128 v[208:211], v173 offset:35840
	ds_read_b128 v[212:215], v173 offset:36864
	ds_read_b128 v[216:219], v173 offset:37888
	ds_read_b128 v[220:223], v173 offset:38912
	ds_read_b128 v[224:227], v173 offset:39936
	global_load_lds_dwordx4 v[236:237], off
	s_mov_b32 m0, s26
	v_lshl_add_u64 v[236:237], s[12:13], 0, v[132:133]
	global_load_lds_dwordx4 v[236:237], off
	s_setprio 1
	s_waitcnt vmcnt(8) lgkmcnt(0)
	s_barrier
	v_mfma_f32_16x16x32_bf16 v[126:129], v[160:163], v[196:199], v[126:129]
	v_mfma_f32_16x16x32_bf16 v[122:125], v[168:171], v[196:199], v[122:125]
	v_mfma_f32_16x16x32_bf16 v[118:121], v[160:163], v[204:207], v[118:121]
	v_mfma_f32_16x16x32_bf16 v[110:113], v[168:171], v[204:207], v[110:113]
	v_mfma_f32_16x16x32_bf16 v[102:105], v[160:163], v[212:215], v[102:105]
	v_mfma_f32_16x16x32_bf16 v[94:97], v[168:171], v[212:215], v[94:97]
	v_mfma_f32_16x16x32_bf16 v[86:89], v[160:163], v[220:223], v[86:89]
	v_mfma_f32_16x16x32_bf16 v[78:81], v[168:171], v[220:223], v[78:81]
	v_mfma_f32_16x16x32_bf16 v[126:129], v[164:167], v[200:203], v[126:129]
	v_mfma_f32_16x16x32_bf16 v[122:125], v[174:177], v[200:203], v[122:125]
	v_mfma_f32_16x16x32_bf16 v[118:121], v[164:167], v[208:211], v[118:121]
	v_mfma_f32_16x16x32_bf16 v[110:113], v[174:177], v[208:211], v[110:113]
	v_mfma_f32_16x16x32_bf16 v[102:105], v[164:167], v[216:219], v[102:105]
	v_mfma_f32_16x16x32_bf16 v[94:97], v[174:177], v[216:219], v[94:97]
	v_mfma_f32_16x16x32_bf16 v[86:89], v[164:167], v[224:227], v[86:89]
	v_mfma_f32_16x16x32_bf16 v[78:81], v[174:177], v[224:227], v[78:81]
	v_mfma_f32_16x16x32_bf16 v[114:117], v[178:181], v[196:199], v[114:117]
	v_mfma_f32_16x16x32_bf16 v[106:109], v[188:191], v[196:199], v[106:109]
	v_mfma_f32_16x16x32_bf16 v[98:101], v[178:181], v[204:207], v[98:101]
	v_mfma_f32_16x16x32_bf16 v[90:93], v[188:191], v[204:207], v[90:93]
	v_mfma_f32_16x16x32_bf16 v[82:85], v[178:181], v[212:215], v[82:85]
	v_mfma_f32_16x16x32_bf16 v[74:77], v[188:191], v[212:215], v[74:77]
	v_mfma_f32_16x16x32_bf16 v[70:73], v[178:181], v[220:223], v[70:73]
	v_mfma_f32_16x16x32_bf16 v[66:69], v[188:191], v[220:223], v[66:69]
	v_mfma_f32_16x16x32_bf16 v[114:117], v[184:187], v[200:203], v[114:117]
	v_mfma_f32_16x16x32_bf16 v[106:109], v[192:195], v[200:203], v[106:109]
	v_mfma_f32_16x16x32_bf16 v[98:101], v[184:187], v[208:211], v[98:101]
	v_mfma_f32_16x16x32_bf16 v[90:93], v[192:195], v[208:211], v[90:93]
	v_mfma_f32_16x16x32_bf16 v[82:85], v[184:187], v[216:219], v[82:85]
	v_mfma_f32_16x16x32_bf16 v[74:77], v[192:195], v[216:219], v[74:77]
	v_mfma_f32_16x16x32_bf16 v[70:73], v[184:187], v[224:227], v[70:73]
	v_mfma_f32_16x16x32_bf16 v[66:69], v[192:195], v[224:227], v[66:69]
	s_barrier
; #define PG8_STAGE(bufoff, gbase, voff) do { _Pragma("unroll") for (int _i = 0; _i < 2; ++_i) \
;         __builtin_amdgcn_global_load_lds((const unsigned*)((const char*)(gbase) + (voff)[_i]), (LAS unsigned*)(lds + (bufoff) + ldsw + _i * 8192), 16, 0, 0); } while (0)
; #define PG8_LDA(dst, b, h) do { _Pragma("unroll") for (int m = 0; m < 4; ++m) _Pragma("unroll") for (int k = 0; k < 2; ++k) dst[m][k] = *(const LAS bf16x8*)(lds + PG8_SA(b, h) + aoff + m * 2048 + k * 1024); } while (0)
; #define PG8_MMA(ai, bj, At, Bt) do { __builtin_amdgcn_s_setprio(1); _Pragma("unroll") for (int m = 0; m < 4; ++m) _Pragma("unroll") for (int n = 0; n < 2; ++n) _Pragma("unroll") for (int k = 0; k < 2; ++k) \
;         acc[ai][bj][m][n] = __builtin_amdgcn_mfma_f32_16x16x32_bf16(Bt[n][k], At[m][k], acc[ai][bj][m][n], 0, 0, 0); __builtin_amdgcn_s_setprio(0); } while (0)
; #define PG8_WAIT_V(n) asm volatile("s_waitcnt vmcnt(" #n ")" ::: "memory")
; #define PG8_WAIT_L(n) asm volatile("s_waitcnt lgkmcnt(" #n ")" ::: "memory")
; #define PG8_BAR __builtin_amdgcn_s_barrier()
; #define PG8_SCHED __builtin_amdgcn_sched_barrier(0)
; template <class Epi, bool ALIGN_EPI = PG8_ALIGN, bool SP2 = PG8_SP2>
; __device__ __forceinline__ void gemm_phase(LAS uchar* lds, const Gemm g, const StaticOrder& S, const Epi& E) {
;     ...
;         for (int t = tb; t < tb + tblk; t += 2) {
;             const bool last = (t == nt - 2);
;             const char* a1 = cA + (size_t)(t + 1) * kstep;
;             const char* a2 = last ? nA : cA + (size_t)(t + 2) * kstep; const char* b2 = last ? nB : cB + (size_t)(t + 2) * kstep;
;             const char* a3 = a2 + kstep; const char* b3 = b2 + kstep;
;     ...
;             PG8_LDA(At, 1, 1); PG8_STAGE(PG8_SB(1, 0), b3, voffB); PG8_STAGE(PG8_SB(1, 1), b3 + hstepB, voffB); PG8_STAGE(PG8_SA(1, 0), a3, voffA);
;             PG8_WAIT_V(8); PG8_WAIT_L(0); PG8_BAR; PG8_MMA(1, 0, At, B0); PG8_MMA(1, 1, At, B1); PG8_BAR; PG8_SCHED;
;     ...
;         if constexpr (ALIGN_EPI) { if (wr == 0) PG8_BAR; }
	s_setprio 0
	s_add_i32 s12, s39, s21
	v_lshl_add_u64 v[228:229], v[228:229], 0, s[84:85]
	s_mov_b32 m0, s12
	ds_read_b128 v[196:199], v173 offset:49152
	ds_read_b128 v[200:203], v173 offset:50176
	ds_read_b128 v[204:207], v173 offset:51200
	ds_read_b128 v[208:211], v173 offset:52224
	ds_read_b128 v[212:215], v173 offset:53248
	ds_read_b128 v[216:219], v173 offset:54272
	ds_read_b128 v[220:223], v173 offset:55296
	ds_read_b128 v[224:227], v173 offset:56320
	global_load_lds_dwordx4 v[228:229], off
	s_add_i32 m0, s12, 0x2000
	s_add_u32 s12, s16, 0x44080
	v_lshl_add_u64 v[228:229], v[230:231], 0, s[84:85]
	s_addc_u32 s13, s17, 0
	s_add_i32 s16, s40, s21
	global_load_lds_dwordx4 v[228:229], off
	s_mov_b32 m0, s16
	v_lshl_add_u64 v[228:229], s[12:13], 0, v[134:135]
	global_load_lds_dwordx4 v[228:229], off
	s_add_i32 m0, s16, 0x2000
	v_lshl_add_u64 v[228:229], s[12:13], 0, v[130:131]
	global_load_lds_dwordx4 v[228:229], off
	s_mov_b32 m0, s27
	v_lshl_add_u64 v[228:229], v[232:233], 0, s[84:85]
	global_load_lds_dwordx4 v[228:229], off
	s_mov_b32 m0, s28
	v_lshl_add_u64 v[228:229], v[234:235], 0, s[84:85]
	global_load_lds_dwordx4 v[228:229], off
	s_setprio 1
	s_waitcnt vmcnt(8) lgkmcnt(0)
	s_barrier
	v_mfma_f32_16x16x32_bf16 v[62:65], v[160:163], v[196:199], v[62:65]
	v_mfma_f32_16x16x32_bf16 v[58:61], v[168:171], v[196:199], v[58:61]
	v_mfma_f32_16x16x32_bf16 v[54:57], v[160:163], v[204:207], v[54:57]
	v_mfma_f32_16x16x32_bf16 v[46:49], v[168:171], v[204:207], v[46:49]
	v_mfma_f32_16x16x32_bf16 v[38:41], v[160:163], v[212:215], v[38:41]
	v_mfma_f32_16x16x32_bf16 v[30:33], v[168:171], v[212:215], v[30:33]
	v_mfma_f32_16x16x32_bf16 v[22:25], v[160:163], v[220:223], v[22:25]
	v_mfma_f32_16x16x32_bf16 v[14:17], v[168:171], v[220:223], v[14:17]
	v_mfma_f32_16x16x32_bf16 v[62:65], v[164:167], v[200:203], v[62:65]
	v_mfma_f32_16x16x32_bf16 v[58:61], v[174:177], v[200:203], v[58:61]
	v_mfma_f32_16x16x32_bf16 v[54:57], v[164:167], v[208:211], v[54:57]
	v_mfma_f32_16x16x32_bf16 v[46:49], v[174:177], v[208:211], v[46:49]
	v_mfma_f32_16x16x32_bf16 v[38:41], v[164:167], v[216:219], v[38:41]
	v_mfma_f32_16x16x32_bf16 v[30:33], v[174:177], v[216:219], v[30:33]
	v_mfma_f32_16x16x32_bf16 v[22:25], v[164:167], v[224:227], v[22:25]
	v_mfma_f32_16x16x32_bf16 v[14:17], v[174:177], v[224:227], v[14:17]
	v_mfma_f32_16x16x32_bf16 v[50:53], v[178:181], v[196:199], v[50:53]
	v_mfma_f32_16x16x32_bf16 v[42:45], v[188:191], v[196:199], v[42:45]
	v_mfma_f32_16x16x32_bf16 v[34:37], v[178:181], v[204:207], v[34:37]
	v_mfma_f32_16x16x32_bf16 v[26:29], v[188:191], v[204:207], v[26:29]
	v_mfma_f32_16x16x32_bf16 v[18:21], v[178:181], v[212:215], v[18:21]
	v_mfma_f32_16x16x32_bf16 v[10:13], v[188:191], v[212:215], v[10:13]
	v_mfma_f32_16x16x32_bf16 v[6:9], v[178:181], v[220:223], v[6:9]
	v_mfma_f32_16x16x32_bf16 v[2:5], v[188:191], v[220:223], v[2:5]
	v_mfma_f32_16x16x32_bf16 v[50:53], v[184:187], v[200:203], v[50:53]
	v_mfma_f32_16x16x32_bf16 v[42:45], v[192:195], v[200:203], v[42:45]
	v_mfma_f32_16x16x32_bf16 v[34:37], v[184:187], v[208:211], v[34:37]
	v_mfma_f32_16x16x32_bf16 v[26:29], v[192:195], v[208:211], v[26:29]
	v_mfma_f32_16x16x32_bf16 v[18:21], v[184:187], v[216:219], v[18:21]
	v_mfma_f32_16x16x32_bf16 v[10:13], v[192:195], v[216:219], v[10:13]
	v_mfma_f32_16x16x32_bf16 v[6:9], v[184:187], v[224:227], v[6:9]
	v_mfma_f32_16x16x32_bf16 v[2:5], v[192:195], v[224:227], v[2:5]
	s_barrier
	s_setprio 0
	s_add_i32 s38, s38, 2
	s_add_u32 s36, s36, 0x100
	s_addc_u32 s37, s37, 0
	s_cmp_gt_u32 s38, 13
	s_mov_b64 s[12:13], s[14:15]
	s_cbranch_scc0 .LBB0_669
	s_and_b64 vcc, exec, s[8:9]
	s_cbranch_vccz .LBB0_672
	s_barrier

; #define PG8_STAGE(bufoff, gbase, voff) do { _Pragma("unroll") for (int _i = 0; _i < 2; ++_i) \
;         __builtin_amdgcn_global_load_lds((const unsigned*)((const char*)(gbase) + (voff)[_i]), (LAS unsigned*)(lds + (bufoff) + ldsw + _i * 8192), 16, 0, 0); } while (0)
; #define PG8_LDA(dst, b, h) do { _Pragma("unroll") for (int m = 0; m < 4; ++m) _Pragma("unroll") for (int k = 0; k < 2; ++k) dst[m][k] = *(const LAS bf16x8*)(lds + PG8_SA(b, h) + aoff + m * 2048 + k * 1024); } while (0)
; #define PG8_LDB(dst, b, h) do { _Pragma("unroll") for (int n = 0; n < 2; ++n) _Pragma("unroll") for (int k = 0; k < 2; ++k) dst[n][k] = *(const LAS bf16x8*)(lds + PG8_SB(b, h) + boff + n * 2048 + k * 1024); } while (0)
; #define PG8_MMA(ai, bj, At, Bt) do { __builtin_amdgcn_s_setprio(1); _Pragma("unroll") for (int m = 0; m < 4; ++m) _Pragma("unroll") for (int n = 0; n < 2; ++n) _Pragma("unroll") for (int k = 0; k < 2; ++k) \
;         acc[ai][bj][m][n] = __builtin_amdgcn_mfma_f32_16x16x32_bf16(Bt[n][k], At[m][k], acc[ai][bj][m][n], 0, 0, 0); __builtin_amdgcn_s_setprio(0); } while (0)
; #define PG8_WAIT_V(n) asm volatile("s_waitcnt vmcnt(" #n ")" ::: "memory")
; #define PG8_WAIT_L(n) asm volatile("s_waitcnt lgkmcnt(" #n ")" ::: "memory")
; #define PG8_BAR __builtin_amdgcn_s_barrier()
; template <class Epi, bool ALIGN_EPI = PG8_ALIGN, bool SP2 = PG8_SP2>
; __device__ __forceinline__ void gemm_phase(LAS uchar* lds, const Gemm g, const StaticOrder& S, const Epi& E) {
;     ...
;         for (int t = tb; t < tb + tblk; t += 2) {
;             const bool last = (t == nt - 2);
;             const char* a1 = cA + (size_t)(t + 1) * kstep;
;             const char* a2 = last ? nA : cA + (size_t)(t + 2) * kstep; const char* b2 = last ? nB : cB + (size_t)(t + 2) * kstep;
;             const char* a3 = a2 + kstep; const char* b3 = b2 + kstep;
;             if constexpr (SP2) {
;             PG8_LDB(B0, 0, 0); PG8_LDB(B1, 0, 1); PG8_SCHED; PG8_LDA(At, 0, 0); PG8_STAGE(PG8_SA(1, 1), a1 + hstepA, voffA);
;             PG8_WAIT_V(8); PG8_WAIT_L(0); PG8_BAR; PG8_MMA(0, 0, At, B0); PG8_MMA(0, 1, At, B1); PG8_BAR; PG8_SCHED;
;             PG8_LDA(At, 0, 1); PG8_STAGE(PG8_SB(0, 0), b2, voffB); PG8_STAGE(PG8_SB(0, 1), b2 + hstepB, voffB); PG8_STAGE(PG8_SA(0, 0), a2, voffA);
;             PG8_WAIT_V(8); PG8_WAIT_L(0); PG8_BAR; PG8_MMA(1, 0, At, B0); PG8_MMA(1, 1, At, B1); PG8_BAR; PG8_SCHED;
.LBB0_836:
	s_add_u32 s36, s14, 0x100
	s_addc_u32 s37, s15, 0
	s_mov_b32 s38, -2
	s_add_u32 s14, s12, 0x100
	s_addc_u32 s15, s13, 0
	s_add_i32 s39, 0, 0x10000
	s_cmp_eq_u32 s38, 12
	s_cselect_b32 s19, s5, s15
	s_cselect_b32 s18, s4, s14
	s_cselect_b32 s17, s11, s37
	s_cselect_b32 s16, s10, s36
	s_add_i32 s40, 0, 0x14000
	v_add_u32_e32 v174, s39, v139
	v_add_u32_e32 v192, s40, v139
	ds_read_b128 v[160:163], v174
	ds_read_b128 v[166:169], v174 offset:1024
	ds_read_b128 v[170:173], v174 offset:2048
	ds_read_b128 v[174:177], v174 offset:3072
	ds_read_b128 v[178:181], v192
	ds_read_b128 v[184:187], v192 offset:1024
	ds_read_b128 v[188:191], v192 offset:2048
	ds_read_b128 v[192:195], v192 offset:3072
	v_lshl_add_u64 v[228:229], s[12:13], 0, v[156:157]
	s_add_i32 m0, s23, 0xc000
	ds_read_b128 v[196:199], v165
	ds_read_b128 v[200:203], v165 offset:1024
	ds_read_b128 v[204:207], v165 offset:2048
	ds_read_b128 v[208:211], v165 offset:3072
	ds_read_b128 v[212:215], v165 offset:4096
	ds_read_b128 v[216:219], v165 offset:5120
	ds_read_b128 v[220:223], v165 offset:6144
	ds_read_b128 v[224:227], v165 offset:7168
	global_load_lds_dwordx4 v[228:229], off
	s_add_i32 m0, s23, 0xe000
	v_lshl_add_u64 v[228:229], s[12:13], 0, v[158:159]
	global_load_lds_dwordx4 v[228:229], off
	s_setprio 1
	s_waitcnt vmcnt(8) lgkmcnt(0)
	s_barrier
	v_mfma_f32_16x16x32_bf16 v[126:129], v[160:163], v[196:199], 0
	v_mfma_f32_16x16x32_bf16 v[122:125], v[170:173], v[196:199], 0
	v_mfma_f32_16x16x32_bf16 v[118:121], v[160:163], v[204:207], 0
	v_mfma_f32_16x16x32_bf16 v[110:113], v[170:173], v[204:207], 0
	v_mfma_f32_16x16x32_bf16 v[102:105], v[160:163], v[212:215], 0
	v_mfma_f32_16x16x32_bf16 v[94:97], v[170:173], v[212:215], 0
	v_mfma_f32_16x16x32_bf16 v[86:89], v[160:163], v[220:223], 0
	v_mfma_f32_16x16x32_bf16 v[78:81], v[170:173], v[220:223], 0
	v_mfma_f32_16x16x32_bf16 v[126:129], v[166:169], v[200:203], v[126:129]
	v_mfma_f32_16x16x32_bf16 v[122:125], v[174:177], v[200:203], v[122:125]
	v_mfma_f32_16x16x32_bf16 v[118:121], v[166:169], v[208:211], v[118:121]
	v_mfma_f32_16x16x32_bf16 v[110:113], v[174:177], v[208:211], v[110:113]
	v_mfma_f32_16x16x32_bf16 v[102:105], v[166:169], v[216:219], v[102:105]
	v_mfma_f32_16x16x32_bf16 v[94:97], v[174:177], v[216:219], v[94:97]
	v_mfma_f32_16x16x32_bf16 v[86:89], v[166:169], v[224:227], v[86:89]
	v_mfma_f32_16x16x32_bf16 v[78:81], v[174:177], v[224:227], v[78:81]
	v_mfma_f32_16x16x32_bf16 v[114:117], v[178:181], v[196:199], 0
	v_mfma_f32_16x16x32_bf16 v[106:109], v[188:191], v[196:199], 0
	v_mfma_f32_16x16x32_bf16 v[98:101], v[178:181], v[204:207], 0
	v_mfma_f32_16x16x32_bf16 v[90:93], v[188:191], v[204:207], 0
	v_mfma_f32_16x16x32_bf16 v[82:85], v[178:181], v[212:215], 0
	v_mfma_f32_16x16x32_bf16 v[74:77], v[188:191], v[212:215], 0
	v_mfma_f32_16x16x32_bf16 v[70:73], v[178:181], v[220:223], 0
	v_mfma_f32_16x16x32_bf16 v[66:69], v[188:191], v[220:223], 0
	v_mfma_f32_16x16x32_bf16 v[114:117], v[184:187], v[200:203], v[114:117]
	v_mfma_f32_16x16x32_bf16 v[106:109], v[192:195], v[200:203], v[106:109]
	v_mfma_f32_16x16x32_bf16 v[98:101], v[184:187], v[208:211], v[98:101]
	v_mfma_f32_16x16x32_bf16 v[90:93], v[192:195], v[208:211], v[90:93]
	v_mfma_f32_16x16x32_bf16 v[82:85], v[184:187], v[216:219], v[82:85]
	v_mfma_f32_16x16x32_bf16 v[74:77], v[192:195], v[216:219], v[74:77]
	v_mfma_f32_16x16x32_bf16 v[70:73], v[184:187], v[224:227], v[70:73]
	v_mfma_f32_16x16x32_bf16 v[66:69], v[192:195], v[224:227], v[66:69]
	s_barrier
	s_setprio 0
	s_add_i32 s12, s39, s22
	v_lshl_add_u64 v[228:229], s[16:17], 0, v[132:133]
	s_mov_b32 m0, s12
	ds_read_b128 v[196:199], v165 offset:16384
	ds_read_b128 v[200:203], v165 offset:17408
	ds_read_b128 v[204:207], v165 offset:18432
	ds_read_b128 v[208:211], v165 offset:19456
	ds_read_b128 v[212:215], v165 offset:20480
	ds_read_b128 v[216:219], v165 offset:21504
	ds_read_b128 v[220:223], v165 offset:22528
	ds_read_b128 v[224:227], v165 offset:23552
	global_load_lds_dwordx4 v[228:229], off
	s_add_i32 m0, s12, 0x2000
	s_add_u32 s12, s16, 0x44000
	v_lshl_add_u64 v[230:231], s[16:17], 0, v[152:153]
	s_addc_u32 s13, s17, 0
	s_add_i32 s39, s40, s22
	global_load_lds_dwordx4 v[230:231], off
	v_lshl_add_u64 v[232:233], s[12:13], 0, v[132:133]
	s_mov_b32 m0, s39
	global_load_lds_dwordx4 v[232:233], off
	s_add_i32 m0, s39, 0x2000
	v_lshl_add_u64 v[232:233], s[12:13], 0, v[152:153]
	global_load_lds_dwordx4 v[232:233], off
	s_mov_b32 m0, s23
	v_lshl_add_u64 v[232:233], s[18:19], 0, v[130:131]
	global_load_lds_dwordx4 v[232:233], off
	s_mov_b32 m0, s24
	v_lshl_add_u64 v[234:235], s[18:19], 0, v[134:135]
	global_load_lds_dwordx4 v[234:235], off
	s_setprio 1
	s_waitcnt vmcnt(8) lgkmcnt(0)
	s_barrier
; #define PG8_STAGE(bufoff, gbase, voff) do { _Pragma("unroll") for (int _i = 0; _i < 2; ++_i) \
;         __builtin_amdgcn_global_load_lds((const unsigned*)((const char*)(gbase) + (voff)[_i]), (LAS unsigned*)(lds + (bufoff) + ldsw + _i * 8192), 16, 0, 0); } while (0)
; #define PG8_LDA(dst, b, h) do { _Pragma("unroll") for (int m = 0; m < 4; ++m) _Pragma("unroll") for (int k = 0; k < 2; ++k) dst[m][k] = *(const LAS bf16x8*)(lds + PG8_SA(b, h) + aoff + m * 2048 + k * 1024); } while (0)
; #define PG8_LDB(dst, b, h) do { _Pragma("unroll") for (int n = 0; n < 2; ++n) _Pragma("unroll") for (int k = 0; k < 2; ++k) dst[n][k] = *(const LAS bf16x8*)(lds + PG8_SB(b, h) + boff + n * 2048 + k * 1024); } while (0)
; #define PG8_MMA(ai, bj, At, Bt) do { __builtin_amdgcn_s_setprio(1); _Pragma("unroll") for (int m = 0; m < 4; ++m) _Pragma("unroll") for (int n = 0; n < 2; ++n) _Pragma("unroll") for (int k = 0; k < 2; ++k) \
;         acc[ai][bj][m][n] = __builtin_amdgcn_mfma_f32_16x16x32_bf16(Bt[n][k], At[m][k], acc[ai][bj][m][n], 0, 0, 0); __builtin_amdgcn_s_setprio(0); } while (0)
; #define PG8_WAIT_V(n) asm volatile("s_waitcnt vmcnt(" #n ")" ::: "memory")
; #define PG8_WAIT_L(n) asm volatile("s_waitcnt lgkmcnt(" #n ")" ::: "memory")
; #define PG8_BAR __builtin_amdgcn_s_barrier()
; #define PG8_SCHED __builtin_amdgcn_sched_barrier(0)
; template <class Epi, bool ALIGN_EPI = PG8_ALIGN, bool SP2 = PG8_SP2>
; __device__ __forceinline__ void gemm_phase(LAS uchar* lds, const Gemm g, const StaticOrder& S, const Epi& E) {
;     ...
;             PG8_WAIT_V(8); PG8_WAIT_L(0); PG8_BAR; PG8_MMA(1, 0, At, B0); PG8_MMA(1, 1, At, B1); PG8_BAR; PG8_SCHED;
;             PG8_LDB(B0, 1, 0); PG8_LDB(B1, 1, 1); PG8_SCHED; PG8_LDA(At, 1, 0); PG8_STAGE(PG8_SA(0, 1), a2 + hstepA, voffA);
;             PG8_WAIT_V(8); PG8_WAIT_L(0); PG8_BAR; PG8_MMA(0, 0, At, B0); PG8_MMA(0, 1, At, B1); PG8_BAR; PG8_SCHED;
	v_mfma_f32_16x16x32_bf16 v[62:65], v[160:163], v[196:199], 0
	v_mfma_f32_16x16x32_bf16 v[58:61], v[170:173], v[196:199], 0
	v_mfma_f32_16x16x32_bf16 v[54:57], v[160:163], v[204:207], 0
	v_mfma_f32_16x16x32_bf16 v[46:49], v[170:173], v[204:207], 0
	v_mfma_f32_16x16x32_bf16 v[38:41], v[160:163], v[212:215], 0
	v_mfma_f32_16x16x32_bf16 v[30:33], v[170:173], v[212:215], 0
	v_mfma_f32_16x16x32_bf16 v[22:25], v[160:163], v[220:223], 0
	v_mfma_f32_16x16x32_bf16 v[14:17], v[170:173], v[220:223], 0
	v_mfma_f32_16x16x32_bf16 v[62:65], v[166:169], v[200:203], v[62:65]
	v_mfma_f32_16x16x32_bf16 v[58:61], v[174:177], v[200:203], v[58:61]
	v_mfma_f32_16x16x32_bf16 v[54:57], v[166:169], v[208:211], v[54:57]
	v_mfma_f32_16x16x32_bf16 v[46:49], v[174:177], v[208:211], v[46:49]
	v_mfma_f32_16x16x32_bf16 v[38:41], v[166:169], v[216:219], v[38:41]
	v_mfma_f32_16x16x32_bf16 v[30:33], v[174:177], v[216:219], v[30:33]
	v_mfma_f32_16x16x32_bf16 v[22:25], v[166:169], v[224:227], v[22:25]
	v_mfma_f32_16x16x32_bf16 v[14:17], v[174:177], v[224:227], v[14:17]
	v_mfma_f32_16x16x32_bf16 v[50:53], v[178:181], v[196:199], 0
	v_mfma_f32_16x16x32_bf16 v[42:45], v[188:191], v[196:199], 0
	v_mfma_f32_16x16x32_bf16 v[34:37], v[178:181], v[204:207], 0
	v_mfma_f32_16x16x32_bf16 v[26:29], v[188:191], v[204:207], 0
	v_mfma_f32_16x16x32_bf16 v[18:21], v[178:181], v[212:215], 0
	v_mfma_f32_16x16x32_bf16 v[10:13], v[188:191], v[212:215], 0
	v_mfma_f32_16x16x32_bf16 v[6:9], v[178:181], v[220:223], 0
	v_mfma_f32_16x16x32_bf16 v[2:5], v[188:191], v[220:223], 0
	v_mfma_f32_16x16x32_bf16 v[50:53], v[184:187], v[200:203], v[50:53]
	v_mfma_f32_16x16x32_bf16 v[42:45], v[192:195], v[200:203], v[42:45]
	v_mfma_f32_16x16x32_bf16 v[34:37], v[184:187], v[208:211], v[34:37]
	v_mfma_f32_16x16x32_bf16 v[26:29], v[192:195], v[208:211], v[26:29]
	v_mfma_f32_16x16x32_bf16 v[18:21], v[184:187], v[216:219], v[18:21]
	v_mfma_f32_16x16x32_bf16 v[10:13], v[192:195], v[216:219], v[10:13]
	v_mfma_f32_16x16x32_bf16 v[6:9], v[184:187], v[224:227], v[6:9]
	v_mfma_f32_16x16x32_bf16 v[2:5], v[192:195], v[224:227], v[2:5]
	s_barrier
	s_setprio 0
	s_add_i32 s39, 0, 0x18000
	s_add_i32 s40, 0, 0x1c000
	v_add_u32_e32 v174, s39, v139
	v_add_u32_e32 v192, s40, v139
	ds_read_b128 v[160:163], v174
	ds_read_b128 v[166:169], v174 offset:1024
	ds_read_b128 v[170:173], v174 offset:2048
	ds_read_b128 v[174:177], v174 offset:3072
	ds_read_b128 v[178:181], v192
	ds_read_b128 v[184:187], v192 offset:1024
	ds_read_b128 v[188:191], v192 offset:2048
	ds_read_b128 v[192:195], v192 offset:3072
	s_add_u32 s12, s18, 0x44000
	s_addc_u32 s13, s19, 0
	s_mov_b32 m0, s25
	v_lshl_add_u64 v[236:237], s[12:13], 0, v[130:131]
	ds_read_b128 v[196:199], v165 offset:32768
	ds_read_b128 v[200:203], v165 offset:33792
	ds_read_b128 v[204:207], v165 offset:34816
	ds_read_b128 v[208:211], v165 offset:35840
	ds_read_b128 v[212:215], v165 offset:36864
	ds_read_b128 v[216:219], v165 offset:37888
	ds_read_b128 v[220:223], v165 offset:38912
	ds_read_b128 v[224:227], v165 offset:39936
	global_load_lds_dwordx4 v[236:237], off
	s_mov_b32 m0, s26
	v_lshl_add_u64 v[236:237], s[12:13], 0, v[134:135]
	global_load_lds_dwordx4 v[236:237], off
	s_setprio 1
	s_waitcnt vmcnt(8) lgkmcnt(0)
	s_barrier
	v_mfma_f32_16x16x32_bf16 v[126:129], v[160:163], v[196:199], v[126:129]
	v_mfma_f32_16x16x32_bf16 v[122:125], v[170:173], v[196:199], v[122:125]
	v_mfma_f32_16x16x32_bf16 v[118:121], v[160:163], v[204:207], v[118:121]
	v_mfma_f32_16x16x32_bf16 v[110:113], v[170:173], v[204:207], v[110:113]
	v_mfma_f32_16x16x32_bf16 v[102:105], v[160:163], v[212:215], v[102:105]
	v_mfma_f32_16x16x32_bf16 v[94:97], v[170:173], v[212:215], v[94:97]
	v_mfma_f32_16x16x32_bf16 v[86:89], v[160:163], v[220:223], v[86:89]
	v_mfma_f32_16x16x32_bf16 v[78:81], v[170:173], v[220:223], v[78:81]
	v_mfma_f32_16x16x32_bf16 v[126:129], v[166:169], v[200:203], v[126:129]
	v_mfma_f32_16x16x32_bf16 v[122:125], v[174:177], v[200:203], v[122:125]
	v_mfma_f32_16x16x32_bf16 v[118:121], v[166:169], v[208:211], v[118:121]
	v_mfma_f32_16x16x32_bf16 v[110:113], v[174:177], v[208:211], v[110:113]
	v_mfma_f32_16x16x32_bf16 v[102:105], v[166:169], v[216:219], v[102:105]
	v_mfma_f32_16x16x32_bf16 v[94:97], v[174:177], v[216:219], v[94:97]
	v_mfma_f32_16x16x32_bf16 v[86:89], v[166:169], v[224:227], v[86:89]
	v_mfma_f32_16x16x32_bf16 v[78:81], v[174:177], v[224:227], v[78:81]
	v_mfma_f32_16x16x32_bf16 v[114:117], v[178:181], v[196:199], v[114:117]
	v_mfma_f32_16x16x32_bf16 v[106:109], v[188:191], v[196:199], v[106:109]
	v_mfma_f32_16x16x32_bf16 v[98:101], v[178:181], v[204:207], v[98:101]
	v_mfma_f32_16x16x32_bf16 v[90:93], v[188:191], v[204:207], v[90:93]
	v_mfma_f32_16x16x32_bf16 v[82:85], v[178:181], v[212:215], v[82:85]
	v_mfma_f32_16x16x32_bf16 v[74:77], v[188:191], v[212:215], v[74:77]
	v_mfma_f32_16x16x32_bf16 v[70:73], v[178:181], v[220:223], v[70:73]
	v_mfma_f32_16x16x32_bf16 v[66:69], v[188:191], v[220:223], v[66:69]
	v_mfma_f32_16x16x32_bf16 v[114:117], v[184:187], v[200:203], v[114:117]
	v_mfma_f32_16x16x32_bf16 v[106:109], v[192:195], v[200:203], v[106:109]
	v_mfma_f32_16x16x32_bf16 v[98:101], v[184:187], v[208:211], v[98:101]
	v_mfma_f32_16x16x32_bf16 v[90:93], v[192:195], v[208:211], v[90:93]
	v_mfma_f32_16x16x32_bf16 v[82:85], v[184:187], v[216:219], v[82:85]
	v_mfma_f32_16x16x32_bf16 v[74:77], v[192:195], v[216:219], v[74:77]
	v_mfma_f32_16x16x32_bf16 v[70:73], v[184:187], v[224:227], v[70:73]
	v_mfma_f32_16x16x32_bf16 v[66:69], v[192:195], v[224:227], v[66:69]
	s_barrier
; #define PG8_STAGE(bufoff, gbase, voff) do { _Pragma("unroll") for (int _i = 0; _i < 2; ++_i) \
;         __builtin_amdgcn_global_load_lds((const unsigned*)((const char*)(gbase) + (voff)[_i]), (LAS unsigned*)(lds + (bufoff) + ldsw + _i * 8192), 16, 0, 0); } while (0)
; #define PG8_LDA(dst, b, h) do { _Pragma("unroll") for (int m = 0; m < 4; ++m) _Pragma("unroll") for (int k = 0; k < 2; ++k) dst[m][k] = *(const LAS bf16x8*)(lds + PG8_SA(b, h) + aoff + m * 2048 + k * 1024); } while (0)
; #define PG8_LDB(dst, b, h) do { _Pragma("unroll") for (int n = 0; n < 2; ++n) _Pragma("unroll") for (int k = 0; k < 2; ++k) dst[n][k] = *(const LAS bf16x8*)(lds + PG8_SB(b, h) + boff + n * 2048 + k * 1024); } while (0)
; #define PG8_MMA(ai, bj, At, Bt) do { __builtin_amdgcn_s_setprio(1); _Pragma("unroll") for (int m = 0; m < 4; ++m) _Pragma("unroll") for (int n = 0; n < 2; ++n) _Pragma("unroll") for (int k = 0; k < 2; ++k) \
;         acc[ai][bj][m][n] = __builtin_amdgcn_mfma_f32_16x16x32_bf16(Bt[n][k], At[m][k], acc[ai][bj][m][n], 0, 0, 0); __builtin_amdgcn_s_setprio(0); } while (0)
; #define PG8_WAIT_V(n) asm volatile("s_waitcnt vmcnt(" #n ")" ::: "memory")
; #define PG8_WAIT_L(n) asm volatile("s_waitcnt lgkmcnt(" #n ")" ::: "memory")
; #define PG8_BAR __builtin_amdgcn_s_barrier()
; #define PG8_SCHED __builtin_amdgcn_sched_barrier(0)
; template <class Epi, bool ALIGN_EPI = PG8_ALIGN, bool SP2 = PG8_SP2>
; __device__ __forceinline__ void gemm_phase(LAS uchar* lds, const Gemm g, const StaticOrder& S, const Epi& E) {
;     ...
;         for (int t = tb; t < tb + tblk; t += 2) {
;             const bool last = (t == nt - 2);
;             const char* a1 = cA + (size_t)(t + 1) * kstep;
;             const char* a2 = last ? nA : cA + (size_t)(t + 2) * kstep; const char* b2 = last ? nB : cB + (size_t)(t + 2) * kstep;
;             const char* a3 = a2 + kstep; const char* b3 = b2 + kstep;
;             if constexpr (SP2) {
;             PG8_LDB(B0, 0, 0); PG8_LDB(B1, 0, 1); PG8_SCHED; PG8_LDA(At, 0, 0); PG8_STAGE(PG8_SA(1, 1), a1 + hstepA, voffA);
;     ...
;             PG8_LDA(At, 1, 1); PG8_STAGE(PG8_SB(1, 0), b3, voffB); PG8_STAGE(PG8_SB(1, 1), b3 + hstepB, voffB); PG8_STAGE(PG8_SA(1, 0), a3, voffA);
;             PG8_WAIT_V(8); PG8_WAIT_L(0); PG8_BAR; PG8_MMA(1, 0, At, B0); PG8_MMA(1, 1, At, B1); PG8_BAR; PG8_SCHED;
	s_setprio 0
	s_add_i32 s12, s39, s22
	v_lshl_add_u64 v[228:229], v[228:229], 0, s[84:85]
	s_mov_b32 m0, s12
	ds_read_b128 v[196:199], v165 offset:49152
	ds_read_b128 v[200:203], v165 offset:50176
	ds_read_b128 v[204:207], v165 offset:51200
	ds_read_b128 v[208:211], v165 offset:52224
	ds_read_b128 v[212:215], v165 offset:53248
	ds_read_b128 v[216:219], v165 offset:54272
	ds_read_b128 v[220:223], v165 offset:55296
	ds_read_b128 v[224:227], v165 offset:56320
	global_load_lds_dwordx4 v[228:229], off
	s_add_i32 m0, s12, 0x2000
	s_add_u32 s12, s16, 0x44080
	v_lshl_add_u64 v[228:229], v[230:231], 0, s[84:85]
	s_addc_u32 s13, s17, 0
	s_add_i32 s16, s40, s22
	global_load_lds_dwordx4 v[228:229], off
	s_mov_b32 m0, s16
	v_lshl_add_u64 v[228:229], s[12:13], 0, v[132:133]
	global_load_lds_dwordx4 v[228:229], off
	s_add_i32 m0, s16, 0x2000
	v_lshl_add_u64 v[228:229], s[12:13], 0, v[152:153]
	global_load_lds_dwordx4 v[228:229], off
	s_mov_b32 m0, s27
	v_lshl_add_u64 v[228:229], v[232:233], 0, s[84:85]
	global_load_lds_dwordx4 v[228:229], off
	s_mov_b32 m0, s28
	v_lshl_add_u64 v[228:229], v[234:235], 0, s[84:85]
	global_load_lds_dwordx4 v[228:229], off
	s_setprio 1
	s_waitcnt vmcnt(8) lgkmcnt(0)
	s_barrier
	v_mfma_f32_16x16x32_bf16 v[62:65], v[160:163], v[196:199], v[62:65]
	v_mfma_f32_16x16x32_bf16 v[58:61], v[170:173], v[196:199], v[58:61]
	v_mfma_f32_16x16x32_bf16 v[54:57], v[160:163], v[204:207], v[54:57]
	v_mfma_f32_16x16x32_bf16 v[46:49], v[170:173], v[204:207], v[46:49]
	v_mfma_f32_16x16x32_bf16 v[38:41], v[160:163], v[212:215], v[38:41]
	v_mfma_f32_16x16x32_bf16 v[30:33], v[170:173], v[212:215], v[30:33]
	v_mfma_f32_16x16x32_bf16 v[22:25], v[160:163], v[220:223], v[22:25]
	v_mfma_f32_16x16x32_bf16 v[14:17], v[170:173], v[220:223], v[14:17]
	v_mfma_f32_16x16x32_bf16 v[62:65], v[166:169], v[200:203], v[62:65]
	v_mfma_f32_16x16x32_bf16 v[58:61], v[174:177], v[200:203], v[58:61]
	v_mfma_f32_16x16x32_bf16 v[54:57], v[166:169], v[208:211], v[54:57]
	v_mfma_f32_16x16x32_bf16 v[46:49], v[174:177], v[208:211], v[46:49]
	v_mfma_f32_16x16x32_bf16 v[38:41], v[166:169], v[216:219], v[38:41]
	v_mfma_f32_16x16x32_bf16 v[30:33], v[174:177], v[216:219], v[30:33]
	v_mfma_f32_16x16x32_bf16 v[22:25], v[166:169], v[224:227], v[22:25]
	v_mfma_f32_16x16x32_bf16 v[14:17], v[174:177], v[224:227], v[14:17]
	v_mfma_f32_16x16x32_bf16 v[50:53], v[178:181], v[196:199], v[50:53]
	v_mfma_f32_16x16x32_bf16 v[42:45], v[188:191], v[196:199], v[42:45]
	v_mfma_f32_16x16x32_bf16 v[34:37], v[178:181], v[204:207], v[34:37]
	v_mfma_f32_16x16x32_bf16 v[26:29], v[188:191], v[204:207], v[26:29]
	v_mfma_f32_16x16x32_bf16 v[18:21], v[178:181], v[212:215], v[18:21]
	v_mfma_f32_16x16x32_bf16 v[10:13], v[188:191], v[212:215], v[10:13]
	v_mfma_f32_16x16x32_bf16 v[6:9], v[178:181], v[220:223], v[6:9]
	v_mfma_f32_16x16x32_bf16 v[2:5], v[188:191], v[220:223], v[2:5]
	v_mfma_f32_16x16x32_bf16 v[50:53], v[184:187], v[200:203], v[50:53]
	v_mfma_f32_16x16x32_bf16 v[42:45], v[192:195], v[200:203], v[42:45]
	v_mfma_f32_16x16x32_bf16 v[34:37], v[184:187], v[208:211], v[34:37]
	v_mfma_f32_16x16x32_bf16 v[26:29], v[192:195], v[208:211], v[26:29]
	v_mfma_f32_16x16x32_bf16 v[18:21], v[184:187], v[216:219], v[18:21]
	v_mfma_f32_16x16x32_bf16 v[10:13], v[192:195], v[216:219], v[10:13]
	v_mfma_f32_16x16x32_bf16 v[6:9], v[184:187], v[224:227], v[6:9]
	v_mfma_f32_16x16x32_bf16 v[2:5], v[192:195], v[224:227], v[2:5]
	s_barrier
	s_setprio 0
	s_add_i32 s38, s38, 2
	s_add_u32 s36, s36, 0x100
	s_addc_u32 s37, s37, 0
	s_cmp_gt_u32 s38, 13
	s_mov_b64 s[12:13], s[14:15]
.LBB0_837:
	s_add_u32 s14, s12, 0x100
	s_addc_u32 s15, s13, 0
	s_add_i32 s39, 0, 0x10000
	s_cmp_eq_u32 s38, 12
	s_cselect_b32 s19, s5, s15
	s_cselect_b32 s18, s4, s14
	s_cselect_b32 s17, s11, s37
	s_cselect_b32 s16, s10, s36
	s_add_i32 s40, 0, 0x14000
	v_add_u32_e32 v174, s39, v139
	v_add_u32_e32 v192, s40, v139
	ds_read_b128 v[160:163], v174
	ds_read_b128 v[166:169], v174 offset:1024
	ds_read_b128 v[170:173], v174 offset:2048
	ds_read_b128 v[174:177], v174 offset:3072
	ds_read_b128 v[178:181], v192
	ds_read_b128 v[184:187], v192 offset:1024
	ds_read_b128 v[188:191], v192 offset:2048
	ds_read_b128 v[192:195], v192 offset:3072
	v_lshl_add_u64 v[228:229], s[12:13], 0, v[156:157]
	s_add_i32 m0, s23, 0xc000
	ds_read_b128 v[196:199], v165
	ds_read_b128 v[200:203], v165 offset:1024
	ds_read_b128 v[204:207], v165 offset:2048
	ds_read_b128 v[208:211], v165 offset:3072
	ds_read_b128 v[212:215], v165 offset:4096
	ds_read_b128 v[216:219], v165 offset:5120
	ds_read_b128 v[220:223], v165 offset:6144
	ds_read_b128 v[224:227], v165 offset:7168
	global_load_lds_dwordx4 v[228:229], off
	s_add_i32 m0, s23, 0xe000
	v_lshl_add_u64 v[228:229], s[12:13], 0, v[158:159]
	global_load_lds_dwordx4 v[228:229], off
	s_setprio 1
	s_waitcnt vmcnt(8) lgkmcnt(0)
	s_barrier
; #define PG8_STAGE(bufoff, gbase, voff) do { _Pragma("unroll") for (int _i = 0; _i < 2; ++_i) \
;         __builtin_amdgcn_global_load_lds((const unsigned*)((const char*)(gbase) + (voff)[_i]), (LAS unsigned*)(lds + (bufoff) + ldsw + _i * 8192), 16, 0, 0); } while (0)
; #define PG8_LDA(dst, b, h) do { _Pragma("unroll") for (int m = 0; m < 4; ++m) _Pragma("unroll") for (int k = 0; k < 2; ++k) dst[m][k] = *(const LAS bf16x8*)(lds + PG8_SA(b, h) + aoff + m * 2048 + k * 1024); } while (0)
; #define PG8_LDB(dst, b, h) do { _Pragma("unroll") for (int n = 0; n < 2; ++n) _Pragma("unroll") for (int k = 0; k < 2; ++k) dst[n][k] = *(const LAS bf16x8*)(lds + PG8_SB(b, h) + boff + n * 2048 + k * 1024); } while (0)
; #define PG8_MMA(ai, bj, At, Bt) do { __builtin_amdgcn_s_setprio(1); _Pragma("unroll") for (int m = 0; m < 4; ++m) _Pragma("unroll") for (int n = 0; n < 2; ++n) _Pragma("unroll") for (int k = 0; k < 2; ++k) \
;         acc[ai][bj][m][n] = __builtin_amdgcn_mfma_f32_16x16x32_bf16(Bt[n][k], At[m][k], acc[ai][bj][m][n], 0, 0, 0); __builtin_amdgcn_s_setprio(0); } while (0)
; #define PG8_WAIT_V(n) asm volatile("s_waitcnt vmcnt(" #n ")" ::: "memory")
; #define PG8_WAIT_L(n) asm volatile("s_waitcnt lgkmcnt(" #n ")" ::: "memory")
; #define PG8_BAR __builtin_amdgcn_s_barrier()
; #define PG8_SCHED __builtin_amdgcn_sched_barrier(0)
; template <class Epi, bool ALIGN_EPI = PG8_ALIGN, bool SP2 = PG8_SP2>
; __device__ __forceinline__ void gemm_phase(LAS uchar* lds, const Gemm g, const StaticOrder& S, const Epi& E) {
;     ...
;             PG8_LDB(B0, 0, 0); PG8_LDB(B1, 0, 1); PG8_SCHED; PG8_LDA(At, 0, 0); PG8_STAGE(PG8_SA(1, 1), a1 + hstepA, voffA);
;             PG8_WAIT_V(8); PG8_WAIT_L(0); PG8_BAR; PG8_MMA(0, 0, At, B0); PG8_MMA(0, 1, At, B1); PG8_BAR; PG8_SCHED;
;             PG8_LDA(At, 0, 1); PG8_STAGE(PG8_SB(0, 0), b2, voffB); PG8_STAGE(PG8_SB(0, 1), b2 + hstepB, voffB); PG8_STAGE(PG8_SA(0, 0), a2, voffA);
;             PG8_WAIT_V(8); PG8_WAIT_L(0); PG8_BAR; PG8_MMA(1, 0, At, B0); PG8_MMA(1, 1, At, B1); PG8_BAR; PG8_SCHED;
	v_mfma_f32_16x16x32_bf16 v[126:129], v[160:163], v[196:199], v[126:129]
	v_mfma_f32_16x16x32_bf16 v[122:125], v[170:173], v[196:199], v[122:125]
	v_mfma_f32_16x16x32_bf16 v[118:121], v[160:163], v[204:207], v[118:121]
	v_mfma_f32_16x16x32_bf16 v[110:113], v[170:173], v[204:207], v[110:113]
	v_mfma_f32_16x16x32_bf16 v[102:105], v[160:163], v[212:215], v[102:105]
	v_mfma_f32_16x16x32_bf16 v[94:97], v[170:173], v[212:215], v[94:97]
	v_mfma_f32_16x16x32_bf16 v[86:89], v[160:163], v[220:223], v[86:89]
	v_mfma_f32_16x16x32_bf16 v[78:81], v[170:173], v[220:223], v[78:81]
	v_mfma_f32_16x16x32_bf16 v[126:129], v[166:169], v[200:203], v[126:129]
	v_mfma_f32_16x16x32_bf16 v[122:125], v[174:177], v[200:203], v[122:125]
	v_mfma_f32_16x16x32_bf16 v[118:121], v[166:169], v[208:211], v[118:121]
	v_mfma_f32_16x16x32_bf16 v[110:113], v[174:177], v[208:211], v[110:113]
	v_mfma_f32_16x16x32_bf16 v[102:105], v[166:169], v[216:219], v[102:105]
	v_mfma_f32_16x16x32_bf16 v[94:97], v[174:177], v[216:219], v[94:97]
	v_mfma_f32_16x16x32_bf16 v[86:89], v[166:169], v[224:227], v[86:89]
	v_mfma_f32_16x16x32_bf16 v[78:81], v[174:177], v[224:227], v[78:81]
	v_mfma_f32_16x16x32_bf16 v[114:117], v[178:181], v[196:199], v[114:117]
	v_mfma_f32_16x16x32_bf16 v[106:109], v[188:191], v[196:199], v[106:109]
	v_mfma_f32_16x16x32_bf16 v[98:101], v[178:181], v[204:207], v[98:101]
	v_mfma_f32_16x16x32_bf16 v[90:93], v[188:191], v[204:207], v[90:93]
	v_mfma_f32_16x16x32_bf16 v[82:85], v[178:181], v[212:215], v[82:85]
	v_mfma_f32_16x16x32_bf16 v[74:77], v[188:191], v[212:215], v[74:77]
	v_mfma_f32_16x16x32_bf16 v[70:73], v[178:181], v[220:223], v[70:73]
	v_mfma_f32_16x16x32_bf16 v[66:69], v[188:191], v[220:223], v[66:69]
	v_mfma_f32_16x16x32_bf16 v[114:117], v[184:187], v[200:203], v[114:117]
	v_mfma_f32_16x16x32_bf16 v[106:109], v[192:195], v[200:203], v[106:109]
	v_mfma_f32_16x16x32_bf16 v[98:101], v[184:187], v[208:211], v[98:101]
	v_mfma_f32_16x16x32_bf16 v[90:93], v[192:195], v[208:211], v[90:93]
	v_mfma_f32_16x16x32_bf16 v[82:85], v[184:187], v[216:219], v[82:85]
	v_mfma_f32_16x16x32_bf16 v[74:77], v[192:195], v[216:219], v[74:77]
	v_mfma_f32_16x16x32_bf16 v[70:73], v[184:187], v[224:227], v[70:73]
	v_mfma_f32_16x16x32_bf16 v[66:69], v[192:195], v[224:227], v[66:69]
	s_barrier
	s_setprio 0
	s_add_i32 s12, s39, s22
	v_lshl_add_u64 v[228:229], s[16:17], 0, v[132:133]
	s_mov_b32 m0, s12
	ds_read_b128 v[196:199], v165 offset:16384
	ds_read_b128 v[200:203], v165 offset:17408
	ds_read_b128 v[204:207], v165 offset:18432
	ds_read_b128 v[208:211], v165 offset:19456
	ds_read_b128 v[212:215], v165 offset:20480
	ds_read_b128 v[216:219], v165 offset:21504
	ds_read_b128 v[220:223], v165 offset:22528
	ds_read_b128 v[224:227], v165 offset:23552
	global_load_lds_dwordx4 v[228:229], off
	s_add_i32 m0, s12, 0x2000
	s_add_u32 s12, s16, 0x44000
	v_lshl_add_u64 v[230:231], s[16:17], 0, v[152:153]
	s_addc_u32 s13, s17, 0
	s_add_i32 s39, s40, s22
	global_load_lds_dwordx4 v[230:231], off
	v_lshl_add_u64 v[232:233], s[12:13], 0, v[132:133]
	s_mov_b32 m0, s39
	global_load_lds_dwordx4 v[232:233], off
	s_add_i32 m0, s39, 0x2000
	v_lshl_add_u64 v[232:233], s[12:13], 0, v[152:153]
	global_load_lds_dwordx4 v[232:233], off
	s_mov_b32 m0, s23
	v_lshl_add_u64 v[232:233], s[18:19], 0, v[130:131]
	global_load_lds_dwordx4 v[232:233], off
	s_mov_b32 m0, s24
	v_lshl_add_u64 v[234:235], s[18:19], 0, v[134:135]
	global_load_lds_dwordx4 v[234:235], off
	s_setprio 1
	s_waitcnt vmcnt(8) lgkmcnt(0)
	s_barrier
	v_mfma_f32_16x16x32_bf16 v[62:65], v[160:163], v[196:199], v[62:65]
	v_mfma_f32_16x16x32_bf16 v[58:61], v[170:173], v[196:199], v[58:61]
	v_mfma_f32_16x16x32_bf16 v[54:57], v[160:163], v[204:207], v[54:57]
	v_mfma_f32_16x16x32_bf16 v[46:49], v[170:173], v[204:207], v[46:49]
	v_mfma_f32_16x16x32_bf16 v[38:41], v[160:163], v[212:215], v[38:41]
	v_mfma_f32_16x16x32_bf16 v[30:33], v[170:173], v[212:215], v[30:33]
	v_mfma_f32_16x16x32_bf16 v[22:25], v[160:163], v[220:223], v[22:25]
	v_mfma_f32_16x16x32_bf16 v[14:17], v[170:173], v[220:223], v[14:17]
	v_mfma_f32_16x16x32_bf16 v[62:65], v[166:169], v[200:203], v[62:65]
	v_mfma_f32_16x16x32_bf16 v[58:61], v[174:177], v[200:203], v[58:61]
	v_mfma_f32_16x16x32_bf16 v[54:57], v[166:169], v[208:211], v[54:57]
	v_mfma_f32_16x16x32_bf16 v[46:49], v[174:177], v[208:211], v[46:49]
	v_mfma_f32_16x16x32_bf16 v[38:41], v[166:169], v[216:219], v[38:41]
	v_mfma_f32_16x16x32_bf16 v[30:33], v[174:177], v[216:219], v[30:33]
	v_mfma_f32_16x16x32_bf16 v[22:25], v[166:169], v[224:227], v[22:25]
	v_mfma_f32_16x16x32_bf16 v[14:17], v[174:177], v[224:227], v[14:17]
	v_mfma_f32_16x16x32_bf16 v[50:53], v[178:181], v[196:199], v[50:53]
	v_mfma_f32_16x16x32_bf16 v[42:45], v[188:191], v[196:199], v[42:45]
	v_mfma_f32_16x16x32_bf16 v[34:37], v[178:181], v[204:207], v[34:37]
	v_mfma_f32_16x16x32_bf16 v[26:29], v[188:191], v[204:207], v[26:29]
	v_mfma_f32_16x16x32_bf16 v[18:21], v[178:181], v[212:215], v[18:21]
	v_mfma_f32_16x16x32_bf16 v[10:13], v[188:191], v[212:215], v[10:13]
	v_mfma_f32_16x16x32_bf16 v[6:9], v[178:181], v[220:223], v[6:9]
	v_mfma_f32_16x16x32_bf16 v[2:5], v[188:191], v[220:223], v[2:5]
	v_mfma_f32_16x16x32_bf16 v[50:53], v[184:187], v[200:203], v[50:53]
	v_mfma_f32_16x16x32_bf16 v[42:45], v[192:195], v[200:203], v[42:45]
	v_mfma_f32_16x16x32_bf16 v[34:37], v[184:187], v[208:211], v[34:37]
	v_mfma_f32_16x16x32_bf16 v[26:29], v[192:195], v[208:211], v[26:29]
	v_mfma_f32_16x16x32_bf16 v[18:21], v[184:187], v[216:219], v[18:21]
	v_mfma_f32_16x16x32_bf16 v[10:13], v[192:195], v[216:219], v[10:13]
	v_mfma_f32_16x16x32_bf16 v[6:9], v[184:187], v[224:227], v[6:9]
	v_mfma_f32_16x16x32_bf16 v[2:5], v[192:195], v[224:227], v[2:5]
	s_barrier
; #define PG8_STAGE(bufoff, gbase, voff) do { _Pragma("unroll") for (int _i = 0; _i < 2; ++_i) \
;         __builtin_amdgcn_global_load_lds((const unsigned*)((const char*)(gbase) + (voff)[_i]), (LAS unsigned*)(lds + (bufoff) + ldsw + _i * 8192), 16, 0, 0); } while (0)
; #define PG8_LDA(dst, b, h) do { _Pragma("unroll") for (int m = 0; m < 4; ++m) _Pragma("unroll") for (int k = 0; k < 2; ++k) dst[m][k] = *(const LAS bf16x8*)(lds + PG8_SA(b, h) + aoff + m * 2048 + k * 1024); } while (0)
; #define PG8_LDB(dst, b, h) do { _Pragma("unroll") for (int n = 0; n < 2; ++n) _Pragma("unroll") for (int k = 0; k < 2; ++k) dst[n][k] = *(const LAS bf16x8*)(lds + PG8_SB(b, h) + boff + n * 2048 + k * 1024); } while (0)
; #define PG8_MMA(ai, bj, At, Bt) do { __builtin_amdgcn_s_setprio(1); _Pragma("unroll") for (int m = 0; m < 4; ++m) _Pragma("unroll") for (int n = 0; n < 2; ++n) _Pragma("unroll") for (int k = 0; k < 2; ++k) \
;         acc[ai][bj][m][n] = __builtin_amdgcn_mfma_f32_16x16x32_bf16(Bt[n][k], At[m][k], acc[ai][bj][m][n], 0, 0, 0); __builtin_amdgcn_s_setprio(0); } while (0)
; #define PG8_WAIT_V(n) asm volatile("s_waitcnt vmcnt(" #n ")" ::: "memory")
; #define PG8_WAIT_L(n) asm volatile("s_waitcnt lgkmcnt(" #n ")" ::: "memory")
; #define PG8_BAR __builtin_amdgcn_s_barrier()
; #define PG8_SCHED __builtin_amdgcn_sched_barrier(0)
; template <class Epi, bool ALIGN_EPI = PG8_ALIGN, bool SP2 = PG8_SP2>
; __device__ __forceinline__ void gemm_phase(LAS uchar* lds, const Gemm g, const StaticOrder& S, const Epi& E) {
;     ...
;             PG8_WAIT_V(8); PG8_WAIT_L(0); PG8_BAR; PG8_MMA(1, 0, At, B0); PG8_MMA(1, 1, At, B1); PG8_BAR; PG8_SCHED;
;             PG8_LDB(B0, 1, 0); PG8_LDB(B1, 1, 1); PG8_SCHED; PG8_LDA(At, 1, 0); PG8_STAGE(PG8_SA(0, 1), a2 + hstepA, voffA);
;             PG8_WAIT_V(8); PG8_WAIT_L(0); PG8_BAR; PG8_MMA(0, 0, At, B0); PG8_MMA(0, 1, At, B1); PG8_BAR; PG8_SCHED;
	s_setprio 0
	s_add_i32 s39, 0, 0x18000
	s_add_i32 s40, 0, 0x1c000
	v_add_u32_e32 v174, s39, v139
	v_add_u32_e32 v192, s40, v139
	ds_read_b128 v[160:163], v174
	ds_read_b128 v[166:169], v174 offset:1024
	ds_read_b128 v[170:173], v174 offset:2048
	ds_read_b128 v[174:177], v174 offset:3072
	ds_read_b128 v[178:181], v192
	ds_read_b128 v[184:187], v192 offset:1024
	ds_read_b128 v[188:191], v192 offset:2048
	ds_read_b128 v[192:195], v192 offset:3072
	s_add_u32 s12, s18, 0x44000
	s_addc_u32 s13, s19, 0
	s_mov_b32 m0, s25
	v_lshl_add_u64 v[236:237], s[12:13], 0, v[130:131]
	ds_read_b128 v[196:199], v165 offset:32768
	ds_read_b128 v[200:203], v165 offset:33792
	ds_read_b128 v[204:207], v165 offset:34816
	ds_read_b128 v[208:211], v165 offset:35840
	ds_read_b128 v[212:215], v165 offset:36864
	ds_read_b128 v[216:219], v165 offset:37888
	ds_read_b128 v[220:223], v165 offset:38912
	ds_read_b128 v[224:227], v165 offset:39936
	global_load_lds_dwordx4 v[236:237], off
	s_mov_b32 m0, s26
	v_lshl_add_u64 v[236:237], s[12:13], 0, v[134:135]
	global_load_lds_dwordx4 v[236:237], off
	s_setprio 1
	s_waitcnt vmcnt(8) lgkmcnt(0)
	s_barrier
	v_mfma_f32_16x16x32_bf16 v[126:129], v[160:163], v[196:199], v[126:129]
	v_mfma_f32_16x16x32_bf16 v[122:125], v[170:173], v[196:199], v[122:125]
	v_mfma_f32_16x16x32_bf16 v[118:121], v[160:163], v[204:207], v[118:121]
	v_mfma_f32_16x16x32_bf16 v[110:113], v[170:173], v[204:207], v[110:113]
	v_mfma_f32_16x16x32_bf16 v[102:105], v[160:163], v[212:215], v[102:105]
	v_mfma_f32_16x16x32_bf16 v[94:97], v[170:173], v[212:215], v[94:97]
	v_mfma_f32_16x16x32_bf16 v[86:89], v[160:163], v[220:223], v[86:89]
	v_mfma_f32_16x16x32_bf16 v[78:81], v[170:173], v[220:223], v[78:81]
	v_mfma_f32_16x16x32_bf16 v[126:129], v[166:169], v[200:203], v[126:129]
	v_mfma_f32_16x16x32_bf16 v[122:125], v[174:177], v[200:203], v[122:125]
	v_mfma_f32_16x16x32_bf16 v[118:121], v[166:169], v[208:211], v[118:121]
	v_mfma_f32_16x16x32_bf16 v[110:113], v[174:177], v[208:211], v[110:113]
	v_mfma_f32_16x16x32_bf16 v[102:105], v[166:169], v[216:219], v[102:105]
	v_mfma_f32_16x16x32_bf16 v[94:97], v[174:177], v[216:219], v[94:97]
	v_mfma_f32_16x16x32_bf16 v[86:89], v[166:169], v[224:227], v[86:89]
	v_mfma_f32_16x16x32_bf16 v[78:81], v[174:177], v[224:227], v[78:81]
	v_mfma_f32_16x16x32_bf16 v[114:117], v[178:181], v[196:199], v[114:117]
	v_mfma_f32_16x16x32_bf16 v[106:109], v[188:191], v[196:199], v[106:109]
	v_mfma_f32_16x16x32_bf16 v[98:101], v[178:181], v[204:207], v[98:101]
	v_mfma_f32_16x16x32_bf16 v[90:93], v[188:191], v[204:207], v[90:93]
	v_mfma_f32_16x16x32_bf16 v[82:85], v[178:181], v[212:215], v[82:85]
	v_mfma_f32_16x16x32_bf16 v[74:77], v[188:191], v[212:215], v[74:77]
	v_mfma_f32_16x16x32_bf16 v[70:73], v[178:181], v[220:223], v[70:73]
	v_mfma_f32_16x16x32_bf16 v[66:69], v[188:191], v[220:223], v[66:69]
	v_mfma_f32_16x16x32_bf16 v[114:117], v[184:187], v[200:203], v[114:117]
	v_mfma_f32_16x16x32_bf16 v[106:109], v[192:195], v[200:203], v[106:109]
	v_mfma_f32_16x16x32_bf16 v[98:101], v[184:187], v[208:211], v[98:101]
	v_mfma_f32_16x16x32_bf16 v[90:93], v[192:195], v[208:211], v[90:93]
	v_mfma_f32_16x16x32_bf16 v[82:85], v[184:187], v[216:219], v[82:85]
	v_mfma_f32_16x16x32_bf16 v[74:77], v[192:195], v[216:219], v[74:77]
	v_mfma_f32_16x16x32_bf16 v[70:73], v[184:187], v[224:227], v[70:73]
	v_mfma_f32_16x16x32_bf16 v[66:69], v[192:195], v[224:227], v[66:69]
	s_barrier
; #define PG8_STAGE(bufoff, gbase, voff) do { _Pragma("unroll") for (int _i = 0; _i < 2; ++_i) \
;         __builtin_amdgcn_global_load_lds((const unsigned*)((const char*)(gbase) + (voff)[_i]), (LAS unsigned*)(lds + (bufoff) + ldsw + _i * 8192), 16, 0, 0); } while (0)
; #define PG8_LDA(dst, b, h) do { _Pragma("unroll") for (int m = 0; m < 4; ++m) _Pragma("unroll") for (int k = 0; k < 2; ++k) dst[m][k] = *(const LAS bf16x8*)(lds + PG8_SA(b, h) + aoff + m * 2048 + k * 1024); } while (0)
; #define PG8_MMA(ai, bj, At, Bt) do { __builtin_amdgcn_s_setprio(1); _Pragma("unroll") for (int m = 0; m < 4; ++m) _Pragma("unroll") for (int n = 0; n < 2; ++n) _Pragma("unroll") for (int k = 0; k < 2; ++k) \
;         acc[ai][bj][m][n] = __builtin_amdgcn_mfma_f32_16x16x32_bf16(Bt[n][k], At[m][k], acc[ai][bj][m][n], 0, 0, 0); __builtin_amdgcn_s_setprio(0); } while (0)
; #define PG8_WAIT_V(n) asm volatile("s_waitcnt vmcnt(" #n ")" ::: "memory")
; #define PG8_WAIT_L(n) asm volatile("s_waitcnt lgkmcnt(" #n ")" ::: "memory")
; #define PG8_BAR __builtin_amdgcn_s_barrier()
; #define PG8_SCHED __builtin_amdgcn_sched_barrier(0)
; template <class Epi, bool ALIGN_EPI = PG8_ALIGN, bool SP2 = PG8_SP2>
; __device__ __forceinline__ void gemm_phase(LAS uchar* lds, const Gemm g, const StaticOrder& S, const Epi& E) {
;     ...
;             PG8_WAIT_V(8); PG8_WAIT_L(0); PG8_BAR; PG8_MMA(0, 0, At, B0); PG8_MMA(0, 1, At, B1); PG8_BAR; PG8_SCHED;
;             PG8_LDA(At, 1, 1); PG8_STAGE(PG8_SB(1, 0), b3, voffB); PG8_STAGE(PG8_SB(1, 1), b3 + hstepB, voffB); PG8_STAGE(PG8_SA(1, 0), a3, voffA);
;             PG8_WAIT_V(8); PG8_WAIT_L(0); PG8_BAR; PG8_MMA(1, 0, At, B0); PG8_MMA(1, 1, At, B1); PG8_BAR; PG8_SCHED;
;     ...
;         if constexpr (ALIGN_EPI) { if (wr == 0) PG8_BAR; }
	s_setprio 0
	s_add_i32 s12, s39, s22
	v_lshl_add_u64 v[228:229], v[228:229], 0, s[84:85]
	s_mov_b32 m0, s12
	ds_read_b128 v[196:199], v165 offset:49152
	ds_read_b128 v[200:203], v165 offset:50176
	ds_read_b128 v[204:207], v165 offset:51200
	ds_read_b128 v[208:211], v165 offset:52224
	ds_read_b128 v[212:215], v165 offset:53248
	ds_read_b128 v[216:219], v165 offset:54272
	ds_read_b128 v[220:223], v165 offset:55296
	ds_read_b128 v[224:227], v165 offset:56320
	global_load_lds_dwordx4 v[228:229], off
	s_add_i32 m0, s12, 0x2000
	s_add_u32 s12, s16, 0x44080
	v_lshl_add_u64 v[228:229], v[230:231], 0, s[84:85]
	s_addc_u32 s13, s17, 0
	s_add_i32 s16, s40, s22
	global_load_lds_dwordx4 v[228:229], off
	s_mov_b32 m0, s16
	v_lshl_add_u64 v[228:229], s[12:13], 0, v[132:133]
	global_load_lds_dwordx4 v[228:229], off
	s_add_i32 m0, s16, 0x2000
	v_lshl_add_u64 v[228:229], s[12:13], 0, v[152:153]
	global_load_lds_dwordx4 v[228:229], off
	s_mov_b32 m0, s27
	v_lshl_add_u64 v[228:229], v[232:233], 0, s[84:85]
	global_load_lds_dwordx4 v[228:229], off
	s_mov_b32 m0, s28
	v_lshl_add_u64 v[228:229], v[234:235], 0, s[84:85]
	global_load_lds_dwordx4 v[228:229], off
	s_setprio 1
	s_waitcnt vmcnt(8) lgkmcnt(0)
	s_barrier
	v_mfma_f32_16x16x32_bf16 v[62:65], v[160:163], v[196:199], v[62:65]
	v_mfma_f32_16x16x32_bf16 v[58:61], v[170:173], v[196:199], v[58:61]
	v_mfma_f32_16x16x32_bf16 v[54:57], v[160:163], v[204:207], v[54:57]
	v_mfma_f32_16x16x32_bf16 v[46:49], v[170:173], v[204:207], v[46:49]
	v_mfma_f32_16x16x32_bf16 v[38:41], v[160:163], v[212:215], v[38:41]
	v_mfma_f32_16x16x32_bf16 v[30:33], v[170:173], v[212:215], v[30:33]
	v_mfma_f32_16x16x32_bf16 v[22:25], v[160:163], v[220:223], v[22:25]
	v_mfma_f32_16x16x32_bf16 v[14:17], v[170:173], v[220:223], v[14:17]
	v_mfma_f32_16x16x32_bf16 v[62:65], v[166:169], v[200:203], v[62:65]
	v_mfma_f32_16x16x32_bf16 v[58:61], v[174:177], v[200:203], v[58:61]
	v_mfma_f32_16x16x32_bf16 v[54:57], v[166:169], v[208:211], v[54:57]
	v_mfma_f32_16x16x32_bf16 v[46:49], v[174:177], v[208:211], v[46:49]
	v_mfma_f32_16x16x32_bf16 v[38:41], v[166:169], v[216:219], v[38:41]
	v_mfma_f32_16x16x32_bf16 v[30:33], v[174:177], v[216:219], v[30:33]
	v_mfma_f32_16x16x32_bf16 v[22:25], v[166:169], v[224:227], v[22:25]
	v_mfma_f32_16x16x32_bf16 v[14:17], v[174:177], v[224:227], v[14:17]
	v_mfma_f32_16x16x32_bf16 v[50:53], v[178:181], v[196:199], v[50:53]
	v_mfma_f32_16x16x32_bf16 v[42:45], v[188:191], v[196:199], v[42:45]
	v_mfma_f32_16x16x32_bf16 v[34:37], v[178:181], v[204:207], v[34:37]
	v_mfma_f32_16x16x32_bf16 v[26:29], v[188:191], v[204:207], v[26:29]
	v_mfma_f32_16x16x32_bf16 v[18:21], v[178:181], v[212:215], v[18:21]
	v_mfma_f32_16x16x32_bf16 v[10:13], v[188:191], v[212:215], v[10:13]
	v_mfma_f32_16x16x32_bf16 v[6:9], v[178:181], v[220:223], v[6:9]
	v_mfma_f32_16x16x32_bf16 v[2:5], v[188:191], v[220:223], v[2:5]
	v_mfma_f32_16x16x32_bf16 v[50:53], v[184:187], v[200:203], v[50:53]
	v_mfma_f32_16x16x32_bf16 v[42:45], v[192:195], v[200:203], v[42:45]
	v_mfma_f32_16x16x32_bf16 v[34:37], v[184:187], v[208:211], v[34:37]
	v_mfma_f32_16x16x32_bf16 v[26:29], v[192:195], v[208:211], v[26:29]
	v_mfma_f32_16x16x32_bf16 v[18:21], v[184:187], v[216:219], v[18:21]
	v_mfma_f32_16x16x32_bf16 v[10:13], v[192:195], v[216:219], v[10:13]
	v_mfma_f32_16x16x32_bf16 v[6:9], v[184:187], v[224:227], v[6:9]
	v_mfma_f32_16x16x32_bf16 v[2:5], v[192:195], v[224:227], v[2:5]
	s_barrier
	s_setprio 0
	s_add_i32 s38, s38, 2
	s_add_u32 s36, s36, 0x100
	s_addc_u32 s37, s37, 0
	s_cmp_gt_u32 s38, 13
	s_mov_b64 s[12:13], s[14:15]
	s_cbranch_scc0 .LBB0_837
	s_and_b64 vcc, exec, s[8:9]
	s_cbranch_vccz .LBB0_840
	s_barrier

; #define PG8_STAGE(bufoff, gbase, voff) do { _Pragma("unroll") for (int _i = 0; _i < 2; ++_i) \
;         __builtin_amdgcn_global_load_lds((const unsigned*)((const char*)(gbase) + (voff)[_i]), (LAS unsigned*)(lds + (bufoff) + ldsw + _i * 8192), 16, 0, 0); } while (0)
; #define PG8_LDA(dst, b, h) do { _Pragma("unroll") for (int m = 0; m < 4; ++m) _Pragma("unroll") for (int k = 0; k < 2; ++k) dst[m][k] = *(const LAS bf16x8*)(lds + PG8_SA(b, h) + aoff + m * 2048 + k * 1024); } while (0)
; #define PG8_LDB(dst, b, h) do { _Pragma("unroll") for (int n = 0; n < 2; ++n) _Pragma("unroll") for (int k = 0; k < 2; ++k) dst[n][k] = *(const LAS bf16x8*)(lds + PG8_SB(b, h) + boff + n * 2048 + k * 1024); } while (0)
; #define PG8_WAIT_V(n) asm volatile("s_waitcnt vmcnt(" #n ")" ::: "memory")
; #define PG8_WAIT_L(n) asm volatile("s_waitcnt lgkmcnt(" #n ")" ::: "memory")
; #define PG8_BAR __builtin_amdgcn_s_barrier()
; #define PG8_SCHED __builtin_amdgcn_sched_barrier(0)
; template <class Epi, bool ALIGN_EPI = PG8_ALIGN, bool SP2 = PG8_SP2>
; __device__ __forceinline__ void gemm_phase(LAS uchar* lds, const Gemm g, const StaticOrder& S, const Epi& E) {
;     ...
;         for (int t = tb; t < tb + tblk; t += 2) {
;             const bool last = (t == nt - 2);
;             const char* a1 = cA + (size_t)(t + 1) * kstep;
;             const char* a2 = last ? nA : cA + (size_t)(t + 2) * kstep; const char* b2 = last ? nB : cB + (size_t)(t + 2) * kstep;
;             const char* a3 = a2 + kstep; const char* b3 = b2 + kstep;
;             if constexpr (SP2) {
;             PG8_LDB(B0, 0, 0); PG8_LDB(B1, 0, 1); PG8_SCHED; PG8_LDA(At, 0, 0); PG8_STAGE(PG8_SA(1, 1), a1 + hstepA, voffA);
;             PG8_WAIT_V(8); PG8_WAIT_L(0); PG8_BAR; PG8_MMA(0, 0, At, B0); PG8_MMA(0, 1, At, B1); PG8_BAR; PG8_SCHED;
;             PG8_LDA(At, 0, 1); PG8_STAGE(PG8_SB(0, 0), b2, voffB); PG8_STAGE(PG8_SB(0, 1), b2 + hstepB, voffB); PG8_STAGE(PG8_SA(0, 0), a2, voffA);
;             PG8_WAIT_V(8); PG8_WAIT_L(0); PG8_BAR; PG8_MMA(1, 0, At, B0); PG8_MMA(1, 1, At, B1); PG8_BAR; PG8_SCHED;
;             PG8_LDB(B0, 1, 0); PG8_LDB(B1, 1, 1); PG8_SCHED; PG8_LDA(At, 1, 0); PG8_STAGE(PG8_SA(0, 1), a2 + hstepA, voffA);
;             PG8_WAIT_V(8); PG8_WAIT_L(0); PG8_BAR; PG8_MMA(0, 0, At, B0); PG8_MMA(0, 1, At, B1); PG8_BAR; PG8_SCHED;
.Lrw_done_1050_1_pl:
	s_waitcnt lgkmcnt(0)
	s_setprio 1
	s_barrier
	v_mfma_f32_16x16x32_bf16 v[62:65], v[164:167], v[200:203], 0
	v_mfma_f32_16x16x32_bf16 v[54:57], v[172:175], v[200:203], 0
	v_mfma_f32_16x16x32_bf16 v[46:49], v[164:167], v[208:211], 0
	v_mfma_f32_16x16x32_bf16 v[38:41], v[172:175], v[208:211], 0
	v_mfma_f32_16x16x32_bf16 v[30:33], v[164:167], v[216:219], 0
	v_mfma_f32_16x16x32_bf16 v[22:25], v[172:175], v[216:219], 0
	v_mfma_f32_16x16x32_bf16 v[14:17], v[164:167], v[224:227], 0
	v_mfma_f32_16x16x32_bf16 v[6:9], v[172:175], v[224:227], 0
	v_mfma_f32_16x16x32_bf16 v[62:65], v[168:171], v[204:207], v[62:65]
	v_mfma_f32_16x16x32_bf16 v[54:57], v[176:179], v[204:207], v[54:57]
	v_mfma_f32_16x16x32_bf16 v[46:49], v[168:171], v[212:215], v[46:49]
	v_mfma_f32_16x16x32_bf16 v[38:41], v[176:179], v[212:215], v[38:41]
	v_mfma_f32_16x16x32_bf16 v[30:33], v[168:171], v[220:223], v[30:33]
	v_mfma_f32_16x16x32_bf16 v[22:25], v[176:179], v[220:223], v[22:25]
	v_mfma_f32_16x16x32_bf16 v[14:17], v[168:171], v[228:231], v[14:17]
	v_mfma_f32_16x16x32_bf16 v[6:9], v[176:179], v[228:231], v[6:9]
	v_mfma_f32_16x16x32_bf16 v[58:61], v[184:187], v[200:203], 0
	v_mfma_f32_16x16x32_bf16 v[50:53], v[192:195], v[200:203], 0
	v_mfma_f32_16x16x32_bf16 v[42:45], v[184:187], v[208:211], 0
	v_mfma_f32_16x16x32_bf16 v[34:37], v[192:195], v[208:211], 0
	v_mfma_f32_16x16x32_bf16 v[26:29], v[184:187], v[216:219], 0
	v_mfma_f32_16x16x32_bf16 v[18:21], v[192:195], v[216:219], 0
	v_mfma_f32_16x16x32_bf16 v[10:13], v[184:187], v[224:227], 0
	v_mfma_f32_16x16x32_bf16 v[2:5], v[192:195], v[224:227], 0
	v_mfma_f32_16x16x32_bf16 v[58:61], v[188:191], v[204:207], v[58:61]
	v_mfma_f32_16x16x32_bf16 v[50:53], v[196:199], v[204:207], v[50:53]
	v_mfma_f32_16x16x32_bf16 v[42:45], v[188:191], v[212:215], v[42:45]
	v_mfma_f32_16x16x32_bf16 v[34:37], v[196:199], v[212:215], v[34:37]
	v_mfma_f32_16x16x32_bf16 v[26:29], v[188:191], v[220:223], v[26:29]
	v_mfma_f32_16x16x32_bf16 v[18:21], v[196:199], v[220:223], v[18:21]
	v_mfma_f32_16x16x32_bf16 v[10:13], v[188:191], v[228:231], v[10:13]
	v_mfma_f32_16x16x32_bf16 v[2:5], v[196:199], v[228:231], v[2:5]
	s_barrier
	s_setprio 0
	s_add_i32 s39, 0, 0x18000
	v_add_u32_e32 v144, s39, v139
	s_add_i32 s40, 0, 0x1c000
	ds_read_b128 v[164:167], v144
	ds_read_b128 v[168:171], v144 offset:1024
	ds_read_b128 v[172:175], v144 offset:2048
	ds_read_b128 v[176:179], v144 offset:3072
	v_add_u32_e32 v144, s40, v139
	ds_read_b128 v[184:187], v144
	ds_read_b128 v[188:191], v144 offset:1024
	ds_read_b128 v[192:195], v144 offset:2048
	ds_read_b128 v[196:199], v144 offset:3072
	s_add_u32 s12, s18, 0x44000
	s_addc_u32 s13, s19, 0
	s_mov_b32 m0, s25
	v_lshl_add_u64 v[236:237], s[12:13], 0, v[154:155]
	ds_read_b128 v[200:203], v163 offset:32768
	ds_read_b128 v[204:207], v163 offset:33792
	ds_read_b128 v[208:211], v163 offset:34816
	ds_read_b128 v[212:215], v163 offset:35840
	ds_read_b128 v[216:219], v163 offset:36864
	ds_read_b128 v[220:223], v163 offset:37888
	ds_read_b128 v[224:227], v163 offset:38912
	ds_read_b128 v[228:231], v163 offset:39936
	global_load_lds_dwordx4 v[236:237], off
	s_mov_b32 m0, s26
	v_lshl_add_u64 v[236:237], s[12:13], 0, v[132:133]
	global_load_lds_dwordx4 v[236:237], off
	s_setprio 1
	s_waitcnt vmcnt(8) lgkmcnt(0)
	s_barrier
	v_mfma_f32_16x16x32_bf16 v[126:129], v[164:167], v[200:203], v[126:129]
	v_mfma_f32_16x16x32_bf16 v[118:121], v[172:175], v[200:203], v[118:121]
	v_mfma_f32_16x16x32_bf16 v[110:113], v[164:167], v[208:211], v[110:113]
	v_mfma_f32_16x16x32_bf16 v[102:105], v[172:175], v[208:211], v[102:105]
	v_mfma_f32_16x16x32_bf16 v[94:97], v[164:167], v[216:219], v[94:97]
	v_mfma_f32_16x16x32_bf16 v[86:89], v[172:175], v[216:219], v[86:89]
	v_mfma_f32_16x16x32_bf16 v[78:81], v[164:167], v[224:227], v[78:81]
	v_mfma_f32_16x16x32_bf16 v[70:73], v[172:175], v[224:227], v[70:73]
	v_mfma_f32_16x16x32_bf16 v[126:129], v[168:171], v[204:207], v[126:129]
	v_mfma_f32_16x16x32_bf16 v[118:121], v[176:179], v[204:207], v[118:121]
	v_mfma_f32_16x16x32_bf16 v[110:113], v[168:171], v[212:215], v[110:113]
	v_mfma_f32_16x16x32_bf16 v[102:105], v[176:179], v[212:215], v[102:105]
	v_mfma_f32_16x16x32_bf16 v[94:97], v[168:171], v[220:223], v[94:97]
	v_mfma_f32_16x16x32_bf16 v[86:89], v[176:179], v[220:223], v[86:89]
	v_mfma_f32_16x16x32_bf16 v[78:81], v[168:171], v[228:231], v[78:81]
	v_mfma_f32_16x16x32_bf16 v[70:73], v[176:179], v[228:231], v[70:73]
	v_mfma_f32_16x16x32_bf16 v[122:125], v[184:187], v[200:203], v[122:125]
	v_mfma_f32_16x16x32_bf16 v[114:117], v[192:195], v[200:203], v[114:117]
	v_mfma_f32_16x16x32_bf16 v[106:109], v[184:187], v[208:211], v[106:109]
	v_mfma_f32_16x16x32_bf16 v[98:101], v[192:195], v[208:211], v[98:101]
	v_mfma_f32_16x16x32_bf16 v[90:93], v[184:187], v[216:219], v[90:93]
	v_mfma_f32_16x16x32_bf16 v[82:85], v[192:195], v[216:219], v[82:85]
	v_mfma_f32_16x16x32_bf16 v[74:77], v[184:187], v[224:227], v[74:77]
	v_mfma_f32_16x16x32_bf16 v[66:69], v[192:195], v[224:227], v[66:69]
	v_mfma_f32_16x16x32_bf16 v[122:125], v[188:191], v[204:207], v[122:125]
	v_mfma_f32_16x16x32_bf16 v[114:117], v[196:199], v[204:207], v[114:117]
	v_mfma_f32_16x16x32_bf16 v[106:109], v[188:191], v[212:215], v[106:109]
	v_mfma_f32_16x16x32_bf16 v[98:101], v[196:199], v[212:215], v[98:101]
	v_mfma_f32_16x16x32_bf16 v[90:93], v[188:191], v[220:223], v[90:93]
	v_mfma_f32_16x16x32_bf16 v[82:85], v[196:199], v[220:223], v[82:85]
	v_mfma_f32_16x16x32_bf16 v[74:77], v[188:191], v[228:231], v[74:77]
	v_mfma_f32_16x16x32_bf16 v[66:69], v[196:199], v[228:231], v[66:69]
	s_barrier
; #define PG8_STAGE(bufoff, gbase, voff) do { _Pragma("unroll") for (int _i = 0; _i < 2; ++_i) \
;         __builtin_amdgcn_global_load_lds((const unsigned*)((const char*)(gbase) + (voff)[_i]), (LAS unsigned*)(lds + (bufoff) + ldsw + _i * 8192), 16, 0, 0); } while (0)
; #define PG8_LDA(dst, b, h) do { _Pragma("unroll") for (int m = 0; m < 4; ++m) _Pragma("unroll") for (int k = 0; k < 2; ++k) dst[m][k] = *(const LAS bf16x8*)(lds + PG8_SA(b, h) + aoff + m * 2048 + k * 1024); } while (0)
; #define PG8_LDB(dst, b, h) do { _Pragma("unroll") for (int n = 0; n < 2; ++n) _Pragma("unroll") for (int k = 0; k < 2; ++k) dst[n][k] = *(const LAS bf16x8*)(lds + PG8_SB(b, h) + boff + n * 2048 + k * 1024); } while (0)
; #define PG8_BAR __builtin_amdgcn_s_barrier()
; template <class Epi, bool ALIGN_EPI = PG8_ALIGN, bool SP2 = PG8_SP2>
; __device__ __forceinline__ void gemm_phase(LAS uchar* lds, const Gemm g, const StaticOrder& S, const Epi& E) {
;     ...
;         for (int t = tb; t < tb + tblk; t += 2) {
;             const bool last = (t == nt - 2);
;             const char* a1 = cA + (size_t)(t + 1) * kstep;
;             const char* a2 = last ? nA : cA + (size_t)(t + 2) * kstep; const char* b2 = last ? nB : cB + (size_t)(t + 2) * kstep;
;             const char* a3 = a2 + kstep; const char* b3 = b2 + kstep;
;             if constexpr (SP2) {
;             PG8_LDB(B0, 0, 0); PG8_LDB(B1, 0, 1); PG8_SCHED; PG8_LDA(At, 0, 0); PG8_STAGE(PG8_SA(1, 1), a1 + hstepA, voffA);
;             PG8_WAIT_V(8); PG8_WAIT_L(0); PG8_BAR; PG8_MMA(0, 0, At, B0); PG8_MMA(0, 1, At, B1); PG8_BAR; PG8_SCHED;
;             PG8_LDA(At, 0, 1); PG8_STAGE(PG8_SB(0, 0), b2, voffB); PG8_STAGE(PG8_SB(0, 1), b2 + hstepB, voffB); PG8_STAGE(PG8_SA(0, 0), a2, voffA);
;             PG8_WAIT_V(8); PG8_WAIT_L(0); PG8_BAR; PG8_MMA(1, 0, At, B0); PG8_MMA(1, 1, At, B1); PG8_BAR; PG8_SCHED;
;             PG8_LDB(B0, 1, 0); PG8_LDB(B1, 1, 1); PG8_SCHED; PG8_LDA(At, 1, 0); PG8_STAGE(PG8_SA(0, 1), a2 + hstepA, voffA);
;             PG8_WAIT_V(8); PG8_WAIT_L(0); PG8_BAR; PG8_MMA(0, 0, At, B0); PG8_MMA(0, 1, At, B1); PG8_BAR; PG8_SCHED;
;             PG8_LDA(At, 1, 1); PG8_STAGE(PG8_SB(1, 0), b3, voffB); PG8_STAGE(PG8_SB(1, 1), b3 + hstepB, voffB); PG8_STAGE(PG8_SA(1, 0), a3, voffA);
;             PG8_WAIT_V(8); PG8_WAIT_L(0); PG8_BAR; PG8_MMA(1, 0, At, B0); PG8_MMA(1, 1, At, B1); PG8_BAR; PG8_SCHED;
	s_setprio 0
	s_add_i32 s12, s39, s21
	v_lshl_add_u64 v[160:161], v[160:161], 0, s[84:85]
	s_mov_b32 m0, s12
	ds_read_b128 v[200:203], v163 offset:49152
	ds_read_b128 v[204:207], v163 offset:50176
	ds_read_b128 v[208:211], v163 offset:51200
	ds_read_b128 v[212:215], v163 offset:52224
	ds_read_b128 v[216:219], v163 offset:53248
	ds_read_b128 v[220:223], v163 offset:54272
	ds_read_b128 v[224:227], v163 offset:55296
	ds_read_b128 v[228:231], v163 offset:56320
	global_load_lds_dwordx4 v[160:161], off
	s_add_i32 m0, s12, 0x2000
	s_add_u32 s12, s16, 0x44080
	v_lshl_add_u64 v[160:161], v[180:181], 0, s[84:85]
	s_addc_u32 s13, s17, 0
	s_add_i32 s16, s40, s21
	global_load_lds_dwordx4 v[160:161], off
	s_mov_b32 m0, s16
	v_lshl_add_u64 v[160:161], s[12:13], 0, v[134:135]
	global_load_lds_dwordx4 v[160:161], off
	s_add_i32 m0, s16, 0x2000
	v_lshl_add_u64 v[160:161], s[12:13], 0, v[130:131]
	global_load_lds_dwordx4 v[160:161], off
	s_mov_b32 m0, s27
	v_lshl_add_u64 v[160:161], v[232:233], 0, s[84:85]
	global_load_lds_dwordx4 v[160:161], off
	s_mov_b32 m0, s28
	v_lshl_add_u64 v[160:161], v[234:235], 0, s[84:85]
	global_load_lds_dwordx4 v[160:161], off
	s_setprio 1
	s_waitcnt vmcnt(8) lgkmcnt(0)
	s_barrier
	v_mfma_f32_16x16x32_bf16 v[62:65], v[164:167], v[200:203], v[62:65]
	v_mfma_f32_16x16x32_bf16 v[54:57], v[172:175], v[200:203], v[54:57]
	v_mfma_f32_16x16x32_bf16 v[46:49], v[164:167], v[208:211], v[46:49]
	v_mfma_f32_16x16x32_bf16 v[38:41], v[172:175], v[208:211], v[38:41]
	v_mfma_f32_16x16x32_bf16 v[30:33], v[164:167], v[216:219], v[30:33]
	v_mfma_f32_16x16x32_bf16 v[22:25], v[172:175], v[216:219], v[22:25]
	v_mfma_f32_16x16x32_bf16 v[14:17], v[164:167], v[224:227], v[14:17]
	v_mfma_f32_16x16x32_bf16 v[6:9], v[172:175], v[224:227], v[6:9]
	v_mfma_f32_16x16x32_bf16 v[62:65], v[168:171], v[204:207], v[62:65]
	v_mfma_f32_16x16x32_bf16 v[54:57], v[176:179], v[204:207], v[54:57]
	v_mfma_f32_16x16x32_bf16 v[46:49], v[168:171], v[212:215], v[46:49]
	v_mfma_f32_16x16x32_bf16 v[38:41], v[176:179], v[212:215], v[38:41]
	v_mfma_f32_16x16x32_bf16 v[30:33], v[168:171], v[220:223], v[30:33]
	v_mfma_f32_16x16x32_bf16 v[22:25], v[176:179], v[220:223], v[22:25]
	v_mfma_f32_16x16x32_bf16 v[14:17], v[168:171], v[228:231], v[14:17]
	v_mfma_f32_16x16x32_bf16 v[6:9], v[176:179], v[228:231], v[6:9]
	v_mfma_f32_16x16x32_bf16 v[58:61], v[184:187], v[200:203], v[58:61]
	v_mfma_f32_16x16x32_bf16 v[50:53], v[192:195], v[200:203], v[50:53]
	v_mfma_f32_16x16x32_bf16 v[42:45], v[184:187], v[208:211], v[42:45]
	v_mfma_f32_16x16x32_bf16 v[34:37], v[192:195], v[208:211], v[34:37]
	v_mfma_f32_16x16x32_bf16 v[26:29], v[184:187], v[216:219], v[26:29]
	v_mfma_f32_16x16x32_bf16 v[18:21], v[192:195], v[216:219], v[18:21]
	v_mfma_f32_16x16x32_bf16 v[10:13], v[184:187], v[224:227], v[10:13]
	v_mfma_f32_16x16x32_bf16 v[2:5], v[192:195], v[224:227], v[2:5]
	v_mfma_f32_16x16x32_bf16 v[58:61], v[188:191], v[204:207], v[58:61]
	v_mfma_f32_16x16x32_bf16 v[50:53], v[196:199], v[204:207], v[50:53]
	v_mfma_f32_16x16x32_bf16 v[42:45], v[188:191], v[212:215], v[42:45]
	v_mfma_f32_16x16x32_bf16 v[34:37], v[196:199], v[212:215], v[34:37]
	v_mfma_f32_16x16x32_bf16 v[26:29], v[188:191], v[220:223], v[26:29]
	v_mfma_f32_16x16x32_bf16 v[18:21], v[196:199], v[220:223], v[18:21]
	v_mfma_f32_16x16x32_bf16 v[10:13], v[188:191], v[228:231], v[10:13]
	v_mfma_f32_16x16x32_bf16 v[2:5], v[196:199], v[228:231], v[2:5]
	s_barrier
	s_setprio 0
	s_add_i32 s38, s38, 2
	s_add_u32 s36, s36, 0x100
	s_addc_u32 s37, s37, 0
	s_cmp_gt_u32 s38, 13
	s_mov_b64 s[12:13], s[14:15]
.LBB0_1050:
	s_add_u32 s14, s12, 0x100
	s_addc_u32 s15, s13, 0
	s_add_i32 s39, 0, 0x10000
	s_cmp_eq_u32 s38, 12
	s_cselect_b32 s19, s1, s15
	s_cselect_b32 s18, s0, s14
	v_add_u32_e32 v144, s39, v139
	s_cselect_b32 s17, s11, s37
	s_cselect_b32 s16, s10, s36
	s_add_i32 s40, 0, 0x14000
	ds_read_b128 v[164:167], v144
	ds_read_b128 v[168:171], v144 offset:1024
	ds_read_b128 v[172:175], v144 offset:2048
	ds_read_b128 v[176:179], v144 offset:3072
	v_add_u32_e32 v144, s40, v139
	ds_read_b128 v[184:187], v144
	ds_read_b128 v[188:191], v144 offset:1024
	ds_read_b128 v[192:195], v144 offset:2048
	ds_read_b128 v[196:199], v144 offset:3072
	v_lshl_add_u64 v[160:161], s[12:13], 0, v[156:157]
	s_add_i32 m0, s23, 0xc000
	ds_read_b128 v[200:203], v163
	ds_read_b128 v[204:207], v163 offset:1024
	ds_read_b128 v[208:211], v163 offset:2048
	ds_read_b128 v[212:215], v163 offset:3072
	ds_read_b128 v[216:219], v163 offset:4096
	ds_read_b128 v[220:223], v163 offset:5120
	ds_read_b128 v[224:227], v163 offset:6144
	ds_read_b128 v[228:231], v163 offset:7168
	global_load_lds_dwordx4 v[160:161], off
	s_add_i32 m0, s23, 0xe000
	v_lshl_add_u64 v[160:161], s[12:13], 0, v[158:159]
	global_load_lds_dwordx4 v[160:161], off
	s_setprio 1
	s_waitcnt vmcnt(8) lgkmcnt(0)
	s_barrier
; #define PG8_STAGE(bufoff, gbase, voff) do { _Pragma("unroll") for (int _i = 0; _i < 2; ++_i) \
;         __builtin_amdgcn_global_load_lds((const unsigned*)((const char*)(gbase) + (voff)[_i]), (LAS unsigned*)(lds + (bufoff) + ldsw + _i * 8192), 16, 0, 0); } while (0)
; #define PG8_LDA(dst, b, h) do { _Pragma("unroll") for (int m = 0; m < 4; ++m) _Pragma("unroll") for (int k = 0; k < 2; ++k) dst[m][k] = *(const LAS bf16x8*)(lds + PG8_SA(b, h) + aoff + m * 2048 + k * 1024); } while (0)
; #define PG8_MMA(ai, bj, At, Bt) do { __builtin_amdgcn_s_setprio(1); _Pragma("unroll") for (int m = 0; m < 4; ++m) _Pragma("unroll") for (int n = 0; n < 2; ++n) _Pragma("unroll") for (int k = 0; k < 2; ++k) \
;         acc[ai][bj][m][n] = __builtin_amdgcn_mfma_f32_16x16x32_bf16(Bt[n][k], At[m][k], acc[ai][bj][m][n], 0, 0, 0); __builtin_amdgcn_s_setprio(0); } while (0)
; #define PG8_WAIT_V(n) asm volatile("s_waitcnt vmcnt(" #n ")" ::: "memory")
; #define PG8_WAIT_L(n) asm volatile("s_waitcnt lgkmcnt(" #n ")" ::: "memory")
; #define PG8_BAR __builtin_amdgcn_s_barrier()
; #define PG8_SCHED __builtin_amdgcn_sched_barrier(0)
; template <class Epi, bool ALIGN_EPI = PG8_ALIGN, bool SP2 = PG8_SP2>
; __device__ __forceinline__ void gemm_phase(LAS uchar* lds, const Gemm g, const StaticOrder& S, const Epi& E) {
;     ...
;             PG8_WAIT_V(8); PG8_WAIT_L(0); PG8_BAR; PG8_MMA(0, 0, At, B0); PG8_MMA(0, 1, At, B1); PG8_BAR; PG8_SCHED;
;             PG8_LDA(At, 0, 1); PG8_STAGE(PG8_SB(0, 0), b2, voffB); PG8_STAGE(PG8_SB(0, 1), b2 + hstepB, voffB); PG8_STAGE(PG8_SA(0, 0), a2, voffA);
;             PG8_WAIT_V(8); PG8_WAIT_L(0); PG8_BAR; PG8_MMA(1, 0, At, B0); PG8_MMA(1, 1, At, B1); PG8_BAR; PG8_SCHED;
	v_mfma_f32_16x16x32_bf16 v[126:129], v[164:167], v[200:203], v[126:129]
	v_mfma_f32_16x16x32_bf16 v[118:121], v[172:175], v[200:203], v[118:121]
	v_mfma_f32_16x16x32_bf16 v[110:113], v[164:167], v[208:211], v[110:113]
	v_mfma_f32_16x16x32_bf16 v[102:105], v[172:175], v[208:211], v[102:105]
	v_mfma_f32_16x16x32_bf16 v[94:97], v[164:167], v[216:219], v[94:97]
	v_mfma_f32_16x16x32_bf16 v[86:89], v[172:175], v[216:219], v[86:89]
	v_mfma_f32_16x16x32_bf16 v[78:81], v[164:167], v[224:227], v[78:81]
	v_mfma_f32_16x16x32_bf16 v[70:73], v[172:175], v[224:227], v[70:73]
	v_mfma_f32_16x16x32_bf16 v[126:129], v[168:171], v[204:207], v[126:129]
	v_mfma_f32_16x16x32_bf16 v[118:121], v[176:179], v[204:207], v[118:121]
	v_mfma_f32_16x16x32_bf16 v[110:113], v[168:171], v[212:215], v[110:113]
	v_mfma_f32_16x16x32_bf16 v[102:105], v[176:179], v[212:215], v[102:105]
	v_mfma_f32_16x16x32_bf16 v[94:97], v[168:171], v[220:223], v[94:97]
	v_mfma_f32_16x16x32_bf16 v[86:89], v[176:179], v[220:223], v[86:89]
	v_mfma_f32_16x16x32_bf16 v[78:81], v[168:171], v[228:231], v[78:81]
	v_mfma_f32_16x16x32_bf16 v[70:73], v[176:179], v[228:231], v[70:73]
	v_mfma_f32_16x16x32_bf16 v[122:125], v[184:187], v[200:203], v[122:125]
	v_mfma_f32_16x16x32_bf16 v[114:117], v[192:195], v[200:203], v[114:117]
	v_mfma_f32_16x16x32_bf16 v[106:109], v[184:187], v[208:211], v[106:109]
	v_mfma_f32_16x16x32_bf16 v[98:101], v[192:195], v[208:211], v[98:101]
	v_mfma_f32_16x16x32_bf16 v[90:93], v[184:187], v[216:219], v[90:93]
	v_mfma_f32_16x16x32_bf16 v[82:85], v[192:195], v[216:219], v[82:85]
	v_mfma_f32_16x16x32_bf16 v[74:77], v[184:187], v[224:227], v[74:77]
	v_mfma_f32_16x16x32_bf16 v[66:69], v[192:195], v[224:227], v[66:69]
	v_mfma_f32_16x16x32_bf16 v[122:125], v[188:191], v[204:207], v[122:125]
	v_mfma_f32_16x16x32_bf16 v[114:117], v[196:199], v[204:207], v[114:117]
	v_mfma_f32_16x16x32_bf16 v[106:109], v[188:191], v[212:215], v[106:109]
	v_mfma_f32_16x16x32_bf16 v[98:101], v[196:199], v[212:215], v[98:101]
	v_mfma_f32_16x16x32_bf16 v[90:93], v[188:191], v[220:223], v[90:93]
	v_mfma_f32_16x16x32_bf16 v[82:85], v[196:199], v[220:223], v[82:85]
	v_mfma_f32_16x16x32_bf16 v[74:77], v[188:191], v[228:231], v[74:77]
	v_mfma_f32_16x16x32_bf16 v[66:69], v[196:199], v[228:231], v[66:69]
	s_barrier
	s_setprio 0
	s_add_i32 s12, s39, s21
	v_lshl_add_u64 v[160:161], s[16:17], 0, v[134:135]
	s_mov_b32 m0, s12
	ds_read_b128 v[200:203], v163 offset:16384
	ds_read_b128 v[204:207], v163 offset:17408
	ds_read_b128 v[208:211], v163 offset:18432
	ds_read_b128 v[212:215], v163 offset:19456
	ds_read_b128 v[216:219], v163 offset:20480
	ds_read_b128 v[220:223], v163 offset:21504
	ds_read_b128 v[224:227], v163 offset:22528
	ds_read_b128 v[228:231], v163 offset:23552
	global_load_lds_dwordx4 v[160:161], off
	s_add_i32 m0, s12, 0x2000
	s_add_u32 s12, s16, 0x44000
	v_lshl_add_u64 v[180:181], s[16:17], 0, v[130:131]
	s_addc_u32 s13, s17, 0
	s_add_i32 s39, s40, s21
	global_load_lds_dwordx4 v[180:181], off
	v_lshl_add_u64 v[232:233], s[12:13], 0, v[134:135]
	s_mov_b32 m0, s39
	global_load_lds_dwordx4 v[232:233], off
	s_add_i32 m0, s39, 0x2000
	v_lshl_add_u64 v[232:233], s[12:13], 0, v[130:131]
	global_load_lds_dwordx4 v[232:233], off
	s_mov_b32 m0, s23
	v_lshl_add_u64 v[232:233], s[18:19], 0, v[154:155]
	global_load_lds_dwordx4 v[232:233], off
	s_mov_b32 m0, s24
	v_lshl_add_u64 v[234:235], s[18:19], 0, v[132:133]
	global_load_lds_dwordx4 v[234:235], off
	s_setprio 1
	s_waitcnt vmcnt(8) lgkmcnt(0)
	s_barrier
	v_mfma_f32_16x16x32_bf16 v[62:65], v[164:167], v[200:203], v[62:65]
	v_mfma_f32_16x16x32_bf16 v[54:57], v[172:175], v[200:203], v[54:57]
	v_mfma_f32_16x16x32_bf16 v[46:49], v[164:167], v[208:211], v[46:49]
	v_mfma_f32_16x16x32_bf16 v[38:41], v[172:175], v[208:211], v[38:41]
	v_mfma_f32_16x16x32_bf16 v[30:33], v[164:167], v[216:219], v[30:33]
	v_mfma_f32_16x16x32_bf16 v[22:25], v[172:175], v[216:219], v[22:25]
	v_mfma_f32_16x16x32_bf16 v[14:17], v[164:167], v[224:227], v[14:17]
	v_mfma_f32_16x16x32_bf16 v[6:9], v[172:175], v[224:227], v[6:9]
	v_mfma_f32_16x16x32_bf16 v[62:65], v[168:171], v[204:207], v[62:65]
	v_mfma_f32_16x16x32_bf16 v[54:57], v[176:179], v[204:207], v[54:57]
	v_mfma_f32_16x16x32_bf16 v[46:49], v[168:171], v[212:215], v[46:49]
	v_mfma_f32_16x16x32_bf16 v[38:41], v[176:179], v[212:215], v[38:41]
	v_mfma_f32_16x16x32_bf16 v[30:33], v[168:171], v[220:223], v[30:33]
	v_mfma_f32_16x16x32_bf16 v[22:25], v[176:179], v[220:223], v[22:25]
	v_mfma_f32_16x16x32_bf16 v[14:17], v[168:171], v[228:231], v[14:17]
	v_mfma_f32_16x16x32_bf16 v[6:9], v[176:179], v[228:231], v[6:9]
	v_mfma_f32_16x16x32_bf16 v[58:61], v[184:187], v[200:203], v[58:61]
	v_mfma_f32_16x16x32_bf16 v[50:53], v[192:195], v[200:203], v[50:53]
	v_mfma_f32_16x16x32_bf16 v[42:45], v[184:187], v[208:211], v[42:45]
	v_mfma_f32_16x16x32_bf16 v[34:37], v[192:195], v[208:211], v[34:37]
	v_mfma_f32_16x16x32_bf16 v[26:29], v[184:187], v[216:219], v[26:29]
	v_mfma_f32_16x16x32_bf16 v[18:21], v[192:195], v[216:219], v[18:21]
	v_mfma_f32_16x16x32_bf16 v[10:13], v[184:187], v[224:227], v[10:13]
	v_mfma_f32_16x16x32_bf16 v[2:5], v[192:195], v[224:227], v[2:5]
	v_mfma_f32_16x16x32_bf16 v[58:61], v[188:191], v[204:207], v[58:61]
	v_mfma_f32_16x16x32_bf16 v[50:53], v[196:199], v[204:207], v[50:53]
	v_mfma_f32_16x16x32_bf16 v[42:45], v[188:191], v[212:215], v[42:45]
	v_mfma_f32_16x16x32_bf16 v[34:37], v[196:199], v[212:215], v[34:37]
	v_mfma_f32_16x16x32_bf16 v[26:29], v[188:191], v[220:223], v[26:29]
	v_mfma_f32_16x16x32_bf16 v[18:21], v[196:199], v[220:223], v[18:21]
	v_mfma_f32_16x16x32_bf16 v[10:13], v[188:191], v[228:231], v[10:13]
	v_mfma_f32_16x16x32_bf16 v[2:5], v[196:199], v[228:231], v[2:5]
	s_barrier
; #define PG8_STAGE(bufoff, gbase, voff) do { _Pragma("unroll") for (int _i = 0; _i < 2; ++_i) \
;         __builtin_amdgcn_global_load_lds((const unsigned*)((const char*)(gbase) + (voff)[_i]), (LAS unsigned*)(lds + (bufoff) + ldsw + _i * 8192), 16, 0, 0); } while (0)
; #define PG8_LDA(dst, b, h) do { _Pragma("unroll") for (int m = 0; m < 4; ++m) _Pragma("unroll") for (int k = 0; k < 2; ++k) dst[m][k] = *(const LAS bf16x8*)(lds + PG8_SA(b, h) + aoff + m * 2048 + k * 1024); } while (0)
; #define PG8_LDB(dst, b, h) do { _Pragma("unroll") for (int n = 0; n < 2; ++n) _Pragma("unroll") for (int k = 0; k < 2; ++k) dst[n][k] = *(const LAS bf16x8*)(lds + PG8_SB(b, h) + boff + n * 2048 + k * 1024); } while (0)
; #define PG8_MMA(ai, bj, At, Bt) do { __builtin_amdgcn_s_setprio(1); _Pragma("unroll") for (int m = 0; m < 4; ++m) _Pragma("unroll") for (int n = 0; n < 2; ++n) _Pragma("unroll") for (int k = 0; k < 2; ++k) \
;         acc[ai][bj][m][n] = __builtin_amdgcn_mfma_f32_16x16x32_bf16(Bt[n][k], At[m][k], acc[ai][bj][m][n], 0, 0, 0); __builtin_amdgcn_s_setprio(0); } while (0)
; #define PG8_WAIT_V(n) asm volatile("s_waitcnt vmcnt(" #n ")" ::: "memory")
; #define PG8_WAIT_L(n) asm volatile("s_waitcnt lgkmcnt(" #n ")" ::: "memory")
; #define PG8_BAR __builtin_amdgcn_s_barrier()
; #define PG8_SCHED __builtin_amdgcn_sched_barrier(0)
; template <class Epi, bool ALIGN_EPI = PG8_ALIGN, bool SP2 = PG8_SP2>
; __device__ __forceinline__ void gemm_phase(LAS uchar* lds, const Gemm g, const StaticOrder& S, const Epi& E) {
;     ...
;             PG8_WAIT_V(8); PG8_WAIT_L(0); PG8_BAR; PG8_MMA(1, 0, At, B0); PG8_MMA(1, 1, At, B1); PG8_BAR; PG8_SCHED;
;             PG8_LDB(B0, 1, 0); PG8_LDB(B1, 1, 1); PG8_SCHED; PG8_LDA(At, 1, 0); PG8_STAGE(PG8_SA(0, 1), a2 + hstepA, voffA);
;             PG8_WAIT_V(8); PG8_WAIT_L(0); PG8_BAR; PG8_MMA(0, 0, At, B0); PG8_MMA(0, 1, At, B1); PG8_BAR; PG8_SCHED;
	s_setprio 0
	s_add_i32 s39, 0, 0x18000
	v_add_u32_e32 v144, s39, v139
	s_add_i32 s40, 0, 0x1c000
	ds_read_b128 v[164:167], v144
	ds_read_b128 v[168:171], v144 offset:1024
	ds_read_b128 v[172:175], v144 offset:2048
	ds_read_b128 v[176:179], v144 offset:3072
	v_add_u32_e32 v144, s40, v139
	ds_read_b128 v[184:187], v144
	ds_read_b128 v[188:191], v144 offset:1024
	ds_read_b128 v[192:195], v144 offset:2048
	ds_read_b128 v[196:199], v144 offset:3072
	s_add_u32 s12, s18, 0x44000
	s_addc_u32 s13, s19, 0
	s_mov_b32 m0, s25
	v_lshl_add_u64 v[236:237], s[12:13], 0, v[154:155]
	ds_read_b128 v[200:203], v163 offset:32768
	ds_read_b128 v[204:207], v163 offset:33792
	ds_read_b128 v[208:211], v163 offset:34816
	ds_read_b128 v[212:215], v163 offset:35840
	ds_read_b128 v[216:219], v163 offset:36864
	ds_read_b128 v[220:223], v163 offset:37888
	ds_read_b128 v[224:227], v163 offset:38912
	ds_read_b128 v[228:231], v163 offset:39936
	global_load_lds_dwordx4 v[236:237], off
	s_mov_b32 m0, s26
	v_lshl_add_u64 v[236:237], s[12:13], 0, v[132:133]
	global_load_lds_dwordx4 v[236:237], off
	s_setprio 1
	s_waitcnt vmcnt(8) lgkmcnt(0)
	s_barrier
	v_mfma_f32_16x16x32_bf16 v[126:129], v[164:167], v[200:203], v[126:129]
	v_mfma_f32_16x16x32_bf16 v[118:121], v[172:175], v[200:203], v[118:121]
	v_mfma_f32_16x16x32_bf16 v[110:113], v[164:167], v[208:211], v[110:113]
	v_mfma_f32_16x16x32_bf16 v[102:105], v[172:175], v[208:211], v[102:105]
	v_mfma_f32_16x16x32_bf16 v[94:97], v[164:167], v[216:219], v[94:97]
	v_mfma_f32_16x16x32_bf16 v[86:89], v[172:175], v[216:219], v[86:89]
	v_mfma_f32_16x16x32_bf16 v[78:81], v[164:167], v[224:227], v[78:81]
	v_mfma_f32_16x16x32_bf16 v[70:73], v[172:175], v[224:227], v[70:73]
	v_mfma_f32_16x16x32_bf16 v[126:129], v[168:171], v[204:207], v[126:129]
	v_mfma_f32_16x16x32_bf16 v[118:121], v[176:179], v[204:207], v[118:121]
	v_mfma_f32_16x16x32_bf16 v[110:113], v[168:171], v[212:215], v[110:113]
	v_mfma_f32_16x16x32_bf16 v[102:105], v[176:179], v[212:215], v[102:105]
	v_mfma_f32_16x16x32_bf16 v[94:97], v[168:171], v[220:223], v[94:97]
	v_mfma_f32_16x16x32_bf16 v[86:89], v[176:179], v[220:223], v[86:89]
	v_mfma_f32_16x16x32_bf16 v[78:81], v[168:171], v[228:231], v[78:81]
	v_mfma_f32_16x16x32_bf16 v[70:73], v[176:179], v[228:231], v[70:73]
	v_mfma_f32_16x16x32_bf16 v[122:125], v[184:187], v[200:203], v[122:125]
	v_mfma_f32_16x16x32_bf16 v[114:117], v[192:195], v[200:203], v[114:117]
	v_mfma_f32_16x16x32_bf16 v[106:109], v[184:187], v[208:211], v[106:109]
	v_mfma_f32_16x16x32_bf16 v[98:101], v[192:195], v[208:211], v[98:101]
	v_mfma_f32_16x16x32_bf16 v[90:93], v[184:187], v[216:219], v[90:93]
	v_mfma_f32_16x16x32_bf16 v[82:85], v[192:195], v[216:219], v[82:85]
	v_mfma_f32_16x16x32_bf16 v[74:77], v[184:187], v[224:227], v[74:77]
	v_mfma_f32_16x16x32_bf16 v[66:69], v[192:195], v[224:227], v[66:69]
	v_mfma_f32_16x16x32_bf16 v[122:125], v[188:191], v[204:207], v[122:125]
	v_mfma_f32_16x16x32_bf16 v[114:117], v[196:199], v[204:207], v[114:117]
	v_mfma_f32_16x16x32_bf16 v[106:109], v[188:191], v[212:215], v[106:109]
	v_mfma_f32_16x16x32_bf16 v[98:101], v[196:199], v[212:215], v[98:101]
	v_mfma_f32_16x16x32_bf16 v[90:93], v[188:191], v[220:223], v[90:93]
	v_mfma_f32_16x16x32_bf16 v[82:85], v[196:199], v[220:223], v[82:85]
	v_mfma_f32_16x16x32_bf16 v[74:77], v[188:191], v[228:231], v[74:77]
	v_mfma_f32_16x16x32_bf16 v[66:69], v[196:199], v[228:231], v[66:69]
	s_barrier
; #define PG8_STAGE(bufoff, gbase, voff) do { _Pragma("unroll") for (int _i = 0; _i < 2; ++_i) \
;         __builtin_amdgcn_global_load_lds((const unsigned*)((const char*)(gbase) + (voff)[_i]), (LAS unsigned*)(lds + (bufoff) + ldsw + _i * 8192), 16, 0, 0); } while (0)
; #define PG8_LDA(dst, b, h) do { _Pragma("unroll") for (int m = 0; m < 4; ++m) _Pragma("unroll") for (int k = 0; k < 2; ++k) dst[m][k] = *(const LAS bf16x8*)(lds + PG8_SA(b, h) + aoff + m * 2048 + k * 1024); } while (0)
; #define PG8_MMA(ai, bj, At, Bt) do { __builtin_amdgcn_s_setprio(1); _Pragma("unroll") for (int m = 0; m < 4; ++m) _Pragma("unroll") for (int n = 0; n < 2; ++n) _Pragma("unroll") for (int k = 0; k < 2; ++k) \
;         acc[ai][bj][m][n] = __builtin_amdgcn_mfma_f32_16x16x32_bf16(Bt[n][k], At[m][k], acc[ai][bj][m][n], 0, 0, 0); __builtin_amdgcn_s_setprio(0); } while (0)
; #define PG8_WAIT_V(n) asm volatile("s_waitcnt vmcnt(" #n ")" ::: "memory")
; #define PG8_WAIT_L(n) asm volatile("s_waitcnt lgkmcnt(" #n ")" ::: "memory")
; #define PG8_BAR __builtin_amdgcn_s_barrier()
; #define PG8_SCHED __builtin_amdgcn_sched_barrier(0)
; template <class Epi, bool ALIGN_EPI = PG8_ALIGN, bool SP2 = PG8_SP2>
; __device__ __forceinline__ void gemm_phase(LAS uchar* lds, const Gemm g, const StaticOrder& S, const Epi& E) {
;     ...
;             PG8_WAIT_V(8); PG8_WAIT_L(0); PG8_BAR; PG8_MMA(0, 0, At, B0); PG8_MMA(0, 1, At, B1); PG8_BAR; PG8_SCHED;
;             PG8_LDA(At, 1, 1); PG8_STAGE(PG8_SB(1, 0), b3, voffB); PG8_STAGE(PG8_SB(1, 1), b3 + hstepB, voffB); PG8_STAGE(PG8_SA(1, 0), a3, voffA);
;             PG8_WAIT_V(8); PG8_WAIT_L(0); PG8_BAR; PG8_MMA(1, 0, At, B0); PG8_MMA(1, 1, At, B1); PG8_BAR; PG8_SCHED;
;     ...
;         if constexpr (ALIGN_EPI) { if (wr == 0) PG8_BAR; }
	s_setprio 0
	s_add_i32 s12, s39, s21
	v_lshl_add_u64 v[160:161], v[160:161], 0, s[84:85]
	s_mov_b32 m0, s12
	ds_read_b128 v[200:203], v163 offset:49152
	ds_read_b128 v[204:207], v163 offset:50176
	ds_read_b128 v[208:211], v163 offset:51200
	ds_read_b128 v[212:215], v163 offset:52224
	ds_read_b128 v[216:219], v163 offset:53248
	ds_read_b128 v[220:223], v163 offset:54272
	ds_read_b128 v[224:227], v163 offset:55296
	ds_read_b128 v[228:231], v163 offset:56320
	global_load_lds_dwordx4 v[160:161], off
	s_add_i32 m0, s12, 0x2000
	s_add_u32 s12, s16, 0x44080
	v_lshl_add_u64 v[160:161], v[180:181], 0, s[84:85]
	s_addc_u32 s13, s17, 0
	s_add_i32 s16, s40, s21
	global_load_lds_dwordx4 v[160:161], off
	s_mov_b32 m0, s16
	v_lshl_add_u64 v[160:161], s[12:13], 0, v[134:135]
	global_load_lds_dwordx4 v[160:161], off
	s_add_i32 m0, s16, 0x2000
	v_lshl_add_u64 v[160:161], s[12:13], 0, v[130:131]
	global_load_lds_dwordx4 v[160:161], off
	s_mov_b32 m0, s27
	v_lshl_add_u64 v[160:161], v[232:233], 0, s[84:85]
	global_load_lds_dwordx4 v[160:161], off
	s_mov_b32 m0, s28
	v_lshl_add_u64 v[160:161], v[234:235], 0, s[84:85]
	global_load_lds_dwordx4 v[160:161], off
	s_setprio 1
	s_waitcnt vmcnt(8) lgkmcnt(0)
	s_barrier
	v_mfma_f32_16x16x32_bf16 v[62:65], v[164:167], v[200:203], v[62:65]
	v_mfma_f32_16x16x32_bf16 v[54:57], v[172:175], v[200:203], v[54:57]
	v_mfma_f32_16x16x32_bf16 v[46:49], v[164:167], v[208:211], v[46:49]
	v_mfma_f32_16x16x32_bf16 v[38:41], v[172:175], v[208:211], v[38:41]
	v_mfma_f32_16x16x32_bf16 v[30:33], v[164:167], v[216:219], v[30:33]
	v_mfma_f32_16x16x32_bf16 v[22:25], v[172:175], v[216:219], v[22:25]
	v_mfma_f32_16x16x32_bf16 v[14:17], v[164:167], v[224:227], v[14:17]
	v_mfma_f32_16x16x32_bf16 v[6:9], v[172:175], v[224:227], v[6:9]
	v_mfma_f32_16x16x32_bf16 v[62:65], v[168:171], v[204:207], v[62:65]
	v_mfma_f32_16x16x32_bf16 v[54:57], v[176:179], v[204:207], v[54:57]
	v_mfma_f32_16x16x32_bf16 v[46:49], v[168:171], v[212:215], v[46:49]
	v_mfma_f32_16x16x32_bf16 v[38:41], v[176:179], v[212:215], v[38:41]
	v_mfma_f32_16x16x32_bf16 v[30:33], v[168:171], v[220:223], v[30:33]
	v_mfma_f32_16x16x32_bf16 v[22:25], v[176:179], v[220:223], v[22:25]
	v_mfma_f32_16x16x32_bf16 v[14:17], v[168:171], v[228:231], v[14:17]
	v_mfma_f32_16x16x32_bf16 v[6:9], v[176:179], v[228:231], v[6:9]
	v_mfma_f32_16x16x32_bf16 v[58:61], v[184:187], v[200:203], v[58:61]
	v_mfma_f32_16x16x32_bf16 v[50:53], v[192:195], v[200:203], v[50:53]
	v_mfma_f32_16x16x32_bf16 v[42:45], v[184:187], v[208:211], v[42:45]
	v_mfma_f32_16x16x32_bf16 v[34:37], v[192:195], v[208:211], v[34:37]
	v_mfma_f32_16x16x32_bf16 v[26:29], v[184:187], v[216:219], v[26:29]
	v_mfma_f32_16x16x32_bf16 v[18:21], v[192:195], v[216:219], v[18:21]
	v_mfma_f32_16x16x32_bf16 v[10:13], v[184:187], v[224:227], v[10:13]
	v_mfma_f32_16x16x32_bf16 v[2:5], v[192:195], v[224:227], v[2:5]
	v_mfma_f32_16x16x32_bf16 v[58:61], v[188:191], v[204:207], v[58:61]
	v_mfma_f32_16x16x32_bf16 v[50:53], v[196:199], v[204:207], v[50:53]
	v_mfma_f32_16x16x32_bf16 v[42:45], v[188:191], v[212:215], v[42:45]
	v_mfma_f32_16x16x32_bf16 v[34:37], v[196:199], v[212:215], v[34:37]
	v_mfma_f32_16x16x32_bf16 v[26:29], v[188:191], v[220:223], v[26:29]
	v_mfma_f32_16x16x32_bf16 v[18:21], v[196:199], v[220:223], v[18:21]
	v_mfma_f32_16x16x32_bf16 v[10:13], v[188:191], v[228:231], v[10:13]
	v_mfma_f32_16x16x32_bf16 v[2:5], v[196:199], v[228:231], v[2:5]
	s_barrier
	s_setprio 0
	s_add_i32 s38, s38, 2
	s_add_u32 s36, s36, 0x100
	s_addc_u32 s37, s37, 0
	s_cmp_gt_u32 s38, 13
	s_mov_b64 s[12:13], s[14:15]
	s_cbranch_scc0 .LBB0_1050
	s_and_b64 vcc, exec, s[8:9]
	s_cbranch_vccz .LBB0_1053
	s_barrier

; #define PG8_STAGE(bufoff, gbase, voff) do { _Pragma("unroll") for (int _i = 0; _i < 2; ++_i) \
;         __builtin_amdgcn_global_load_lds((const unsigned*)((const char*)(gbase) + (voff)[_i]), (LAS unsigned*)(lds + (bufoff) + ldsw + _i * 8192), 16, 0, 0); } while (0)
; #define PG8_LDA(dst, b, h) do { _Pragma("unroll") for (int m = 0; m < 4; ++m) _Pragma("unroll") for (int k = 0; k < 2; ++k) dst[m][k] = *(const LAS bf16x8*)(lds + PG8_SA(b, h) + aoff + m * 2048 + k * 1024); } while (0)
; #define PG8_LDB(dst, b, h) do { _Pragma("unroll") for (int n = 0; n < 2; ++n) _Pragma("unroll") for (int k = 0; k < 2; ++k) dst[n][k] = *(const LAS bf16x8*)(lds + PG8_SB(b, h) + boff + n * 2048 + k * 1024); } while (0)
; #define PG8_MMA(ai, bj, At, Bt) do { __builtin_amdgcn_s_setprio(1); _Pragma("unroll") for (int m = 0; m < 4; ++m) _Pragma("unroll") for (int n = 0; n < 2; ++n) _Pragma("unroll") for (int k = 0; k < 2; ++k) \
;         acc[ai][bj][m][n] = __builtin_amdgcn_mfma_f32_16x16x32_bf16(Bt[n][k], At[m][k], acc[ai][bj][m][n], 0, 0, 0); __builtin_amdgcn_s_setprio(0); } while (0)
; #define PG8_WAIT_V(n) asm volatile("s_waitcnt vmcnt(" #n ")" ::: "memory")
; #define PG8_WAIT_L(n) asm volatile("s_waitcnt lgkmcnt(" #n ")" ::: "memory")
; #define PG8_BAR __builtin_amdgcn_s_barrier()
; template <class Epi, bool ALIGN_EPI = PG8_ALIGN, bool SP2 = PG8_SP2>
; __device__ __forceinline__ void gemm_phase(LAS uchar* lds, const Gemm g, const StaticOrder& S, const Epi& E) {
;     ...
;         for (int t = tb; t < tb + tblk; t += 2) {
;             const bool last = (t == nt - 2);
;             const char* a1 = cA + (size_t)(t + 1) * kstep;
;             const char* a2 = last ? nA : cA + (size_t)(t + 2) * kstep; const char* b2 = last ? nB : cB + (size_t)(t + 2) * kstep;
;             const char* a3 = a2 + kstep; const char* b3 = b2 + kstep;
;             if constexpr (SP2) {
;             PG8_LDB(B0, 0, 0); PG8_LDB(B1, 0, 1); PG8_SCHED; PG8_LDA(At, 0, 0); PG8_STAGE(PG8_SA(1, 1), a1 + hstepA, voffA);
;             PG8_WAIT_V(8); PG8_WAIT_L(0); PG8_BAR; PG8_MMA(0, 0, At, B0); PG8_MMA(0, 1, At, B1); PG8_BAR; PG8_SCHED;
;             PG8_LDA(At, 0, 1); PG8_STAGE(PG8_SB(0, 0), b2, voffB); PG8_STAGE(PG8_SB(0, 1), b2 + hstepB, voffB); PG8_STAGE(PG8_SA(0, 0), a2, voffA);
;             PG8_WAIT_V(8); PG8_WAIT_L(0); PG8_BAR; PG8_MMA(1, 0, At, B0); PG8_MMA(1, 1, At, B1); PG8_BAR; PG8_SCHED;
.LBB0_1142:
	s_add_u32 s38, s16, 0x100
	s_addc_u32 s39, s17, 0
	s_mov_b32 s40, -2
	s_add_u32 s16, s14, 0x100
	s_addc_u32 s17, s15, 0
	s_add_i32 s41, 0, 0x10000
	s_cmp_eq_u32 s40, 40
	s_cselect_b32 s21, s5, s17
	s_cselect_b32 s20, s4, s16
	v_add_u32_e32 v144, s41, v139
	s_cselect_b32 s19, s13, s39
	s_cselect_b32 s18, s12, s38
	s_add_i32 s42, 0, 0x14000
	ds_read_b128 v[160:163], v144
	ds_read_b128 v[166:169], v144 offset:1024
	ds_read_b128 v[170:173], v144 offset:2048
	ds_read_b128 v[174:177], v144 offset:3072
	v_add_u32_e32 v144, s42, v139
	ds_read_b128 v[178:181], v144
	ds_read_b128 v[184:187], v144 offset:1024
	ds_read_b128 v[188:191], v144 offset:2048
	ds_read_b128 v[192:195], v144 offset:3072
	v_lshl_add_u64 v[228:229], s[14:15], 0, v[156:157]
	s_add_i32 m0, s25, 0xc000
	ds_read_b128 v[196:199], v165
	ds_read_b128 v[200:203], v165 offset:1024
	ds_read_b128 v[204:207], v165 offset:2048
	ds_read_b128 v[208:211], v165 offset:3072
	ds_read_b128 v[212:215], v165 offset:4096
	ds_read_b128 v[216:219], v165 offset:5120
	ds_read_b128 v[220:223], v165 offset:6144
	ds_read_b128 v[224:227], v165 offset:7168
	global_load_lds_dwordx4 v[228:229], off
	s_add_i32 m0, s25, 0xe000
	v_lshl_add_u64 v[228:229], s[14:15], 0, v[158:159]
	global_load_lds_dwordx4 v[228:229], off
	s_setprio 1
	s_waitcnt vmcnt(8) lgkmcnt(0)
	s_barrier
	v_mfma_f32_16x16x32_bf16 v[126:129], v[160:163], v[196:199], 0
	v_mfma_f32_16x16x32_bf16 v[122:125], v[170:173], v[196:199], 0
	v_mfma_f32_16x16x32_bf16 v[118:121], v[160:163], v[204:207], 0
	v_mfma_f32_16x16x32_bf16 v[110:113], v[170:173], v[204:207], 0
	v_mfma_f32_16x16x32_bf16 v[102:105], v[160:163], v[212:215], 0
	v_mfma_f32_16x16x32_bf16 v[94:97], v[170:173], v[212:215], 0
	v_mfma_f32_16x16x32_bf16 v[86:89], v[160:163], v[220:223], 0
	v_mfma_f32_16x16x32_bf16 v[78:81], v[170:173], v[220:223], 0
	v_mfma_f32_16x16x32_bf16 v[126:129], v[166:169], v[200:203], v[126:129]
	v_mfma_f32_16x16x32_bf16 v[122:125], v[174:177], v[200:203], v[122:125]
	v_mfma_f32_16x16x32_bf16 v[118:121], v[166:169], v[208:211], v[118:121]
	v_mfma_f32_16x16x32_bf16 v[110:113], v[174:177], v[208:211], v[110:113]
	v_mfma_f32_16x16x32_bf16 v[102:105], v[166:169], v[216:219], v[102:105]
	v_mfma_f32_16x16x32_bf16 v[94:97], v[174:177], v[216:219], v[94:97]
	v_mfma_f32_16x16x32_bf16 v[86:89], v[166:169], v[224:227], v[86:89]
	v_mfma_f32_16x16x32_bf16 v[78:81], v[174:177], v[224:227], v[78:81]
	v_mfma_f32_16x16x32_bf16 v[114:117], v[178:181], v[196:199], 0
	v_mfma_f32_16x16x32_bf16 v[106:109], v[188:191], v[196:199], 0
	v_mfma_f32_16x16x32_bf16 v[98:101], v[178:181], v[204:207], 0
	v_mfma_f32_16x16x32_bf16 v[90:93], v[188:191], v[204:207], 0
	v_mfma_f32_16x16x32_bf16 v[82:85], v[178:181], v[212:215], 0
	v_mfma_f32_16x16x32_bf16 v[74:77], v[188:191], v[212:215], 0
	v_mfma_f32_16x16x32_bf16 v[70:73], v[178:181], v[220:223], 0
	v_mfma_f32_16x16x32_bf16 v[66:69], v[188:191], v[220:223], 0
	v_mfma_f32_16x16x32_bf16 v[114:117], v[184:187], v[200:203], v[114:117]
	v_mfma_f32_16x16x32_bf16 v[106:109], v[192:195], v[200:203], v[106:109]
	v_mfma_f32_16x16x32_bf16 v[98:101], v[184:187], v[208:211], v[98:101]
	v_mfma_f32_16x16x32_bf16 v[90:93], v[192:195], v[208:211], v[90:93]
	v_mfma_f32_16x16x32_bf16 v[82:85], v[184:187], v[216:219], v[82:85]
	v_mfma_f32_16x16x32_bf16 v[74:77], v[192:195], v[216:219], v[74:77]
	v_mfma_f32_16x16x32_bf16 v[70:73], v[184:187], v[224:227], v[70:73]
	v_mfma_f32_16x16x32_bf16 v[66:69], v[192:195], v[224:227], v[66:69]
	s_barrier
	s_setprio 0
	s_add_i32 s14, s41, s24
	v_lshl_add_u64 v[228:229], s[18:19], 0, v[132:133]
	s_mov_b32 m0, s14
	ds_read_b128 v[196:199], v165 offset:16384
	ds_read_b128 v[200:203], v165 offset:17408
	ds_read_b128 v[204:207], v165 offset:18432
	ds_read_b128 v[208:211], v165 offset:19456
	ds_read_b128 v[212:215], v165 offset:20480
	ds_read_b128 v[216:219], v165 offset:21504
	ds_read_b128 v[220:223], v165 offset:22528
	ds_read_b128 v[224:227], v165 offset:23552
	global_load_lds_dwordx4 v[228:229], off
	s_add_i32 m0, s14, 0x2000
	s_add_u32 s14, s18, 0xb0000
	v_lshl_add_u64 v[230:231], s[18:19], 0, v[154:155]
	s_addc_u32 s15, s19, 0
	s_add_i32 s41, s42, s24
	global_load_lds_dwordx4 v[230:231], off
	v_lshl_add_u64 v[232:233], s[14:15], 0, v[132:133]
	s_mov_b32 m0, s41
	global_load_lds_dwordx4 v[232:233], off
	s_add_i32 m0, s41, 0x2000
	v_lshl_add_u64 v[232:233], s[14:15], 0, v[154:155]
	global_load_lds_dwordx4 v[232:233], off
	s_mov_b32 m0, s25
	v_lshl_add_u64 v[232:233], s[20:21], 0, v[130:131]
	global_load_lds_dwordx4 v[232:233], off
	s_mov_b32 m0, s26
	v_lshl_add_u64 v[234:235], s[20:21], 0, v[134:135]
	global_load_lds_dwordx4 v[234:235], off
	s_setprio 1
	s_waitcnt vmcnt(8) lgkmcnt(0)
	s_barrier
; #define PG8_STAGE(bufoff, gbase, voff) do { _Pragma("unroll") for (int _i = 0; _i < 2; ++_i) \
;         __builtin_amdgcn_global_load_lds((const unsigned*)((const char*)(gbase) + (voff)[_i]), (LAS unsigned*)(lds + (bufoff) + ldsw + _i * 8192), 16, 0, 0); } while (0)
; #define PG8_LDA(dst, b, h) do { _Pragma("unroll") for (int m = 0; m < 4; ++m) _Pragma("unroll") for (int k = 0; k < 2; ++k) dst[m][k] = *(const LAS bf16x8*)(lds + PG8_SA(b, h) + aoff + m * 2048 + k * 1024); } while (0)
; #define PG8_LDB(dst, b, h) do { _Pragma("unroll") for (int n = 0; n < 2; ++n) _Pragma("unroll") for (int k = 0; k < 2; ++k) dst[n][k] = *(const LAS bf16x8*)(lds + PG8_SB(b, h) + boff + n * 2048 + k * 1024); } while (0)
; #define PG8_MMA(ai, bj, At, Bt) do { __builtin_amdgcn_s_setprio(1); _Pragma("unroll") for (int m = 0; m < 4; ++m) _Pragma("unroll") for (int n = 0; n < 2; ++n) _Pragma("unroll") for (int k = 0; k < 2; ++k) \
;         acc[ai][bj][m][n] = __builtin_amdgcn_mfma_f32_16x16x32_bf16(Bt[n][k], At[m][k], acc[ai][bj][m][n], 0, 0, 0); __builtin_amdgcn_s_setprio(0); } while (0)
; #define PG8_WAIT_V(n) asm volatile("s_waitcnt vmcnt(" #n ")" ::: "memory")
; #define PG8_WAIT_L(n) asm volatile("s_waitcnt lgkmcnt(" #n ")" ::: "memory")
; #define PG8_BAR __builtin_amdgcn_s_barrier()
; #define PG8_SCHED __builtin_amdgcn_sched_barrier(0)
; template <class Epi, bool ALIGN_EPI = PG8_ALIGN, bool SP2 = PG8_SP2>
; __device__ __forceinline__ void gemm_phase(LAS uchar* lds, const Gemm g, const StaticOrder& S, const Epi& E) {
;     ...
;             PG8_WAIT_V(8); PG8_WAIT_L(0); PG8_BAR; PG8_MMA(1, 0, At, B0); PG8_MMA(1, 1, At, B1); PG8_BAR; PG8_SCHED;
;             PG8_LDB(B0, 1, 0); PG8_LDB(B1, 1, 1); PG8_SCHED; PG8_LDA(At, 1, 0); PG8_STAGE(PG8_SA(0, 1), a2 + hstepA, voffA);
;             PG8_WAIT_V(8); PG8_WAIT_L(0); PG8_BAR; PG8_MMA(0, 0, At, B0); PG8_MMA(0, 1, At, B1); PG8_BAR; PG8_SCHED;
	v_mfma_f32_16x16x32_bf16 v[62:65], v[160:163], v[196:199], 0
	v_mfma_f32_16x16x32_bf16 v[58:61], v[170:173], v[196:199], 0
	v_mfma_f32_16x16x32_bf16 v[54:57], v[160:163], v[204:207], 0
	v_mfma_f32_16x16x32_bf16 v[46:49], v[170:173], v[204:207], 0
	v_mfma_f32_16x16x32_bf16 v[38:41], v[160:163], v[212:215], 0
	v_mfma_f32_16x16x32_bf16 v[30:33], v[170:173], v[212:215], 0
	v_mfma_f32_16x16x32_bf16 v[22:25], v[160:163], v[220:223], 0
	v_mfma_f32_16x16x32_bf16 v[14:17], v[170:173], v[220:223], 0
	v_mfma_f32_16x16x32_bf16 v[62:65], v[166:169], v[200:203], v[62:65]
	v_mfma_f32_16x16x32_bf16 v[58:61], v[174:177], v[200:203], v[58:61]
	v_mfma_f32_16x16x32_bf16 v[54:57], v[166:169], v[208:211], v[54:57]
	v_mfma_f32_16x16x32_bf16 v[46:49], v[174:177], v[208:211], v[46:49]
	v_mfma_f32_16x16x32_bf16 v[38:41], v[166:169], v[216:219], v[38:41]
	v_mfma_f32_16x16x32_bf16 v[30:33], v[174:177], v[216:219], v[30:33]
	v_mfma_f32_16x16x32_bf16 v[22:25], v[166:169], v[224:227], v[22:25]
	v_mfma_f32_16x16x32_bf16 v[14:17], v[174:177], v[224:227], v[14:17]
	v_mfma_f32_16x16x32_bf16 v[50:53], v[178:181], v[196:199], 0
	v_mfma_f32_16x16x32_bf16 v[42:45], v[188:191], v[196:199], 0
	v_mfma_f32_16x16x32_bf16 v[34:37], v[178:181], v[204:207], 0
	v_mfma_f32_16x16x32_bf16 v[26:29], v[188:191], v[204:207], 0
	v_mfma_f32_16x16x32_bf16 v[18:21], v[178:181], v[212:215], 0
	v_mfma_f32_16x16x32_bf16 v[10:13], v[188:191], v[212:215], 0
	v_mfma_f32_16x16x32_bf16 v[6:9], v[178:181], v[220:223], 0
	v_mfma_f32_16x16x32_bf16 v[2:5], v[188:191], v[220:223], 0
	v_mfma_f32_16x16x32_bf16 v[50:53], v[184:187], v[200:203], v[50:53]
	v_mfma_f32_16x16x32_bf16 v[42:45], v[192:195], v[200:203], v[42:45]
	v_mfma_f32_16x16x32_bf16 v[34:37], v[184:187], v[208:211], v[34:37]
	v_mfma_f32_16x16x32_bf16 v[26:29], v[192:195], v[208:211], v[26:29]
	v_mfma_f32_16x16x32_bf16 v[18:21], v[184:187], v[216:219], v[18:21]
	v_mfma_f32_16x16x32_bf16 v[10:13], v[192:195], v[216:219], v[10:13]
	v_mfma_f32_16x16x32_bf16 v[6:9], v[184:187], v[224:227], v[6:9]
	v_mfma_f32_16x16x32_bf16 v[2:5], v[192:195], v[224:227], v[2:5]
	s_barrier
	s_setprio 0
	s_add_i32 s41, 0, 0x18000
	v_add_u32_e32 v144, s41, v139
	s_add_i32 s42, 0, 0x1c000
	ds_read_b128 v[160:163], v144
	ds_read_b128 v[166:169], v144 offset:1024
	ds_read_b128 v[170:173], v144 offset:2048
	ds_read_b128 v[174:177], v144 offset:3072
	v_add_u32_e32 v144, s42, v139
	ds_read_b128 v[178:181], v144
	ds_read_b128 v[184:187], v144 offset:1024
	ds_read_b128 v[188:191], v144 offset:2048
	ds_read_b128 v[192:195], v144 offset:3072
	s_add_u32 s14, s20, 0xb0000
	s_addc_u32 s15, s21, 0
	s_mov_b32 m0, s27
	v_lshl_add_u64 v[236:237], s[14:15], 0, v[130:131]
	ds_read_b128 v[196:199], v165 offset:32768
	ds_read_b128 v[200:203], v165 offset:33792
	ds_read_b128 v[204:207], v165 offset:34816
	ds_read_b128 v[208:211], v165 offset:35840
	ds_read_b128 v[212:215], v165 offset:36864
	ds_read_b128 v[216:219], v165 offset:37888
	ds_read_b128 v[220:223], v165 offset:38912
	ds_read_b128 v[224:227], v165 offset:39936
	global_load_lds_dwordx4 v[236:237], off
	s_mov_b32 m0, s28
	v_lshl_add_u64 v[236:237], s[14:15], 0, v[134:135]
	global_load_lds_dwordx4 v[236:237], off
	s_setprio 1
	s_waitcnt vmcnt(8) lgkmcnt(0)
	s_barrier
	v_mfma_f32_16x16x32_bf16 v[126:129], v[160:163], v[196:199], v[126:129]
	v_mfma_f32_16x16x32_bf16 v[122:125], v[170:173], v[196:199], v[122:125]
	v_mfma_f32_16x16x32_bf16 v[118:121], v[160:163], v[204:207], v[118:121]
	v_mfma_f32_16x16x32_bf16 v[110:113], v[170:173], v[204:207], v[110:113]
	v_mfma_f32_16x16x32_bf16 v[102:105], v[160:163], v[212:215], v[102:105]
	v_mfma_f32_16x16x32_bf16 v[94:97], v[170:173], v[212:215], v[94:97]
	v_mfma_f32_16x16x32_bf16 v[86:89], v[160:163], v[220:223], v[86:89]
	v_mfma_f32_16x16x32_bf16 v[78:81], v[170:173], v[220:223], v[78:81]
	v_mfma_f32_16x16x32_bf16 v[126:129], v[166:169], v[200:203], v[126:129]
	v_mfma_f32_16x16x32_bf16 v[122:125], v[174:177], v[200:203], v[122:125]
	v_mfma_f32_16x16x32_bf16 v[118:121], v[166:169], v[208:211], v[118:121]
	v_mfma_f32_16x16x32_bf16 v[110:113], v[174:177], v[208:211], v[110:113]
	v_mfma_f32_16x16x32_bf16 v[102:105], v[166:169], v[216:219], v[102:105]
	v_mfma_f32_16x16x32_bf16 v[94:97], v[174:177], v[216:219], v[94:97]
	v_mfma_f32_16x16x32_bf16 v[86:89], v[166:169], v[224:227], v[86:89]
	v_mfma_f32_16x16x32_bf16 v[78:81], v[174:177], v[224:227], v[78:81]
	v_mfma_f32_16x16x32_bf16 v[114:117], v[178:181], v[196:199], v[114:117]
	v_mfma_f32_16x16x32_bf16 v[106:109], v[188:191], v[196:199], v[106:109]
	v_mfma_f32_16x16x32_bf16 v[98:101], v[178:181], v[204:207], v[98:101]
	v_mfma_f32_16x16x32_bf16 v[90:93], v[188:191], v[204:207], v[90:93]
	v_mfma_f32_16x16x32_bf16 v[82:85], v[178:181], v[212:215], v[82:85]
	v_mfma_f32_16x16x32_bf16 v[74:77], v[188:191], v[212:215], v[74:77]
	v_mfma_f32_16x16x32_bf16 v[70:73], v[178:181], v[220:223], v[70:73]
	v_mfma_f32_16x16x32_bf16 v[66:69], v[188:191], v[220:223], v[66:69]
	v_mfma_f32_16x16x32_bf16 v[114:117], v[184:187], v[200:203], v[114:117]
	v_mfma_f32_16x16x32_bf16 v[106:109], v[192:195], v[200:203], v[106:109]
	v_mfma_f32_16x16x32_bf16 v[98:101], v[184:187], v[208:211], v[98:101]
	v_mfma_f32_16x16x32_bf16 v[90:93], v[192:195], v[208:211], v[90:93]
	v_mfma_f32_16x16x32_bf16 v[82:85], v[184:187], v[216:219], v[82:85]
	v_mfma_f32_16x16x32_bf16 v[74:77], v[192:195], v[216:219], v[74:77]
	v_mfma_f32_16x16x32_bf16 v[70:73], v[184:187], v[224:227], v[70:73]
	v_mfma_f32_16x16x32_bf16 v[66:69], v[192:195], v[224:227], v[66:69]
	s_barrier
; #define PG8_STAGE(bufoff, gbase, voff) do { _Pragma("unroll") for (int _i = 0; _i < 2; ++_i) \
;         __builtin_amdgcn_global_load_lds((const unsigned*)((const char*)(gbase) + (voff)[_i]), (LAS unsigned*)(lds + (bufoff) + ldsw + _i * 8192), 16, 0, 0); } while (0)
; #define PG8_LDA(dst, b, h) do { _Pragma("unroll") for (int m = 0; m < 4; ++m) _Pragma("unroll") for (int k = 0; k < 2; ++k) dst[m][k] = *(const LAS bf16x8*)(lds + PG8_SA(b, h) + aoff + m * 2048 + k * 1024); } while (0)
; #define PG8_LDB(dst, b, h) do { _Pragma("unroll") for (int n = 0; n < 2; ++n) _Pragma("unroll") for (int k = 0; k < 2; ++k) dst[n][k] = *(const LAS bf16x8*)(lds + PG8_SB(b, h) + boff + n * 2048 + k * 1024); } while (0)
; #define PG8_BAR __builtin_amdgcn_s_barrier()
; template <class Epi, bool ALIGN_EPI = PG8_ALIGN, bool SP2 = PG8_SP2>
; __device__ __forceinline__ void gemm_phase(LAS uchar* lds, const Gemm g, const StaticOrder& S, const Epi& E) {
;     ...
;         for (int t = tb; t < tb + tblk; t += 2) {
;             const bool last = (t == nt - 2);
;             const char* a1 = cA + (size_t)(t + 1) * kstep;
;             const char* a2 = last ? nA : cA + (size_t)(t + 2) * kstep; const char* b2 = last ? nB : cB + (size_t)(t + 2) * kstep;
;             const char* a3 = a2 + kstep; const char* b3 = b2 + kstep;
;             if constexpr (SP2) {
;             PG8_LDB(B0, 0, 0); PG8_LDB(B1, 0, 1); PG8_SCHED; PG8_LDA(At, 0, 0); PG8_STAGE(PG8_SA(1, 1), a1 + hstepA, voffA);
;             PG8_WAIT_V(8); PG8_WAIT_L(0); PG8_BAR; PG8_MMA(0, 0, At, B0); PG8_MMA(0, 1, At, B1); PG8_BAR; PG8_SCHED;
;             PG8_LDA(At, 0, 1); PG8_STAGE(PG8_SB(0, 0), b2, voffB); PG8_STAGE(PG8_SB(0, 1), b2 + hstepB, voffB); PG8_STAGE(PG8_SA(0, 0), a2, voffA);
;             PG8_WAIT_V(8); PG8_WAIT_L(0); PG8_BAR; PG8_MMA(1, 0, At, B0); PG8_MMA(1, 1, At, B1); PG8_BAR; PG8_SCHED;
;             PG8_LDB(B0, 1, 0); PG8_LDB(B1, 1, 1); PG8_SCHED; PG8_LDA(At, 1, 0); PG8_STAGE(PG8_SA(0, 1), a2 + hstepA, voffA);
;             PG8_WAIT_V(8); PG8_WAIT_L(0); PG8_BAR; PG8_MMA(0, 0, At, B0); PG8_MMA(0, 1, At, B1); PG8_BAR; PG8_SCHED;
;             PG8_LDA(At, 1, 1); PG8_STAGE(PG8_SB(1, 0), b3, voffB); PG8_STAGE(PG8_SB(1, 1), b3 + hstepB, voffB); PG8_STAGE(PG8_SA(1, 0), a3, voffA);
;             PG8_WAIT_V(8); PG8_WAIT_L(0); PG8_BAR; PG8_MMA(1, 0, At, B0); PG8_MMA(1, 1, At, B1); PG8_BAR; PG8_SCHED;
	s_setprio 0
	s_add_i32 s14, s41, s24
	v_lshl_add_u64 v[228:229], v[228:229], 0, s[84:85]
	s_mov_b32 m0, s14
	ds_read_b128 v[196:199], v165 offset:49152
	ds_read_b128 v[200:203], v165 offset:50176
	ds_read_b128 v[204:207], v165 offset:51200
	ds_read_b128 v[208:211], v165 offset:52224
	ds_read_b128 v[212:215], v165 offset:53248
	ds_read_b128 v[216:219], v165 offset:54272
	ds_read_b128 v[220:223], v165 offset:55296
	ds_read_b128 v[224:227], v165 offset:56320
	global_load_lds_dwordx4 v[228:229], off
	s_add_i32 m0, s14, 0x2000
	s_add_u32 s14, s18, 0xb0080
	v_lshl_add_u64 v[228:229], v[230:231], 0, s[84:85]
	s_addc_u32 s15, s19, 0
	s_add_i32 s18, s42, s24
	global_load_lds_dwordx4 v[228:229], off
	s_mov_b32 m0, s18
	v_lshl_add_u64 v[228:229], s[14:15], 0, v[132:133]
	global_load_lds_dwordx4 v[228:229], off
	s_add_i32 m0, s18, 0x2000
	v_lshl_add_u64 v[228:229], s[14:15], 0, v[154:155]
	global_load_lds_dwordx4 v[228:229], off
	s_mov_b32 m0, s29
	v_lshl_add_u64 v[228:229], v[232:233], 0, s[84:85]
	global_load_lds_dwordx4 v[228:229], off
	s_mov_b32 m0, s30
	v_lshl_add_u64 v[228:229], v[234:235], 0, s[84:85]
	global_load_lds_dwordx4 v[228:229], off
	s_setprio 1
	s_waitcnt vmcnt(8) lgkmcnt(0)
	s_barrier
	v_mfma_f32_16x16x32_bf16 v[62:65], v[160:163], v[196:199], v[62:65]
	v_mfma_f32_16x16x32_bf16 v[58:61], v[170:173], v[196:199], v[58:61]
	v_mfma_f32_16x16x32_bf16 v[54:57], v[160:163], v[204:207], v[54:57]
	v_mfma_f32_16x16x32_bf16 v[46:49], v[170:173], v[204:207], v[46:49]
	v_mfma_f32_16x16x32_bf16 v[38:41], v[160:163], v[212:215], v[38:41]
	v_mfma_f32_16x16x32_bf16 v[30:33], v[170:173], v[212:215], v[30:33]
	v_mfma_f32_16x16x32_bf16 v[22:25], v[160:163], v[220:223], v[22:25]
	v_mfma_f32_16x16x32_bf16 v[14:17], v[170:173], v[220:223], v[14:17]
	v_mfma_f32_16x16x32_bf16 v[62:65], v[166:169], v[200:203], v[62:65]
	v_mfma_f32_16x16x32_bf16 v[58:61], v[174:177], v[200:203], v[58:61]
	v_mfma_f32_16x16x32_bf16 v[54:57], v[166:169], v[208:211], v[54:57]
	v_mfma_f32_16x16x32_bf16 v[46:49], v[174:177], v[208:211], v[46:49]
	v_mfma_f32_16x16x32_bf16 v[38:41], v[166:169], v[216:219], v[38:41]
	v_mfma_f32_16x16x32_bf16 v[30:33], v[174:177], v[216:219], v[30:33]
	v_mfma_f32_16x16x32_bf16 v[22:25], v[166:169], v[224:227], v[22:25]
	v_mfma_f32_16x16x32_bf16 v[14:17], v[174:177], v[224:227], v[14:17]
	v_mfma_f32_16x16x32_bf16 v[50:53], v[178:181], v[196:199], v[50:53]
	v_mfma_f32_16x16x32_bf16 v[42:45], v[188:191], v[196:199], v[42:45]
	v_mfma_f32_16x16x32_bf16 v[34:37], v[178:181], v[204:207], v[34:37]
	v_mfma_f32_16x16x32_bf16 v[26:29], v[188:191], v[204:207], v[26:29]
	v_mfma_f32_16x16x32_bf16 v[18:21], v[178:181], v[212:215], v[18:21]
	v_mfma_f32_16x16x32_bf16 v[10:13], v[188:191], v[212:215], v[10:13]
	v_mfma_f32_16x16x32_bf16 v[6:9], v[178:181], v[220:223], v[6:9]
	v_mfma_f32_16x16x32_bf16 v[2:5], v[188:191], v[220:223], v[2:5]
	v_mfma_f32_16x16x32_bf16 v[50:53], v[184:187], v[200:203], v[50:53]
	v_mfma_f32_16x16x32_bf16 v[42:45], v[192:195], v[200:203], v[42:45]
	v_mfma_f32_16x16x32_bf16 v[34:37], v[184:187], v[208:211], v[34:37]
	v_mfma_f32_16x16x32_bf16 v[26:29], v[192:195], v[208:211], v[26:29]
	v_mfma_f32_16x16x32_bf16 v[18:21], v[184:187], v[216:219], v[18:21]
	v_mfma_f32_16x16x32_bf16 v[10:13], v[192:195], v[216:219], v[10:13]
	v_mfma_f32_16x16x32_bf16 v[6:9], v[184:187], v[224:227], v[6:9]
	v_mfma_f32_16x16x32_bf16 v[2:5], v[192:195], v[224:227], v[2:5]
	s_barrier
	s_setprio 0
	s_add_i32 s40, s40, 2
	s_add_u32 s38, s38, 0x100
	s_addc_u32 s39, s39, 0
	s_cmp_gt_u32 s40, 41
	s_mov_b64 s[14:15], s[16:17]
.LBB0_1143:
	s_add_u32 s16, s14, 0x100
	s_addc_u32 s17, s15, 0
	s_add_i32 s41, 0, 0x10000
	s_cmp_eq_u32 s40, 40
	s_cselect_b32 s21, s5, s17
	s_cselect_b32 s20, s4, s16
	v_add_u32_e32 v144, s41, v139
	s_cselect_b32 s19, s13, s39
	s_cselect_b32 s18, s12, s38
	s_add_i32 s42, 0, 0x14000
	ds_read_b128 v[160:163], v144
	ds_read_b128 v[166:169], v144 offset:1024
	ds_read_b128 v[170:173], v144 offset:2048
	ds_read_b128 v[174:177], v144 offset:3072
	v_add_u32_e32 v144, s42, v139
	ds_read_b128 v[178:181], v144
	ds_read_b128 v[184:187], v144 offset:1024
	ds_read_b128 v[188:191], v144 offset:2048
	ds_read_b128 v[192:195], v144 offset:3072
	v_lshl_add_u64 v[228:229], s[14:15], 0, v[156:157]
	s_add_i32 m0, s25, 0xc000
	ds_read_b128 v[196:199], v165
	ds_read_b128 v[200:203], v165 offset:1024
	ds_read_b128 v[204:207], v165 offset:2048
	ds_read_b128 v[208:211], v165 offset:3072
	ds_read_b128 v[212:215], v165 offset:4096
	ds_read_b128 v[216:219], v165 offset:5120
	ds_read_b128 v[220:223], v165 offset:6144
	ds_read_b128 v[224:227], v165 offset:7168
	global_load_lds_dwordx4 v[228:229], off
	s_add_i32 m0, s25, 0xe000
	v_lshl_add_u64 v[228:229], s[14:15], 0, v[158:159]
	global_load_lds_dwordx4 v[228:229], off
	s_setprio 1
	s_waitcnt vmcnt(8) lgkmcnt(0)
	s_barrier
; #define PG8_STAGE(bufoff, gbase, voff) do { _Pragma("unroll") for (int _i = 0; _i < 2; ++_i) \
;         __builtin_amdgcn_global_load_lds((const unsigned*)((const char*)(gbase) + (voff)[_i]), (LAS unsigned*)(lds + (bufoff) + ldsw + _i * 8192), 16, 0, 0); } while (0)
; #define PG8_LDA(dst, b, h) do { _Pragma("unroll") for (int m = 0; m < 4; ++m) _Pragma("unroll") for (int k = 0; k < 2; ++k) dst[m][k] = *(const LAS bf16x8*)(lds + PG8_SA(b, h) + aoff + m * 2048 + k * 1024); } while (0)
; #define PG8_MMA(ai, bj, At, Bt) do { __builtin_amdgcn_s_setprio(1); _Pragma("unroll") for (int m = 0; m < 4; ++m) _Pragma("unroll") for (int n = 0; n < 2; ++n) _Pragma("unroll") for (int k = 0; k < 2; ++k) \
;         acc[ai][bj][m][n] = __builtin_amdgcn_mfma_f32_16x16x32_bf16(Bt[n][k], At[m][k], acc[ai][bj][m][n], 0, 0, 0); __builtin_amdgcn_s_setprio(0); } while (0)
; #define PG8_WAIT_V(n) asm volatile("s_waitcnt vmcnt(" #n ")" ::: "memory")
; #define PG8_WAIT_L(n) asm volatile("s_waitcnt lgkmcnt(" #n ")" ::: "memory")
; #define PG8_BAR __builtin_amdgcn_s_barrier()
; #define PG8_SCHED __builtin_amdgcn_sched_barrier(0)
; template <class Epi, bool ALIGN_EPI = PG8_ALIGN, bool SP2 = PG8_SP2>
; __device__ __forceinline__ void gemm_phase(LAS uchar* lds, const Gemm g, const StaticOrder& S, const Epi& E) {
;     ...
;             PG8_WAIT_V(8); PG8_WAIT_L(0); PG8_BAR; PG8_MMA(0, 0, At, B0); PG8_MMA(0, 1, At, B1); PG8_BAR; PG8_SCHED;
;             PG8_LDA(At, 0, 1); PG8_STAGE(PG8_SB(0, 0), b2, voffB); PG8_STAGE(PG8_SB(0, 1), b2 + hstepB, voffB); PG8_STAGE(PG8_SA(0, 0), a2, voffA);
;             PG8_WAIT_V(8); PG8_WAIT_L(0); PG8_BAR; PG8_MMA(1, 0, At, B0); PG8_MMA(1, 1, At, B1); PG8_BAR; PG8_SCHED;
	v_mfma_f32_16x16x32_bf16 v[126:129], v[160:163], v[196:199], v[126:129]
	v_mfma_f32_16x16x32_bf16 v[122:125], v[170:173], v[196:199], v[122:125]
	v_mfma_f32_16x16x32_bf16 v[118:121], v[160:163], v[204:207], v[118:121]
	v_mfma_f32_16x16x32_bf16 v[110:113], v[170:173], v[204:207], v[110:113]
	v_mfma_f32_16x16x32_bf16 v[102:105], v[160:163], v[212:215], v[102:105]
	v_mfma_f32_16x16x32_bf16 v[94:97], v[170:173], v[212:215], v[94:97]
	v_mfma_f32_16x16x32_bf16 v[86:89], v[160:163], v[220:223], v[86:89]
	v_mfma_f32_16x16x32_bf16 v[78:81], v[170:173], v[220:223], v[78:81]
	v_mfma_f32_16x16x32_bf16 v[126:129], v[166:169], v[200:203], v[126:129]
	v_mfma_f32_16x16x32_bf16 v[122:125], v[174:177], v[200:203], v[122:125]
	v_mfma_f32_16x16x32_bf16 v[118:121], v[166:169], v[208:211], v[118:121]
	v_mfma_f32_16x16x32_bf16 v[110:113], v[174:177], v[208:211], v[110:113]
	v_mfma_f32_16x16x32_bf16 v[102:105], v[166:169], v[216:219], v[102:105]
	v_mfma_f32_16x16x32_bf16 v[94:97], v[174:177], v[216:219], v[94:97]
	v_mfma_f32_16x16x32_bf16 v[86:89], v[166:169], v[224:227], v[86:89]
	v_mfma_f32_16x16x32_bf16 v[78:81], v[174:177], v[224:227], v[78:81]
	v_mfma_f32_16x16x32_bf16 v[114:117], v[178:181], v[196:199], v[114:117]
	v_mfma_f32_16x16x32_bf16 v[106:109], v[188:191], v[196:199], v[106:109]
	v_mfma_f32_16x16x32_bf16 v[98:101], v[178:181], v[204:207], v[98:101]
	v_mfma_f32_16x16x32_bf16 v[90:93], v[188:191], v[204:207], v[90:93]
	v_mfma_f32_16x16x32_bf16 v[82:85], v[178:181], v[212:215], v[82:85]
	v_mfma_f32_16x16x32_bf16 v[74:77], v[188:191], v[212:215], v[74:77]
	v_mfma_f32_16x16x32_bf16 v[70:73], v[178:181], v[220:223], v[70:73]
	v_mfma_f32_16x16x32_bf16 v[66:69], v[188:191], v[220:223], v[66:69]
	v_mfma_f32_16x16x32_bf16 v[114:117], v[184:187], v[200:203], v[114:117]
	v_mfma_f32_16x16x32_bf16 v[106:109], v[192:195], v[200:203], v[106:109]
	v_mfma_f32_16x16x32_bf16 v[98:101], v[184:187], v[208:211], v[98:101]
	v_mfma_f32_16x16x32_bf16 v[90:93], v[192:195], v[208:211], v[90:93]
	v_mfma_f32_16x16x32_bf16 v[82:85], v[184:187], v[216:219], v[82:85]
	v_mfma_f32_16x16x32_bf16 v[74:77], v[192:195], v[216:219], v[74:77]
	v_mfma_f32_16x16x32_bf16 v[70:73], v[184:187], v[224:227], v[70:73]
	v_mfma_f32_16x16x32_bf16 v[66:69], v[192:195], v[224:227], v[66:69]
	s_barrier
	s_setprio 0
	s_add_i32 s14, s41, s24
	v_lshl_add_u64 v[228:229], s[18:19], 0, v[132:133]
	s_mov_b32 m0, s14
	ds_read_b128 v[196:199], v165 offset:16384
	ds_read_b128 v[200:203], v165 offset:17408
	ds_read_b128 v[204:207], v165 offset:18432
	ds_read_b128 v[208:211], v165 offset:19456
	ds_read_b128 v[212:215], v165 offset:20480
	ds_read_b128 v[216:219], v165 offset:21504
	ds_read_b128 v[220:223], v165 offset:22528
	ds_read_b128 v[224:227], v165 offset:23552
	global_load_lds_dwordx4 v[228:229], off
	s_add_i32 m0, s14, 0x2000
	s_add_u32 s14, s18, 0xb0000
	v_lshl_add_u64 v[230:231], s[18:19], 0, v[154:155]
	s_addc_u32 s15, s19, 0
	s_add_i32 s41, s42, s24
	global_load_lds_dwordx4 v[230:231], off
	v_lshl_add_u64 v[232:233], s[14:15], 0, v[132:133]
	s_mov_b32 m0, s41
	global_load_lds_dwordx4 v[232:233], off
	s_add_i32 m0, s41, 0x2000
	v_lshl_add_u64 v[232:233], s[14:15], 0, v[154:155]
	global_load_lds_dwordx4 v[232:233], off
	s_mov_b32 m0, s25
	v_lshl_add_u64 v[232:233], s[20:21], 0, v[130:131]
	global_load_lds_dwordx4 v[232:233], off
	s_mov_b32 m0, s26
	v_lshl_add_u64 v[234:235], s[20:21], 0, v[134:135]
	global_load_lds_dwordx4 v[234:235], off
	s_setprio 1
	s_waitcnt vmcnt(8) lgkmcnt(0)
	s_barrier
	v_mfma_f32_16x16x32_bf16 v[62:65], v[160:163], v[196:199], v[62:65]
	v_mfma_f32_16x16x32_bf16 v[58:61], v[170:173], v[196:199], v[58:61]
	v_mfma_f32_16x16x32_bf16 v[54:57], v[160:163], v[204:207], v[54:57]
	v_mfma_f32_16x16x32_bf16 v[46:49], v[170:173], v[204:207], v[46:49]
	v_mfma_f32_16x16x32_bf16 v[38:41], v[160:163], v[212:215], v[38:41]
	v_mfma_f32_16x16x32_bf16 v[30:33], v[170:173], v[212:215], v[30:33]
	v_mfma_f32_16x16x32_bf16 v[22:25], v[160:163], v[220:223], v[22:25]
	v_mfma_f32_16x16x32_bf16 v[14:17], v[170:173], v[220:223], v[14:17]
	v_mfma_f32_16x16x32_bf16 v[62:65], v[166:169], v[200:203], v[62:65]
	v_mfma_f32_16x16x32_bf16 v[58:61], v[174:177], v[200:203], v[58:61]
	v_mfma_f32_16x16x32_bf16 v[54:57], v[166:169], v[208:211], v[54:57]
	v_mfma_f32_16x16x32_bf16 v[46:49], v[174:177], v[208:211], v[46:49]
	v_mfma_f32_16x16x32_bf16 v[38:41], v[166:169], v[216:219], v[38:41]
	v_mfma_f32_16x16x32_bf16 v[30:33], v[174:177], v[216:219], v[30:33]
	v_mfma_f32_16x16x32_bf16 v[22:25], v[166:169], v[224:227], v[22:25]
	v_mfma_f32_16x16x32_bf16 v[14:17], v[174:177], v[224:227], v[14:17]
	v_mfma_f32_16x16x32_bf16 v[50:53], v[178:181], v[196:199], v[50:53]
	v_mfma_f32_16x16x32_bf16 v[42:45], v[188:191], v[196:199], v[42:45]
	v_mfma_f32_16x16x32_bf16 v[34:37], v[178:181], v[204:207], v[34:37]
	v_mfma_f32_16x16x32_bf16 v[26:29], v[188:191], v[204:207], v[26:29]
	v_mfma_f32_16x16x32_bf16 v[18:21], v[178:181], v[212:215], v[18:21]
	v_mfma_f32_16x16x32_bf16 v[10:13], v[188:191], v[212:215], v[10:13]
	v_mfma_f32_16x16x32_bf16 v[6:9], v[178:181], v[220:223], v[6:9]
	v_mfma_f32_16x16x32_bf16 v[2:5], v[188:191], v[220:223], v[2:5]
	v_mfma_f32_16x16x32_bf16 v[50:53], v[184:187], v[200:203], v[50:53]
	v_mfma_f32_16x16x32_bf16 v[42:45], v[192:195], v[200:203], v[42:45]
	v_mfma_f32_16x16x32_bf16 v[34:37], v[184:187], v[208:211], v[34:37]
	v_mfma_f32_16x16x32_bf16 v[26:29], v[192:195], v[208:211], v[26:29]
	v_mfma_f32_16x16x32_bf16 v[18:21], v[184:187], v[216:219], v[18:21]
	v_mfma_f32_16x16x32_bf16 v[10:13], v[192:195], v[216:219], v[10:13]
	v_mfma_f32_16x16x32_bf16 v[6:9], v[184:187], v[224:227], v[6:9]
	v_mfma_f32_16x16x32_bf16 v[2:5], v[192:195], v[224:227], v[2:5]
	s_barrier
; #define PG8_STAGE(bufoff, gbase, voff) do { _Pragma("unroll") for (int _i = 0; _i < 2; ++_i) \
;         __builtin_amdgcn_global_load_lds((const unsigned*)((const char*)(gbase) + (voff)[_i]), (LAS unsigned*)(lds + (bufoff) + ldsw + _i * 8192), 16, 0, 0); } while (0)
; #define PG8_LDA(dst, b, h) do { _Pragma("unroll") for (int m = 0; m < 4; ++m) _Pragma("unroll") for (int k = 0; k < 2; ++k) dst[m][k] = *(const LAS bf16x8*)(lds + PG8_SA(b, h) + aoff + m * 2048 + k * 1024); } while (0)
; #define PG8_LDB(dst, b, h) do { _Pragma("unroll") for (int n = 0; n < 2; ++n) _Pragma("unroll") for (int k = 0; k < 2; ++k) dst[n][k] = *(const LAS bf16x8*)(lds + PG8_SB(b, h) + boff + n * 2048 + k * 1024); } while (0)
; #define PG8_MMA(ai, bj, At, Bt) do { __builtin_amdgcn_s_setprio(1); _Pragma("unroll") for (int m = 0; m < 4; ++m) _Pragma("unroll") for (int n = 0; n < 2; ++n) _Pragma("unroll") for (int k = 0; k < 2; ++k) \
;         acc[ai][bj][m][n] = __builtin_amdgcn_mfma_f32_16x16x32_bf16(Bt[n][k], At[m][k], acc[ai][bj][m][n], 0, 0, 0); __builtin_amdgcn_s_setprio(0); } while (0)
; #define PG8_WAIT_V(n) asm volatile("s_waitcnt vmcnt(" #n ")" ::: "memory")
; #define PG8_WAIT_L(n) asm volatile("s_waitcnt lgkmcnt(" #n ")" ::: "memory")
; #define PG8_BAR __builtin_amdgcn_s_barrier()
; #define PG8_SCHED __builtin_amdgcn_sched_barrier(0)
; template <class Epi, bool ALIGN_EPI = PG8_ALIGN, bool SP2 = PG8_SP2>
; __device__ __forceinline__ void gemm_phase(LAS uchar* lds, const Gemm g, const StaticOrder& S, const Epi& E) {
;     ...
;             PG8_WAIT_V(8); PG8_WAIT_L(0); PG8_BAR; PG8_MMA(1, 0, At, B0); PG8_MMA(1, 1, At, B1); PG8_BAR; PG8_SCHED;
;             PG8_LDB(B0, 1, 0); PG8_LDB(B1, 1, 1); PG8_SCHED; PG8_LDA(At, 1, 0); PG8_STAGE(PG8_SA(0, 1), a2 + hstepA, voffA);
;             PG8_WAIT_V(8); PG8_WAIT_L(0); PG8_BAR; PG8_MMA(0, 0, At, B0); PG8_MMA(0, 1, At, B1); PG8_BAR; PG8_SCHED;
	s_setprio 0
	s_add_i32 s41, 0, 0x18000
	v_add_u32_e32 v144, s41, v139
	s_add_i32 s42, 0, 0x1c000
	ds_read_b128 v[160:163], v144
	ds_read_b128 v[166:169], v144 offset:1024
	ds_read_b128 v[170:173], v144 offset:2048
	ds_read_b128 v[174:177], v144 offset:3072
	v_add_u32_e32 v144, s42, v139
	ds_read_b128 v[178:181], v144
	ds_read_b128 v[184:187], v144 offset:1024
	ds_read_b128 v[188:191], v144 offset:2048
	ds_read_b128 v[192:195], v144 offset:3072
	s_add_u32 s14, s20, 0xb0000
	s_addc_u32 s15, s21, 0
	s_mov_b32 m0, s27
	v_lshl_add_u64 v[236:237], s[14:15], 0, v[130:131]
	ds_read_b128 v[196:199], v165 offset:32768
	ds_read_b128 v[200:203], v165 offset:33792
	ds_read_b128 v[204:207], v165 offset:34816
	ds_read_b128 v[208:211], v165 offset:35840
	ds_read_b128 v[212:215], v165 offset:36864
	ds_read_b128 v[216:219], v165 offset:37888
	ds_read_b128 v[220:223], v165 offset:38912
	ds_read_b128 v[224:227], v165 offset:39936
	global_load_lds_dwordx4 v[236:237], off
	s_mov_b32 m0, s28
	v_lshl_add_u64 v[236:237], s[14:15], 0, v[134:135]
	global_load_lds_dwordx4 v[236:237], off
	s_setprio 1
	s_waitcnt vmcnt(8) lgkmcnt(0)
	s_barrier
	v_mfma_f32_16x16x32_bf16 v[126:129], v[160:163], v[196:199], v[126:129]
	v_mfma_f32_16x16x32_bf16 v[122:125], v[170:173], v[196:199], v[122:125]
	v_mfma_f32_16x16x32_bf16 v[118:121], v[160:163], v[204:207], v[118:121]
	v_mfma_f32_16x16x32_bf16 v[110:113], v[170:173], v[204:207], v[110:113]
	v_mfma_f32_16x16x32_bf16 v[102:105], v[160:163], v[212:215], v[102:105]
	v_mfma_f32_16x16x32_bf16 v[94:97], v[170:173], v[212:215], v[94:97]
	v_mfma_f32_16x16x32_bf16 v[86:89], v[160:163], v[220:223], v[86:89]
	v_mfma_f32_16x16x32_bf16 v[78:81], v[170:173], v[220:223], v[78:81]
	v_mfma_f32_16x16x32_bf16 v[126:129], v[166:169], v[200:203], v[126:129]
	v_mfma_f32_16x16x32_bf16 v[122:125], v[174:177], v[200:203], v[122:125]
	v_mfma_f32_16x16x32_bf16 v[118:121], v[166:169], v[208:211], v[118:121]
	v_mfma_f32_16x16x32_bf16 v[110:113], v[174:177], v[208:211], v[110:113]
	v_mfma_f32_16x16x32_bf16 v[102:105], v[166:169], v[216:219], v[102:105]
	v_mfma_f32_16x16x32_bf16 v[94:97], v[174:177], v[216:219], v[94:97]
	v_mfma_f32_16x16x32_bf16 v[86:89], v[166:169], v[224:227], v[86:89]
	v_mfma_f32_16x16x32_bf16 v[78:81], v[174:177], v[224:227], v[78:81]
	v_mfma_f32_16x16x32_bf16 v[114:117], v[178:181], v[196:199], v[114:117]
	v_mfma_f32_16x16x32_bf16 v[106:109], v[188:191], v[196:199], v[106:109]
	v_mfma_f32_16x16x32_bf16 v[98:101], v[178:181], v[204:207], v[98:101]
	v_mfma_f32_16x16x32_bf16 v[90:93], v[188:191], v[204:207], v[90:93]
	v_mfma_f32_16x16x32_bf16 v[82:85], v[178:181], v[212:215], v[82:85]
	v_mfma_f32_16x16x32_bf16 v[74:77], v[188:191], v[212:215], v[74:77]
	v_mfma_f32_16x16x32_bf16 v[70:73], v[178:181], v[220:223], v[70:73]
	v_mfma_f32_16x16x32_bf16 v[66:69], v[188:191], v[220:223], v[66:69]
	v_mfma_f32_16x16x32_bf16 v[114:117], v[184:187], v[200:203], v[114:117]
	v_mfma_f32_16x16x32_bf16 v[106:109], v[192:195], v[200:203], v[106:109]
	v_mfma_f32_16x16x32_bf16 v[98:101], v[184:187], v[208:211], v[98:101]
	v_mfma_f32_16x16x32_bf16 v[90:93], v[192:195], v[208:211], v[90:93]
	v_mfma_f32_16x16x32_bf16 v[82:85], v[184:187], v[216:219], v[82:85]
	v_mfma_f32_16x16x32_bf16 v[74:77], v[192:195], v[216:219], v[74:77]
	v_mfma_f32_16x16x32_bf16 v[70:73], v[184:187], v[224:227], v[70:73]
	v_mfma_f32_16x16x32_bf16 v[66:69], v[192:195], v[224:227], v[66:69]
	s_barrier
; #define PG8_STAGE(bufoff, gbase, voff) do { _Pragma("unroll") for (int _i = 0; _i < 2; ++_i) \
;         __builtin_amdgcn_global_load_lds((const unsigned*)((const char*)(gbase) + (voff)[_i]), (LAS unsigned*)(lds + (bufoff) + ldsw + _i * 8192), 16, 0, 0); } while (0)
; #define PG8_LDA(dst, b, h) do { _Pragma("unroll") for (int m = 0; m < 4; ++m) _Pragma("unroll") for (int k = 0; k < 2; ++k) dst[m][k] = *(const LAS bf16x8*)(lds + PG8_SA(b, h) + aoff + m * 2048 + k * 1024); } while (0)
; #define PG8_MMA(ai, bj, At, Bt) do { __builtin_amdgcn_s_setprio(1); _Pragma("unroll") for (int m = 0; m < 4; ++m) _Pragma("unroll") for (int n = 0; n < 2; ++n) _Pragma("unroll") for (int k = 0; k < 2; ++k) \
;         acc[ai][bj][m][n] = __builtin_amdgcn_mfma_f32_16x16x32_bf16(Bt[n][k], At[m][k], acc[ai][bj][m][n], 0, 0, 0); __builtin_amdgcn_s_setprio(0); } while (0)
; #define PG8_WAIT_V(n) asm volatile("s_waitcnt vmcnt(" #n ")" ::: "memory")
; #define PG8_WAIT_L(n) asm volatile("s_waitcnt lgkmcnt(" #n ")" ::: "memory")
; #define PG8_BAR __builtin_amdgcn_s_barrier()
; #define PG8_SCHED __builtin_amdgcn_sched_barrier(0)
; template <class Epi, bool ALIGN_EPI = PG8_ALIGN, bool SP2 = PG8_SP2>
; __device__ __forceinline__ void gemm_phase(LAS uchar* lds, const Gemm g, const StaticOrder& S, const Epi& E) {
;     ...
;             PG8_WAIT_V(8); PG8_WAIT_L(0); PG8_BAR; PG8_MMA(0, 0, At, B0); PG8_MMA(0, 1, At, B1); PG8_BAR; PG8_SCHED;
;             PG8_LDA(At, 1, 1); PG8_STAGE(PG8_SB(1, 0), b3, voffB); PG8_STAGE(PG8_SB(1, 1), b3 + hstepB, voffB); PG8_STAGE(PG8_SA(1, 0), a3, voffA);
;             PG8_WAIT_V(8); PG8_WAIT_L(0); PG8_BAR; PG8_MMA(1, 0, At, B0); PG8_MMA(1, 1, At, B1); PG8_BAR; PG8_SCHED;
;     ...
;         if constexpr (ALIGN_EPI) { if (wr == 0) PG8_BAR; }
	s_setprio 0
	s_add_i32 s14, s41, s24
	v_lshl_add_u64 v[228:229], v[228:229], 0, s[84:85]
	s_mov_b32 m0, s14
	ds_read_b128 v[196:199], v165 offset:49152
	ds_read_b128 v[200:203], v165 offset:50176
	ds_read_b128 v[204:207], v165 offset:51200
	ds_read_b128 v[208:211], v165 offset:52224
	ds_read_b128 v[212:215], v165 offset:53248
	ds_read_b128 v[216:219], v165 offset:54272
	ds_read_b128 v[220:223], v165 offset:55296
	ds_read_b128 v[224:227], v165 offset:56320
	global_load_lds_dwordx4 v[228:229], off
	s_add_i32 m0, s14, 0x2000
	s_add_u32 s14, s18, 0xb0080
	v_lshl_add_u64 v[228:229], v[230:231], 0, s[84:85]
	s_addc_u32 s15, s19, 0
	s_add_i32 s18, s42, s24
	global_load_lds_dwordx4 v[228:229], off
	s_mov_b32 m0, s18
	v_lshl_add_u64 v[228:229], s[14:15], 0, v[132:133]
	global_load_lds_dwordx4 v[228:229], off
	s_add_i32 m0, s18, 0x2000
	v_lshl_add_u64 v[228:229], s[14:15], 0, v[154:155]
	global_load_lds_dwordx4 v[228:229], off
	s_mov_b32 m0, s29
	v_lshl_add_u64 v[228:229], v[232:233], 0, s[84:85]
	global_load_lds_dwordx4 v[228:229], off
	s_mov_b32 m0, s30
	v_lshl_add_u64 v[228:229], v[234:235], 0, s[84:85]
	global_load_lds_dwordx4 v[228:229], off
	s_setprio 1
	s_waitcnt vmcnt(8) lgkmcnt(0)
	s_barrier
	v_mfma_f32_16x16x32_bf16 v[62:65], v[160:163], v[196:199], v[62:65]
	v_mfma_f32_16x16x32_bf16 v[58:61], v[170:173], v[196:199], v[58:61]
	v_mfma_f32_16x16x32_bf16 v[54:57], v[160:163], v[204:207], v[54:57]
	v_mfma_f32_16x16x32_bf16 v[46:49], v[170:173], v[204:207], v[46:49]
	v_mfma_f32_16x16x32_bf16 v[38:41], v[160:163], v[212:215], v[38:41]
	v_mfma_f32_16x16x32_bf16 v[30:33], v[170:173], v[212:215], v[30:33]
	v_mfma_f32_16x16x32_bf16 v[22:25], v[160:163], v[220:223], v[22:25]
	v_mfma_f32_16x16x32_bf16 v[14:17], v[170:173], v[220:223], v[14:17]
	v_mfma_f32_16x16x32_bf16 v[62:65], v[166:169], v[200:203], v[62:65]
	v_mfma_f32_16x16x32_bf16 v[58:61], v[174:177], v[200:203], v[58:61]
	v_mfma_f32_16x16x32_bf16 v[54:57], v[166:169], v[208:211], v[54:57]
	v_mfma_f32_16x16x32_bf16 v[46:49], v[174:177], v[208:211], v[46:49]
	v_mfma_f32_16x16x32_bf16 v[38:41], v[166:169], v[216:219], v[38:41]
	v_mfma_f32_16x16x32_bf16 v[30:33], v[174:177], v[216:219], v[30:33]
	v_mfma_f32_16x16x32_bf16 v[22:25], v[166:169], v[224:227], v[22:25]
	v_mfma_f32_16x16x32_bf16 v[14:17], v[174:177], v[224:227], v[14:17]
	v_mfma_f32_16x16x32_bf16 v[50:53], v[178:181], v[196:199], v[50:53]
	v_mfma_f32_16x16x32_bf16 v[42:45], v[188:191], v[196:199], v[42:45]
	v_mfma_f32_16x16x32_bf16 v[34:37], v[178:181], v[204:207], v[34:37]
	v_mfma_f32_16x16x32_bf16 v[26:29], v[188:191], v[204:207], v[26:29]
	v_mfma_f32_16x16x32_bf16 v[18:21], v[178:181], v[212:215], v[18:21]
	v_mfma_f32_16x16x32_bf16 v[10:13], v[188:191], v[212:215], v[10:13]
	v_mfma_f32_16x16x32_bf16 v[6:9], v[178:181], v[220:223], v[6:9]
	v_mfma_f32_16x16x32_bf16 v[2:5], v[188:191], v[220:223], v[2:5]
	v_mfma_f32_16x16x32_bf16 v[50:53], v[184:187], v[200:203], v[50:53]
	v_mfma_f32_16x16x32_bf16 v[42:45], v[192:195], v[200:203], v[42:45]
	v_mfma_f32_16x16x32_bf16 v[34:37], v[184:187], v[208:211], v[34:37]
	v_mfma_f32_16x16x32_bf16 v[26:29], v[192:195], v[208:211], v[26:29]
	v_mfma_f32_16x16x32_bf16 v[18:21], v[184:187], v[216:219], v[18:21]
	v_mfma_f32_16x16x32_bf16 v[10:13], v[192:195], v[216:219], v[10:13]
	v_mfma_f32_16x16x32_bf16 v[6:9], v[184:187], v[224:227], v[6:9]
	v_mfma_f32_16x16x32_bf16 v[2:5], v[192:195], v[224:227], v[2:5]
	s_barrier
	s_setprio 0
	s_add_i32 s40, s40, 2
	s_add_u32 s38, s38, 0x100
	s_addc_u32 s39, s39, 0
	s_cmp_gt_u32 s40, 41
	s_mov_b64 s[14:15], s[16:17]
	s_cbranch_scc0 .LBB0_1143
	s_and_b64 vcc, exec, s[10:11]
	s_cbranch_vccz .LBB0_1146
	s_barrier
